# static priority (lever 4): removed hipcc's per-MMA-cluster s_setprio toggles in all GEMM loops, waves 4-7 raised to priority 1 once at kernel entry; attention MFMA sections at priority 2
# speedup vs baseline: 1.0081x; 1.0081x over previous
_Z4mega6Params:
	s_load_dword s55, s[0:1], 0xe0
	s_mov_b64 s[14:15], s[0:1]
	s_add_u32 s0, s14, 0xe0
	s_addc_u32 s1, s15, 0
	s_mov_b32 s57, s2
	v_writelane_b32 v251, s0, 0
	v_and_b32_e32 v1, 0x3ff, v0
	v_readfirstlane_b32 s3, v1
	s_cmpk_ge_u32 s3, 0x100
	s_cbranch_scc0 .Lprio_skip
	s_setprio 1
.Lprio_skip:
	s_nop 0
	v_writelane_b32 v251, s1, 1
	s_waitcnt lgkmcnt(0)
	s_and_b32 s0, s55, 7
	s_cmp_eq_u32 s0, 0
	v_readfirstlane_b32 s6, v1
	s_cselect_b64 s[2:3], -1, 0
	s_cmp_lg_u32 s0, 0
	v_writelane_b32 v251, s57, 2
	s_cbranch_scc0 .LBB0_2
	s_load_dwordx2 s[88:89], s[14:15], 0xd0
	v_cmp_eq_u32_e32 vcc, 0, v1
	s_and_saveexec_b64 s[0:1], vcc
	s_cbranch_execnz .LBB0_3
	s_branch .LBB0_5

.LBB0_44:
	s_add_u32 s6, s4, 0xfffc0080
	s_addc_u32 s7, s5, -1
	s_add_i32 s30, 0, 0x10000
	v_add_u32_e32 v146, s30, v132
	ds_read_b128 v[134:137], v146
	ds_read_b128 v[138:141], v146 offset:1024
	ds_read_b128 v[142:145], v146 offset:2048
	ds_read_b128 v[146:149], v146 offset:3072
	s_cmp_eq_u32 s29, 12
	s_cselect_b32 s15, s9, s7
	s_cselect_b32 s14, s8, s6
	s_cselect_b32 s7, s11, s17
	s_cselect_b32 s6, s10, s16
	v_lshl_add_u64 v[182:183], s[4:5], 0, v[0:1]
	s_add_i32 m0, s63, 0xc000
	ds_read_b128 v[150:153], v133
	ds_read_b128 v[154:157], v133 offset:1024
	ds_read_b128 v[158:161], v133 offset:2048
	ds_read_b128 v[162:165], v133 offset:3072
	ds_read_b128 v[166:169], v133 offset:4096
	ds_read_b128 v[170:173], v133 offset:5120
	ds_read_b128 v[174:177], v133 offset:6144
	ds_read_b128 v[178:181], v133 offset:7168
	global_load_lds_dwordx4 v[182:183], off
	v_lshl_add_u64 v[182:183], s[4:5], 0, v[130:131]
	s_add_i32 m0, s63, 0xe000
	s_nop 0
	global_load_lds_dwordx4 v[182:183], off
	s_waitcnt lgkmcnt(8)
	s_barrier
	s_waitcnt lgkmcnt(0)
	s_waitcnt lgkmcnt(0)
	v_mfma_f32_16x16x32_bf16 v[126:129], v[134:137], v[150:153], v[126:129]
	v_mfma_f32_16x16x32_bf16 v[122:125], v[142:145], v[150:153], v[122:125]
	v_mfma_f32_16x16x32_bf16 v[110:113], v[134:137], v[158:161], v[110:113]
	v_mfma_f32_16x16x32_bf16 v[106:109], v[142:145], v[158:161], v[106:109]
	v_mfma_f32_16x16x32_bf16 v[94:97], v[134:137], v[166:169], v[94:97]
	v_mfma_f32_16x16x32_bf16 v[90:93], v[142:145], v[166:169], v[90:93]
	v_mfma_f32_16x16x32_bf16 v[78:81], v[134:137], v[174:177], v[78:81]
	v_mfma_f32_16x16x32_bf16 v[74:77], v[142:145], v[174:177], v[74:77]
	v_mfma_f32_16x16x32_bf16 v[126:129], v[138:141], v[154:157], v[126:129]
	v_mfma_f32_16x16x32_bf16 v[122:125], v[146:149], v[154:157], v[122:125]
	v_mfma_f32_16x16x32_bf16 v[110:113], v[138:141], v[162:165], v[110:113]
	v_mfma_f32_16x16x32_bf16 v[106:109], v[146:149], v[162:165], v[106:109]
	v_mfma_f32_16x16x32_bf16 v[94:97], v[138:141], v[170:173], v[94:97]
	v_mfma_f32_16x16x32_bf16 v[90:93], v[146:149], v[170:173], v[90:93]
	v_mfma_f32_16x16x32_bf16 v[78:81], v[138:141], v[178:181], v[78:81]
	v_mfma_f32_16x16x32_bf16 v[74:77], v[146:149], v[178:181], v[74:77]
	s_barrier
	s_add_i32 s36, 0, 0x14000
	v_add_u32_e32 v190, s36, v132
	s_add_i32 s30, s30, s53
	ds_read_b128 v[182:185], v190
	ds_read_b128 v[186:189], v190 offset:1024
	ds_read_b128 v[192:195], v190 offset:2048
	ds_read_b128 v[196:199], v190 offset:3072
	v_lshl_add_u64 v[190:191], s[6:7], 0, v[0:1]
	s_mov_b32 m0, s30
	v_lshl_add_u64 v[200:201], s[6:7], 0, v[130:131]
	global_load_lds_dwordx4 v[190:191], off
	s_add_i32 m0, s30, 0x2000
	s_nop 0
	global_load_lds_dwordx4 v[200:201], off
	s_barrier
	s_waitcnt lgkmcnt(0)
	s_waitcnt lgkmcnt(0)
	v_mfma_f32_16x16x32_bf16 v[118:121], v[182:185], v[150:153], v[118:121]
	v_mfma_f32_16x16x32_bf16 v[114:117], v[192:195], v[150:153], v[114:117]
	v_mfma_f32_16x16x32_bf16 v[102:105], v[182:185], v[158:161], v[102:105]
	v_mfma_f32_16x16x32_bf16 v[98:101], v[192:195], v[158:161], v[98:101]
	v_mfma_f32_16x16x32_bf16 v[86:89], v[182:185], v[166:169], v[86:89]
	v_mfma_f32_16x16x32_bf16 v[82:85], v[192:195], v[166:169], v[82:85]
	v_mfma_f32_16x16x32_bf16 v[70:73], v[182:185], v[174:177], v[70:73]
	v_mfma_f32_16x16x32_bf16 v[66:69], v[192:195], v[174:177], v[66:69]
	v_mfma_f32_16x16x32_bf16 v[118:121], v[186:189], v[154:157], v[118:121]
	v_mfma_f32_16x16x32_bf16 v[114:117], v[196:199], v[154:157], v[114:117]
	v_mfma_f32_16x16x32_bf16 v[102:105], v[186:189], v[162:165], v[102:105]
	v_mfma_f32_16x16x32_bf16 v[98:101], v[196:199], v[162:165], v[98:101]
	v_mfma_f32_16x16x32_bf16 v[86:89], v[186:189], v[170:173], v[86:89]
	v_mfma_f32_16x16x32_bf16 v[82:85], v[196:199], v[170:173], v[82:85]
	v_mfma_f32_16x16x32_bf16 v[70:73], v[186:189], v[178:181], v[70:73]
	v_mfma_f32_16x16x32_bf16 v[66:69], v[196:199], v[178:181], v[66:69]
	s_mov_b32 m0, s63
	v_lshl_add_u64 v[202:203], s[14:15], 0, v[0:1]
	s_barrier
	ds_read_b128 v[150:153], v133 offset:16384
	ds_read_b128 v[154:157], v133 offset:17408
	ds_read_b128 v[158:161], v133 offset:18432
	ds_read_b128 v[162:165], v133 offset:19456
	ds_read_b128 v[166:169], v133 offset:20480
	ds_read_b128 v[170:173], v133 offset:21504
	ds_read_b128 v[174:177], v133 offset:22528
	ds_read_b128 v[178:181], v133 offset:23552
	global_load_lds_dwordx4 v[202:203], off
	v_lshl_add_u64 v[204:205], s[14:15], 0, v[130:131]
	s_mov_b32 m0, s18
	s_nop 0
	global_load_lds_dwordx4 v[204:205], off
	s_barrier
	s_waitcnt lgkmcnt(0)
	s_waitcnt lgkmcnt(0)
	v_mfma_f32_16x16x32_bf16 v[62:65], v[134:137], v[150:153], v[62:65]
	v_mfma_f32_16x16x32_bf16 v[58:61], v[142:145], v[150:153], v[58:61]
	v_mfma_f32_16x16x32_bf16 v[46:49], v[134:137], v[158:161], v[46:49]
	v_mfma_f32_16x16x32_bf16 v[42:45], v[142:145], v[158:161], v[42:45]
	v_mfma_f32_16x16x32_bf16 v[30:33], v[134:137], v[166:169], v[30:33]
	v_mfma_f32_16x16x32_bf16 v[26:29], v[142:145], v[166:169], v[26:29]
	v_mfma_f32_16x16x32_bf16 v[14:17], v[134:137], v[174:177], v[14:17]
	v_mfma_f32_16x16x32_bf16 v[10:13], v[142:145], v[174:177], v[10:13]
	v_mfma_f32_16x16x32_bf16 v[62:65], v[138:141], v[154:157], v[62:65]
	v_mfma_f32_16x16x32_bf16 v[58:61], v[146:149], v[154:157], v[58:61]
	v_mfma_f32_16x16x32_bf16 v[46:49], v[138:141], v[162:165], v[46:49]
	v_mfma_f32_16x16x32_bf16 v[42:45], v[146:149], v[162:165], v[42:45]
	v_mfma_f32_16x16x32_bf16 v[30:33], v[138:141], v[170:173], v[30:33]
	v_mfma_f32_16x16x32_bf16 v[26:29], v[146:149], v[170:173], v[26:29]
	v_mfma_f32_16x16x32_bf16 v[14:17], v[138:141], v[178:181], v[14:17]
	v_mfma_f32_16x16x32_bf16 v[10:13], v[146:149], v[178:181], v[10:13]
	s_barrier
	s_add_u32 s30, s6, 0x40000
	s_addc_u32 s31, s7, 0
	s_add_i32 s36, s36, s53
	v_lshl_add_u64 v[134:135], s[30:31], 0, v[0:1]
	s_mov_b32 m0, s36
	s_nop 0
	global_load_lds_dwordx4 v[134:135], off
	v_lshl_add_u64 v[134:135], s[30:31], 0, v[130:131]
	s_add_i32 m0, s36, 0x2000
	s_nop 0
	global_load_lds_dwordx4 v[134:135], off
	s_waitcnt vmcnt(6)
	s_barrier
	v_mfma_f32_16x16x32_bf16 v[54:57], v[182:185], v[150:153], v[54:57]
	v_mfma_f32_16x16x32_bf16 v[50:53], v[192:195], v[150:153], v[50:53]
	v_mfma_f32_16x16x32_bf16 v[38:41], v[182:185], v[158:161], v[38:41]
	v_mfma_f32_16x16x32_bf16 v[34:37], v[192:195], v[158:161], v[34:37]
	v_mfma_f32_16x16x32_bf16 v[22:25], v[182:185], v[166:169], v[22:25]
	v_mfma_f32_16x16x32_bf16 v[18:21], v[192:195], v[166:169], v[18:21]
	v_mfma_f32_16x16x32_bf16 v[6:9], v[182:185], v[174:177], v[6:9]
	v_mfma_f32_16x16x32_bf16 v[2:5], v[192:195], v[174:177], v[2:5]
	v_mfma_f32_16x16x32_bf16 v[54:57], v[186:189], v[154:157], v[54:57]
	v_mfma_f32_16x16x32_bf16 v[50:53], v[196:199], v[154:157], v[50:53]
	v_mfma_f32_16x16x32_bf16 v[38:41], v[186:189], v[162:165], v[38:41]
	v_mfma_f32_16x16x32_bf16 v[34:37], v[196:199], v[162:165], v[34:37]
	v_mfma_f32_16x16x32_bf16 v[22:25], v[186:189], v[170:173], v[22:25]
	v_mfma_f32_16x16x32_bf16 v[18:21], v[196:199], v[170:173], v[18:21]
	v_mfma_f32_16x16x32_bf16 v[6:9], v[186:189], v[178:181], v[6:9]
	v_mfma_f32_16x16x32_bf16 v[2:5], v[196:199], v[178:181], v[2:5]
	s_add_i32 s30, 0, 0x18000
	v_add_u32_e32 v146, s30, v132
	s_barrier
	ds_read_b128 v[134:137], v146
	ds_read_b128 v[138:141], v146 offset:1024
	ds_read_b128 v[142:145], v146 offset:2048
	ds_read_b128 v[146:149], v146 offset:3072
	s_add_u32 s14, s14, 0x40000
	s_addc_u32 s15, s15, 0
	s_mov_b32 m0, s19
	v_lshl_add_u64 v[182:183], s[14:15], 0, v[0:1]
	ds_read_b128 v[150:153], v133 offset:32768
	ds_read_b128 v[154:157], v133 offset:33792
	ds_read_b128 v[158:161], v133 offset:34816
	ds_read_b128 v[162:165], v133 offset:35840
	ds_read_b128 v[166:169], v133 offset:36864
	ds_read_b128 v[170:173], v133 offset:37888
	ds_read_b128 v[174:177], v133 offset:38912
	ds_read_b128 v[178:181], v133 offset:39936
	global_load_lds_dwordx4 v[182:183], off
	v_lshl_add_u64 v[182:183], s[14:15], 0, v[130:131]
	s_mov_b32 m0, s20
	s_nop 0
	global_load_lds_dwordx4 v[182:183], off
	s_waitcnt lgkmcnt(8)
	s_barrier
	s_waitcnt lgkmcnt(0)
	s_waitcnt lgkmcnt(0)
	v_mfma_f32_16x16x32_bf16 v[126:129], v[134:137], v[150:153], v[126:129]
	v_mfma_f32_16x16x32_bf16 v[122:125], v[142:145], v[150:153], v[122:125]
	v_mfma_f32_16x16x32_bf16 v[110:113], v[134:137], v[158:161], v[110:113]
	v_mfma_f32_16x16x32_bf16 v[106:109], v[142:145], v[158:161], v[106:109]
	v_mfma_f32_16x16x32_bf16 v[94:97], v[134:137], v[166:169], v[94:97]
	v_mfma_f32_16x16x32_bf16 v[90:93], v[142:145], v[166:169], v[90:93]
	v_mfma_f32_16x16x32_bf16 v[78:81], v[134:137], v[174:177], v[78:81]
	v_mfma_f32_16x16x32_bf16 v[74:77], v[142:145], v[174:177], v[74:77]
	v_mfma_f32_16x16x32_bf16 v[126:129], v[138:141], v[154:157], v[126:129]
	v_mfma_f32_16x16x32_bf16 v[122:125], v[146:149], v[154:157], v[122:125]
	v_mfma_f32_16x16x32_bf16 v[110:113], v[138:141], v[162:165], v[110:113]
	v_mfma_f32_16x16x32_bf16 v[106:109], v[146:149], v[162:165], v[106:109]
	v_mfma_f32_16x16x32_bf16 v[94:97], v[138:141], v[170:173], v[94:97]
	v_mfma_f32_16x16x32_bf16 v[90:93], v[146:149], v[170:173], v[90:93]
	v_mfma_f32_16x16x32_bf16 v[78:81], v[138:141], v[178:181], v[78:81]
	v_mfma_f32_16x16x32_bf16 v[74:77], v[146:149], v[178:181], v[74:77]
	s_barrier
	s_add_i32 s14, 0, 0x1c000
	s_add_i32 s15, s30, s53
	v_add_u32_e32 v196, s14, v132
	v_lshl_add_u64 v[190:191], v[190:191], 0, s[70:71]
	s_mov_b32 m0, s15
	ds_read_b128 v[182:185], v196
	ds_read_b128 v[186:189], v196 offset:1024
	ds_read_b128 v[192:195], v196 offset:2048
	ds_read_b128 v[196:199], v196 offset:3072
	global_load_lds_dwordx4 v[190:191], off
	v_lshl_add_u64 v[190:191], v[200:201], 0, s[70:71]
	s_add_i32 m0, s15, 0x2000
	s_nop 0
	global_load_lds_dwordx4 v[190:191], off
	s_barrier
	s_waitcnt lgkmcnt(0)
	s_waitcnt lgkmcnt(0)
	v_mfma_f32_16x16x32_bf16 v[118:121], v[182:185], v[150:153], v[118:121]
	v_mfma_f32_16x16x32_bf16 v[114:117], v[192:195], v[150:153], v[114:117]
	v_mfma_f32_16x16x32_bf16 v[102:105], v[182:185], v[158:161], v[102:105]
	v_mfma_f32_16x16x32_bf16 v[98:101], v[192:195], v[158:161], v[98:101]
	v_mfma_f32_16x16x32_bf16 v[86:89], v[182:185], v[166:169], v[86:89]
	v_mfma_f32_16x16x32_bf16 v[82:85], v[192:195], v[166:169], v[82:85]
	v_mfma_f32_16x16x32_bf16 v[70:73], v[182:185], v[174:177], v[70:73]
	v_mfma_f32_16x16x32_bf16 v[66:69], v[192:195], v[174:177], v[66:69]
	v_mfma_f32_16x16x32_bf16 v[118:121], v[186:189], v[154:157], v[118:121]
	v_mfma_f32_16x16x32_bf16 v[114:117], v[196:199], v[154:157], v[114:117]
	v_mfma_f32_16x16x32_bf16 v[102:105], v[186:189], v[162:165], v[102:105]
	v_mfma_f32_16x16x32_bf16 v[98:101], v[196:199], v[162:165], v[98:101]
	v_mfma_f32_16x16x32_bf16 v[86:89], v[186:189], v[170:173], v[86:89]
	v_mfma_f32_16x16x32_bf16 v[82:85], v[196:199], v[170:173], v[82:85]
	v_mfma_f32_16x16x32_bf16 v[70:73], v[186:189], v[178:181], v[70:73]
	v_mfma_f32_16x16x32_bf16 v[66:69], v[196:199], v[178:181], v[66:69]
	s_mov_b32 m0, s23
	v_lshl_add_u64 v[190:191], v[202:203], 0, s[70:71]
	s_barrier
	ds_read_b128 v[150:153], v133 offset:49152
	ds_read_b128 v[154:157], v133 offset:50176
	ds_read_b128 v[158:161], v133 offset:51200
	ds_read_b128 v[162:165], v133 offset:52224
	ds_read_b128 v[166:169], v133 offset:53248
	ds_read_b128 v[170:173], v133 offset:54272
	ds_read_b128 v[174:177], v133 offset:55296
	ds_read_b128 v[178:181], v133 offset:56320
	global_load_lds_dwordx4 v[190:191], off
	v_lshl_add_u64 v[190:191], v[204:205], 0, s[70:71]
	s_mov_b32 m0, s24
	s_nop 0
	global_load_lds_dwordx4 v[190:191], off
	s_barrier
	s_waitcnt lgkmcnt(0)
	s_waitcnt lgkmcnt(0)
	v_mfma_f32_16x16x32_bf16 v[62:65], v[134:137], v[150:153], v[62:65]
	v_mfma_f32_16x16x32_bf16 v[58:61], v[142:145], v[150:153], v[58:61]
	v_mfma_f32_16x16x32_bf16 v[46:49], v[134:137], v[158:161], v[46:49]
	v_mfma_f32_16x16x32_bf16 v[42:45], v[142:145], v[158:161], v[42:45]
	v_mfma_f32_16x16x32_bf16 v[30:33], v[134:137], v[166:169], v[30:33]
	v_mfma_f32_16x16x32_bf16 v[26:29], v[142:145], v[166:169], v[26:29]
	v_mfma_f32_16x16x32_bf16 v[14:17], v[134:137], v[174:177], v[14:17]
	v_mfma_f32_16x16x32_bf16 v[10:13], v[142:145], v[174:177], v[10:13]
	v_mfma_f32_16x16x32_bf16 v[62:65], v[138:141], v[154:157], v[62:65]
	v_mfma_f32_16x16x32_bf16 v[58:61], v[146:149], v[154:157], v[58:61]
	v_mfma_f32_16x16x32_bf16 v[46:49], v[138:141], v[162:165], v[46:49]
	v_mfma_f32_16x16x32_bf16 v[42:45], v[146:149], v[162:165], v[42:45]
	v_mfma_f32_16x16x32_bf16 v[30:33], v[138:141], v[170:173], v[30:33]
	v_mfma_f32_16x16x32_bf16 v[26:29], v[146:149], v[170:173], v[26:29]
	v_mfma_f32_16x16x32_bf16 v[14:17], v[138:141], v[178:181], v[14:17]
	v_mfma_f32_16x16x32_bf16 v[10:13], v[146:149], v[178:181], v[10:13]
	s_barrier
	s_add_u32 s6, s6, 0x40080
	s_addc_u32 s7, s7, 0
	s_add_i32 s14, s14, s53
	v_lshl_add_u64 v[134:135], s[6:7], 0, v[0:1]
	s_mov_b32 m0, s14
	s_nop 0
	global_load_lds_dwordx4 v[134:135], off
	v_lshl_add_u64 v[134:135], s[6:7], 0, v[130:131]
	s_add_i32 m0, s14, 0x2000
	s_nop 0
	global_load_lds_dwordx4 v[134:135], off
	s_waitcnt vmcnt(6)
	s_barrier
	v_mfma_f32_16x16x32_bf16 v[54:57], v[182:185], v[150:153], v[54:57]
	v_mfma_f32_16x16x32_bf16 v[50:53], v[192:195], v[150:153], v[50:53]
	v_mfma_f32_16x16x32_bf16 v[38:41], v[182:185], v[158:161], v[38:41]
	v_mfma_f32_16x16x32_bf16 v[34:37], v[192:195], v[158:161], v[34:37]
	v_mfma_f32_16x16x32_bf16 v[22:25], v[182:185], v[166:169], v[22:25]
	v_mfma_f32_16x16x32_bf16 v[18:21], v[192:195], v[166:169], v[18:21]
	v_mfma_f32_16x16x32_bf16 v[6:9], v[182:185], v[174:177], v[6:9]
	v_mfma_f32_16x16x32_bf16 v[2:5], v[192:195], v[174:177], v[2:5]
	v_mfma_f32_16x16x32_bf16 v[54:57], v[186:189], v[154:157], v[54:57]
	v_mfma_f32_16x16x32_bf16 v[50:53], v[196:199], v[154:157], v[50:53]
	v_mfma_f32_16x16x32_bf16 v[38:41], v[186:189], v[162:165], v[38:41]
	v_mfma_f32_16x16x32_bf16 v[34:37], v[196:199], v[162:165], v[34:37]
	v_mfma_f32_16x16x32_bf16 v[22:25], v[186:189], v[170:173], v[22:25]
	v_mfma_f32_16x16x32_bf16 v[18:21], v[196:199], v[170:173], v[18:21]
	v_mfma_f32_16x16x32_bf16 v[6:9], v[186:189], v[178:181], v[6:9]
	v_mfma_f32_16x16x32_bf16 v[2:5], v[196:199], v[178:181], v[2:5]
	s_add_i32 s29, s29, 2
	s_add_u32 s16, s16, 0x100
	s_addc_u32 s17, s17, 0
	s_add_u32 s4, s4, 0x100
	s_addc_u32 s5, s5, 0
	s_cmp_gt_u32 s29, 13
	s_barrier
	s_cbranch_scc0 .LBB0_44
	v_readlane_b32 s4, v253, 15
	v_mbcnt_lo_u32_b32 v0, -1, 0
	v_mbcnt_hi_u32_b32 v0, -1, v0
	s_ashr_i32 s29, s34, 1
	s_mov_b32 s30, s49
	v_add_u32_e32 v130, s4, v0
	s_mov_b32 s31, s48
	v_readlane_b32 s4, v252, 13
	v_readlane_b32 s5, v252, 14
	s_add_u32 s4, s31, s4
	s_addc_u32 s5, s30, s5
	v_ashrrev_i32_e32 v131, 31, v130
	v_lshl_add_u64 v[132:133], v[130:131], 4, s[4:5]
	s_mov_b64 s[4:5], 0x10480000
	v_lshl_add_u64 v[162:163], v[132:133], 0, s[4:5]
	s_lshl_b32 s4, s35, 8
	s_add_i32 s4, s4, s42
	s_bitcmp1_b32 s34, 0
	s_cselect_b64 s[14:15], -1, 0
	v_bfe_u32 v178, v0, 4, 2
	s_mov_b32 s6, s51
	s_mov_b32 s7, s50
	v_and_or_b32 v164, v0, 15, s4
	s_mov_b64 s[4:5], -1
	s_and_b64 vcc, exec, s[14:15]
	s_cbranch_vccz .LBB0_175
	global_load_dwordx4 v[158:161], v[162:163], off
	v_readlane_b32 s4, v252, 13
	v_readlane_b32 s5, v252, 14
	s_add_u32 s4, s7, s4
	s_addc_u32 s5, s6, s5
	s_cmp_gt_i32 s29, 0
	v_lshl_add_u64 v[166:167], v[130:131], 4, s[4:5]
	s_cselect_b64 s[6:7], -1, 0
	s_cmp_lt_i32 s29, 1
	s_cbranch_scc1 .LBB0_48
	global_load_dwordx4 v[142:145], v[166:167], off

.LBB0_312:
	v_readlane_b32 s29, v254, 9
	s_add_i32 s38, 0, 0x10000
	s_add_i32 s36, 0, 0x14000
	v_or_b32_e32 v5, s29, v3
	v_add_u32_e32 v200, s38, v5
	ds_read_b128 v[10:13], v200
	ds_read_b128 v[14:17], v200 offset:1024
	ds_read_b128 v[18:21], v200 offset:2048
	ds_read_b128 v[22:25], v200 offset:3072
	s_add_i32 s29, s62, 0
	v_add_u32_e32 v4, s29, v3
	s_add_i32 s39, 0, 0x18000
	s_add_i32 s29, 0, 0x1c000
	v_add_u32_e32 v201, s36, v5
	v_add_u32_e32 v236, s39, v5
	v_add_u32_e32 v5, s29, v5
	s_add_u32 s34, s14, 0x40080
	s_addc_u32 s35, s15, 0
	s_add_i32 s30, s63, 0xc000
	s_mov_b32 m0, s30
	s_add_i32 s31, s63, 0xe000
	ds_read_b128 v[26:29], v4
	ds_read_b128 v[30:33], v4 offset:1024
	ds_read_b128 v[34:37], v4 offset:2048
	ds_read_b128 v[38:41], v4 offset:3072
	ds_read_b128 v[42:45], v4 offset:4096
	ds_read_b128 v[46:49], v4 offset:5120
	ds_read_b128 v[50:53], v4 offset:6144
	ds_read_b128 v[54:57], v4 offset:7168
	global_load_lds_dwordx4 v0, s[34:35]
	s_mov_b32 m0, s31
	v_mov_b32_e32 v3, v1
	global_load_lds_dwordx4 v2, s[34:35]
	s_waitcnt lgkmcnt(8)
	s_barrier
	s_waitcnt lgkmcnt(0)
	s_waitcnt lgkmcnt(0)
	v_mfma_f32_16x16x32_bf16 v[58:61], v[10:13], v[26:29], 0
	v_mfma_f32_16x16x32_bf16 v[62:65], v[18:21], v[26:29], 0
	v_mfma_f32_16x16x32_bf16 v[66:69], v[10:13], v[34:37], 0
	v_mfma_f32_16x16x32_bf16 v[70:73], v[18:21], v[34:37], 0
	v_mfma_f32_16x16x32_bf16 v[74:77], v[10:13], v[42:45], 0
	v_mfma_f32_16x16x32_bf16 v[78:81], v[18:21], v[42:45], 0
	v_mfma_f32_16x16x32_bf16 v[82:85], v[10:13], v[50:53], 0
	v_mfma_f32_16x16x32_bf16 v[86:89], v[18:21], v[50:53], 0
	v_mfma_f32_16x16x32_bf16 v[58:61], v[14:17], v[30:33], v[58:61]
	v_mfma_f32_16x16x32_bf16 v[62:65], v[22:25], v[30:33], v[62:65]
	v_mfma_f32_16x16x32_bf16 v[66:69], v[14:17], v[38:41], v[66:69]
	v_mfma_f32_16x16x32_bf16 v[70:73], v[22:25], v[38:41], v[70:73]
	v_mfma_f32_16x16x32_bf16 v[74:77], v[14:17], v[46:49], v[74:77]
	v_mfma_f32_16x16x32_bf16 v[78:81], v[22:25], v[46:49], v[78:81]
	v_mfma_f32_16x16x32_bf16 v[82:85], v[14:17], v[54:57], v[82:85]
	v_mfma_f32_16x16x32_bf16 v[86:89], v[22:25], v[54:57], v[86:89]
	s_barrier
	v_mov_b32_e32 v7, v1
	v_lshl_add_u64 v[190:191], s[16:17], 0, v[6:7]
	s_add_i32 s38, s38, s53
	v_mov_b32_e32 v9, v1
	v_lshl_add_u64 v[106:107], v[190:191], 0, s[76:77]
	s_mov_b32 m0, s38
	v_lshl_add_u64 v[196:197], s[16:17], 0, v[8:9]
	s_add_i32 s35, s38, 0x2000
	ds_read_b128 v[90:93], v201
	ds_read_b128 v[94:97], v201 offset:1024
	ds_read_b128 v[98:101], v201 offset:2048
	ds_read_b128 v[102:105], v201 offset:3072
	global_load_lds_dwordx4 v[106:107], off
	v_lshl_add_u64 v[106:107], v[196:197], 0, s[76:77]
	s_mov_b32 m0, s35
	s_nop 0
	global_load_lds_dwordx4 v[106:107], off
	s_barrier
	s_waitcnt lgkmcnt(0)
	s_waitcnt lgkmcnt(0)
	v_mfma_f32_16x16x32_bf16 v[106:109], v[90:93], v[26:29], 0
	v_mfma_f32_16x16x32_bf16 v[26:29], v[98:101], v[26:29], 0
	v_mfma_f32_16x16x32_bf16 v[106:109], v[94:97], v[30:33], v[106:109]
	v_mfma_f32_16x16x32_bf16 v[26:29], v[102:105], v[30:33], v[26:29]
	v_mfma_f32_16x16x32_bf16 v[30:33], v[90:93], v[34:37], 0
	v_mfma_f32_16x16x32_bf16 v[34:37], v[98:101], v[34:37], 0
	v_mfma_f32_16x16x32_bf16 v[30:33], v[94:97], v[38:41], v[30:33]
	v_mfma_f32_16x16x32_bf16 v[34:37], v[102:105], v[38:41], v[34:37]
	v_mfma_f32_16x16x32_bf16 v[38:41], v[90:93], v[42:45], 0
	v_mfma_f32_16x16x32_bf16 v[42:45], v[98:101], v[42:45], 0
	v_mfma_f32_16x16x32_bf16 v[38:41], v[94:97], v[46:49], v[38:41]
	v_mfma_f32_16x16x32_bf16 v[42:45], v[102:105], v[46:49], v[42:45]
	v_mfma_f32_16x16x32_bf16 v[46:49], v[90:93], v[50:53], 0
	v_mfma_f32_16x16x32_bf16 v[50:53], v[98:101], v[50:53], 0
	v_mfma_f32_16x16x32_bf16 v[46:49], v[94:97], v[54:57], v[46:49]
	v_mfma_f32_16x16x32_bf16 v[50:53], v[102:105], v[54:57], v[50:53]
	v_lshl_add_u64 v[198:199], s[14:15], 0, v[0:1]
	s_mov_b32 m0, s63
	v_lshl_add_u64 v[138:139], v[198:199], 0, s[76:77]
	v_lshl_add_u64 v[212:213], s[14:15], 0, v[2:3]
	s_barrier
	ds_read_b128 v[54:57], v4 offset:16384
	ds_read_b128 v[110:113], v4 offset:17408
	ds_read_b128 v[114:117], v4 offset:18432
	ds_read_b128 v[118:121], v4 offset:19456
	ds_read_b128 v[122:125], v4 offset:20480
	ds_read_b128 v[126:129], v4 offset:21504
	ds_read_b128 v[130:133], v4 offset:22528
	ds_read_b128 v[134:137], v4 offset:23552
	global_load_lds_dwordx4 v[138:139], off
	v_lshl_add_u64 v[138:139], v[212:213], 0, s[76:77]
	s_mov_b32 m0, s18
	s_nop 0
	global_load_lds_dwordx4 v[138:139], off
	s_barrier
	s_waitcnt lgkmcnt(0)
	s_waitcnt lgkmcnt(0)
	v_mfma_f32_16x16x32_bf16 v[138:141], v[10:13], v[54:57], 0
	s_waitcnt vmcnt(0)
	v_mfma_f32_16x16x32_bf16 v[146:149], v[10:13], v[114:117], 0
	v_mfma_f32_16x16x32_bf16 v[154:157], v[10:13], v[122:125], 0
	v_mfma_f32_16x16x32_bf16 v[10:13], v[10:13], v[130:133], 0
	v_mfma_f32_16x16x32_bf16 v[138:141], v[14:17], v[110:113], v[138:141]
	v_mfma_f32_16x16x32_bf16 v[142:145], v[18:21], v[54:57], 0
	v_mfma_f32_16x16x32_bf16 v[146:149], v[14:17], v[118:121], v[146:149]
	v_mfma_f32_16x16x32_bf16 v[150:153], v[18:21], v[114:117], 0
	v_mfma_f32_16x16x32_bf16 v[154:157], v[14:17], v[126:129], v[154:157]
	v_mfma_f32_16x16x32_bf16 v[158:161], v[18:21], v[122:125], 0
	v_mfma_f32_16x16x32_bf16 v[10:13], v[14:17], v[134:137], v[10:13]
	v_mfma_f32_16x16x32_bf16 v[14:17], v[18:21], v[130:133], 0
	v_mfma_f32_16x16x32_bf16 v[142:145], v[22:25], v[110:113], v[142:145]
	v_mfma_f32_16x16x32_bf16 v[150:153], v[22:25], v[118:121], v[150:153]
	v_mfma_f32_16x16x32_bf16 v[158:161], v[22:25], v[126:129], v[158:161]
	v_mfma_f32_16x16x32_bf16 v[14:17], v[22:25], v[134:137], v[14:17]
	s_barrier
	s_add_u32 s40, s16, 0x10100
	s_addc_u32 s41, s17, 0
	s_add_i32 s34, s36, s53
	s_mov_b32 m0, s34
	s_add_i32 s36, s34, 0x2000
	global_load_lds_dwordx4 v6, s[40:41]
	s_mov_b32 m0, s36
	s_nop 0
	global_load_lds_dwordx4 v8, s[40:41]
	s_waitcnt vmcnt(6)
	s_barrier
	v_mfma_f32_16x16x32_bf16 v[18:21], v[90:93], v[54:57], 0
	v_mfma_f32_16x16x32_bf16 v[22:25], v[98:101], v[54:57], 0
	v_mfma_f32_16x16x32_bf16 v[18:21], v[94:97], v[110:113], v[18:21]
	v_mfma_f32_16x16x32_bf16 v[22:25], v[102:105], v[110:113], v[22:25]
	v_mfma_f32_16x16x32_bf16 v[54:57], v[90:93], v[114:117], 0
	v_mfma_f32_16x16x32_bf16 v[110:113], v[98:101], v[114:117], 0
	v_mfma_f32_16x16x32_bf16 v[114:117], v[90:93], v[122:125], 0
	v_mfma_f32_16x16x32_bf16 v[90:93], v[90:93], v[130:133], 0
	v_mfma_f32_16x16x32_bf16 v[54:57], v[94:97], v[118:121], v[54:57]
	v_mfma_f32_16x16x32_bf16 v[110:113], v[102:105], v[118:121], v[110:113]
	v_mfma_f32_16x16x32_bf16 v[114:117], v[94:97], v[126:129], v[114:117]
	v_mfma_f32_16x16x32_bf16 v[118:121], v[98:101], v[122:125], 0
	v_mfma_f32_16x16x32_bf16 v[90:93], v[94:97], v[134:137], v[90:93]
	v_mfma_f32_16x16x32_bf16 v[94:97], v[98:101], v[130:133], 0
	v_mfma_f32_16x16x32_bf16 v[118:121], v[102:105], v[126:129], v[118:121]
	v_mfma_f32_16x16x32_bf16 v[94:97], v[102:105], v[134:137], v[94:97]
	s_barrier
	ds_read_b128 v[98:101], v236
	ds_read_b128 v[102:105], v236 offset:1024
	ds_read_b128 v[122:125], v236 offset:2048
	ds_read_b128 v[126:129], v236 offset:3072
	s_add_u32 s40, s14, 0x40100
	s_addc_u32 s41, s15, 0
	s_mov_b32 m0, s19
	ds_read_b128 v[130:133], v4 offset:32768
	ds_read_b128 v[134:137], v4 offset:33792
	ds_read_b128 v[162:165], v4 offset:34816
	ds_read_b128 v[166:169], v4 offset:35840
	ds_read_b128 v[170:173], v4 offset:36864
	ds_read_b128 v[174:177], v4 offset:37888
	ds_read_b128 v[178:181], v4 offset:38912
	ds_read_b128 v[182:185], v4 offset:39936
	global_load_lds_dwordx4 v0, s[40:41]
	s_mov_b32 m0, s20
	s_nop 0
	global_load_lds_dwordx4 v2, s[40:41]
	s_waitcnt lgkmcnt(8)
	s_barrier
	s_waitcnt lgkmcnt(0)
	s_waitcnt lgkmcnt(0)
	v_mfma_f32_16x16x32_bf16 v[58:61], v[98:101], v[130:133], v[58:61]
	v_mfma_f32_16x16x32_bf16 v[62:65], v[122:125], v[130:133], v[62:65]
	v_mfma_f32_16x16x32_bf16 v[66:69], v[98:101], v[162:165], v[66:69]
	v_mfma_f32_16x16x32_bf16 v[70:73], v[122:125], v[162:165], v[70:73]
	v_mfma_f32_16x16x32_bf16 v[74:77], v[98:101], v[170:173], v[74:77]
	v_mfma_f32_16x16x32_bf16 v[78:81], v[122:125], v[170:173], v[78:81]
	v_mfma_f32_16x16x32_bf16 v[82:85], v[98:101], v[178:181], v[82:85]
	v_mfma_f32_16x16x32_bf16 v[86:89], v[122:125], v[178:181], v[86:89]
	v_mfma_f32_16x16x32_bf16 v[58:61], v[102:105], v[134:137], v[58:61]
	v_mfma_f32_16x16x32_bf16 v[62:65], v[126:129], v[134:137], v[62:65]
	v_mfma_f32_16x16x32_bf16 v[66:69], v[102:105], v[166:169], v[66:69]
	v_mfma_f32_16x16x32_bf16 v[70:73], v[126:129], v[166:169], v[70:73]
	v_mfma_f32_16x16x32_bf16 v[74:77], v[102:105], v[174:177], v[74:77]
	v_mfma_f32_16x16x32_bf16 v[78:81], v[126:129], v[174:177], v[78:81]
	v_mfma_f32_16x16x32_bf16 v[82:85], v[102:105], v[182:185], v[82:85]
	v_mfma_f32_16x16x32_bf16 v[86:89], v[126:129], v[182:185], v[86:89]
	s_barrier
	s_mov_b64 s[40:41], 0x180
	s_add_i32 s39, s39, s53
	v_lshl_add_u64 v[190:191], v[190:191], 0, s[40:41]
	s_mov_b32 m0, s39
	s_add_i32 s37, s39, 0x2000
	ds_read_b128 v[186:189], v5
	ds_read_b128 v[192:195], v5 offset:1024
	ds_read_b128 v[204:207], v5 offset:2048
	ds_read_b128 v[208:211], v5 offset:3072
	global_load_lds_dwordx4 v[190:191], off
	v_lshl_add_u64 v[190:191], v[196:197], 0, s[40:41]
	s_mov_b32 m0, s37
	s_nop 0
	global_load_lds_dwordx4 v[190:191], off
	s_barrier
	s_waitcnt lgkmcnt(0)
	s_waitcnt lgkmcnt(0)
	v_mfma_f32_16x16x32_bf16 v[106:109], v[186:189], v[130:133], v[106:109]
	v_mfma_f32_16x16x32_bf16 v[26:29], v[204:207], v[130:133], v[26:29]
	v_mfma_f32_16x16x32_bf16 v[30:33], v[186:189], v[162:165], v[30:33]
	v_mfma_f32_16x16x32_bf16 v[34:37], v[204:207], v[162:165], v[34:37]
	v_mfma_f32_16x16x32_bf16 v[38:41], v[186:189], v[170:173], v[38:41]
	v_mfma_f32_16x16x32_bf16 v[42:45], v[204:207], v[170:173], v[42:45]
	v_mfma_f32_16x16x32_bf16 v[46:49], v[186:189], v[178:181], v[46:49]
	v_mfma_f32_16x16x32_bf16 v[50:53], v[204:207], v[178:181], v[50:53]
	v_mfma_f32_16x16x32_bf16 v[106:109], v[192:195], v[134:137], v[106:109]
	v_mfma_f32_16x16x32_bf16 v[26:29], v[208:211], v[134:137], v[26:29]
	v_mfma_f32_16x16x32_bf16 v[30:33], v[192:195], v[166:169], v[30:33]
	v_mfma_f32_16x16x32_bf16 v[34:37], v[208:211], v[166:169], v[34:37]
	v_mfma_f32_16x16x32_bf16 v[38:41], v[192:195], v[174:177], v[38:41]
	v_mfma_f32_16x16x32_bf16 v[42:45], v[208:211], v[174:177], v[42:45]
	v_mfma_f32_16x16x32_bf16 v[46:49], v[192:195], v[182:185], v[46:49]
	v_mfma_f32_16x16x32_bf16 v[50:53], v[208:211], v[182:185], v[50:53]
	s_mov_b32 m0, s21
	v_lshl_add_u64 v[190:191], v[198:199], 0, s[40:41]
	s_barrier
	ds_read_b128 v[130:133], v4 offset:49152
	ds_read_b128 v[134:137], v4 offset:50176
	ds_read_b128 v[162:165], v4 offset:51200
	ds_read_b128 v[166:169], v4 offset:52224
	ds_read_b128 v[170:173], v4 offset:53248
	ds_read_b128 v[174:177], v4 offset:54272
	ds_read_b128 v[178:181], v4 offset:55296
	ds_read_b128 v[182:185], v4 offset:56320
	global_load_lds_dwordx4 v[190:191], off
	v_lshl_add_u64 v[190:191], v[212:213], 0, s[40:41]
	s_mov_b32 m0, s22
	s_nop 0
	global_load_lds_dwordx4 v[190:191], off
	s_barrier
	s_waitcnt lgkmcnt(0)
	s_waitcnt lgkmcnt(0)
	v_mfma_f32_16x16x32_bf16 v[138:141], v[98:101], v[130:133], v[138:141]
	v_mfma_f32_16x16x32_bf16 v[142:145], v[122:125], v[130:133], v[142:145]
	v_mfma_f32_16x16x32_bf16 v[146:149], v[98:101], v[162:165], v[146:149]
	v_mfma_f32_16x16x32_bf16 v[150:153], v[122:125], v[162:165], v[150:153]
	v_mfma_f32_16x16x32_bf16 v[154:157], v[98:101], v[170:173], v[154:157]
	v_mfma_f32_16x16x32_bf16 v[158:161], v[122:125], v[170:173], v[158:161]
	v_mfma_f32_16x16x32_bf16 v[10:13], v[98:101], v[178:181], v[10:13]
	v_mfma_f32_16x16x32_bf16 v[14:17], v[122:125], v[178:181], v[14:17]
	v_mfma_f32_16x16x32_bf16 v[138:141], v[102:105], v[134:137], v[138:141]
	v_mfma_f32_16x16x32_bf16 v[142:145], v[126:129], v[134:137], v[142:145]
	v_mfma_f32_16x16x32_bf16 v[146:149], v[102:105], v[166:169], v[146:149]
	v_mfma_f32_16x16x32_bf16 v[150:153], v[126:129], v[166:169], v[150:153]
	v_mfma_f32_16x16x32_bf16 v[154:157], v[102:105], v[174:177], v[154:157]
	v_mfma_f32_16x16x32_bf16 v[158:161], v[126:129], v[174:177], v[158:161]
	v_mfma_f32_16x16x32_bf16 v[10:13], v[102:105], v[182:185], v[10:13]
	v_mfma_f32_16x16x32_bf16 v[14:17], v[126:129], v[182:185], v[14:17]
	s_barrier
	s_add_u32 s40, s16, 0x10180
	s_addc_u32 s41, s17, 0
	s_add_i32 s16, s29, s53
	s_mov_b32 m0, s16
	s_add_i32 s17, s16, 0x2000
	global_load_lds_dwordx4 v6, s[40:41]
	s_mov_b32 m0, s17
	s_nop 0
	global_load_lds_dwordx4 v8, s[40:41]
	s_waitcnt vmcnt(6)
	s_barrier
	v_mfma_f32_16x16x32_bf16 v[18:21], v[186:189], v[130:133], v[18:21]
	v_mfma_f32_16x16x32_bf16 v[22:25], v[204:207], v[130:133], v[22:25]
	v_mfma_f32_16x16x32_bf16 v[54:57], v[186:189], v[162:165], v[54:57]
	v_mfma_f32_16x16x32_bf16 v[98:101], v[204:207], v[162:165], v[110:113]
	v_mfma_f32_16x16x32_bf16 v[102:105], v[186:189], v[170:173], v[114:117]
	v_mfma_f32_16x16x32_bf16 v[110:113], v[204:207], v[170:173], v[118:121]
	v_mfma_f32_16x16x32_bf16 v[90:93], v[186:189], v[178:181], v[90:93]
	v_mfma_f32_16x16x32_bf16 v[94:97], v[204:207], v[178:181], v[94:97]
	v_mfma_f32_16x16x32_bf16 v[18:21], v[192:195], v[134:137], v[18:21]
	v_mfma_f32_16x16x32_bf16 v[22:25], v[208:211], v[134:137], v[22:25]
	v_mfma_f32_16x16x32_bf16 v[54:57], v[192:195], v[166:169], v[54:57]
	v_mfma_f32_16x16x32_bf16 v[98:101], v[208:211], v[166:169], v[98:101]
	v_mfma_f32_16x16x32_bf16 v[102:105], v[192:195], v[174:177], v[102:105]
	v_mfma_f32_16x16x32_bf16 v[110:113], v[208:211], v[174:177], v[110:113]
	v_mfma_f32_16x16x32_bf16 v[90:93], v[192:195], v[182:185], v[90:93]
	v_mfma_f32_16x16x32_bf16 v[94:97], v[208:211], v[182:185], v[94:97]
	s_barrier
	ds_read_b128 v[114:117], v200
	ds_read_b128 v[118:121], v200 offset:1024
	ds_read_b128 v[122:125], v200 offset:2048
	ds_read_b128 v[126:129], v200 offset:3072
	s_add_u32 s14, s14, 0x40180
	s_addc_u32 s15, s15, 0
	s_mov_b32 m0, s30
	ds_read_b128 v[130:133], v4
	ds_read_b128 v[134:137], v4 offset:1024
	ds_read_b128 v[162:165], v4 offset:2048
	ds_read_b128 v[166:169], v4 offset:3072
	ds_read_b128 v[170:173], v4 offset:4096
	ds_read_b128 v[174:177], v4 offset:5120
	ds_read_b128 v[178:181], v4 offset:6144
	ds_read_b128 v[182:185], v4 offset:7168
	global_load_lds_dwordx4 v0, s[14:15]
	s_mov_b32 m0, s31
	s_nop 0
	global_load_lds_dwordx4 v2, s[14:15]
	s_waitcnt lgkmcnt(8)
	s_barrier
	s_waitcnt lgkmcnt(0)
	s_waitcnt lgkmcnt(0)
	v_mfma_f32_16x16x32_bf16 v[58:61], v[114:117], v[130:133], v[58:61]
	v_mfma_f32_16x16x32_bf16 v[62:65], v[122:125], v[130:133], v[62:65]
	v_mfma_f32_16x16x32_bf16 v[66:69], v[114:117], v[162:165], v[66:69]
	v_mfma_f32_16x16x32_bf16 v[70:73], v[122:125], v[162:165], v[70:73]
	v_mfma_f32_16x16x32_bf16 v[74:77], v[114:117], v[170:173], v[74:77]
	v_mfma_f32_16x16x32_bf16 v[78:81], v[122:125], v[170:173], v[78:81]
	v_mfma_f32_16x16x32_bf16 v[82:85], v[114:117], v[178:181], v[82:85]
	v_mfma_f32_16x16x32_bf16 v[86:89], v[122:125], v[178:181], v[86:89]
	v_mfma_f32_16x16x32_bf16 v[58:61], v[118:121], v[134:137], v[58:61]
	v_mfma_f32_16x16x32_bf16 v[62:65], v[126:129], v[134:137], v[62:65]
	v_mfma_f32_16x16x32_bf16 v[66:69], v[118:121], v[166:169], v[66:69]
	v_mfma_f32_16x16x32_bf16 v[70:73], v[126:129], v[166:169], v[70:73]
	v_mfma_f32_16x16x32_bf16 v[74:77], v[118:121], v[174:177], v[74:77]
	v_mfma_f32_16x16x32_bf16 v[78:81], v[126:129], v[174:177], v[78:81]
	v_mfma_f32_16x16x32_bf16 v[82:85], v[118:121], v[182:185], v[82:85]
	v_mfma_f32_16x16x32_bf16 v[86:89], v[126:129], v[182:185], v[86:89]
	s_barrier
	s_mov_b32 m0, s38
	ds_read_b128 v[186:189], v201
	ds_read_b128 v[192:195], v201 offset:1024
	ds_read_b128 v[204:207], v201 offset:2048
	ds_read_b128 v[208:211], v201 offset:3072
	global_load_lds_dwordx4 v6, s[10:11]
	s_mov_b32 m0, s35
	v_lshl_add_u64 v[190:191], s[10:11], 0, v[6:7]
	global_load_lds_dwordx4 v8, s[10:11]
	s_barrier
	s_waitcnt lgkmcnt(0)
	v_lshl_add_u64 v[248:249], s[10:11], 0, v[8:9]
	s_waitcnt lgkmcnt(0)
	v_mfma_f32_16x16x32_bf16 v[106:109], v[186:189], v[130:133], v[106:109]
	v_mfma_f32_16x16x32_bf16 v[26:29], v[204:207], v[130:133], v[26:29]
	v_mfma_f32_16x16x32_bf16 v[30:33], v[186:189], v[162:165], v[30:33]
	v_mfma_f32_16x16x32_bf16 v[34:37], v[204:207], v[162:165], v[34:37]
	v_mfma_f32_16x16x32_bf16 v[38:41], v[186:189], v[170:173], v[38:41]
	v_mfma_f32_16x16x32_bf16 v[42:45], v[204:207], v[170:173], v[42:45]
	v_mfma_f32_16x16x32_bf16 v[46:49], v[186:189], v[178:181], v[46:49]
	v_mfma_f32_16x16x32_bf16 v[50:53], v[204:207], v[178:181], v[50:53]
	v_mfma_f32_16x16x32_bf16 v[212:215], v[192:195], v[134:137], v[106:109]
	v_mfma_f32_16x16x32_bf16 v[26:29], v[208:211], v[134:137], v[26:29]
	v_mfma_f32_16x16x32_bf16 v[30:33], v[192:195], v[166:169], v[30:33]
	v_mfma_f32_16x16x32_bf16 v[34:37], v[208:211], v[166:169], v[34:37]
	v_mfma_f32_16x16x32_bf16 v[38:41], v[192:195], v[174:177], v[38:41]
	v_mfma_f32_16x16x32_bf16 v[42:45], v[208:211], v[174:177], v[42:45]
	v_mfma_f32_16x16x32_bf16 v[46:49], v[192:195], v[182:185], v[46:49]
	v_mfma_f32_16x16x32_bf16 v[50:53], v[208:211], v[182:185], v[50:53]
	s_mov_b32 m0, s63
	s_barrier
	ds_read_b128 v[106:109], v4 offset:16384
	ds_read_b128 v[130:133], v4 offset:17408
	ds_read_b128 v[134:137], v4 offset:18432
	ds_read_b128 v[162:165], v4 offset:19456
	ds_read_b128 v[166:169], v4 offset:20480
	ds_read_b128 v[170:173], v4 offset:21504
	ds_read_b128 v[174:177], v4 offset:22528
	ds_read_b128 v[178:181], v4 offset:23552
	global_load_lds_dwordx4 v0, s[8:9]
	s_mov_b32 m0, s18
	v_lshl_add_u64 v[202:203], s[8:9], 0, v[0:1]
	global_load_lds_dwordx4 v2, s[8:9]
	s_barrier
	s_waitcnt lgkmcnt(0)
	v_lshl_add_u64 v[200:201], s[8:9], 0, v[2:3]
	s_waitcnt lgkmcnt(0)
	v_mfma_f32_16x16x32_bf16 v[138:141], v[114:117], v[106:109], v[138:141]
	v_mfma_f32_16x16x32_bf16 v[182:185], v[118:121], v[130:133], v[138:141]
	v_mfma_f32_16x16x32_bf16 v[138:141], v[122:125], v[106:109], v[142:145]
	v_mfma_f32_16x16x32_bf16 v[216:219], v[126:129], v[130:133], v[138:141]
	v_mfma_f32_16x16x32_bf16 v[138:141], v[114:117], v[134:137], v[146:149]
	v_mfma_f32_16x16x32_bf16 v[146:149], v[118:121], v[162:165], v[138:141]
	v_mfma_f32_16x16x32_bf16 v[138:141], v[122:125], v[134:137], v[150:153]
	v_mfma_f32_16x16x32_bf16 v[220:223], v[126:129], v[162:165], v[138:141]
	v_mfma_f32_16x16x32_bf16 v[138:141], v[114:117], v[166:169], v[154:157]
	v_mfma_f32_16x16x32_bf16 v[224:227], v[118:121], v[170:173], v[138:141]
	v_mfma_f32_16x16x32_bf16 v[138:141], v[122:125], v[166:169], v[158:161]
	v_mfma_f32_16x16x32_bf16 v[10:13], v[114:117], v[174:177], v[10:13]
	v_mfma_f32_16x16x32_bf16 v[14:17], v[122:125], v[174:177], v[14:17]
	v_mfma_f32_16x16x32_bf16 v[158:161], v[126:129], v[170:173], v[138:141]
	v_mfma_f32_16x16x32_bf16 v[10:13], v[118:121], v[178:181], v[10:13]
	v_mfma_f32_16x16x32_bf16 v[14:17], v[126:129], v[178:181], v[14:17]
	s_barrier
	s_add_u32 s14, s10, 0x10000
	s_addc_u32 s15, s11, 0
	s_mov_b32 m0, s34
	s_nop 0
	global_load_lds_dwordx4 v6, s[14:15]
	s_mov_b32 m0, s36
	s_nop 0
	global_load_lds_dwordx4 v8, s[14:15]
	s_waitcnt vmcnt(6)
	s_barrier
	v_mfma_f32_16x16x32_bf16 v[18:21], v[186:189], v[106:109], v[18:21]
	v_mfma_f32_16x16x32_bf16 v[228:231], v[192:195], v[130:133], v[18:21]
	v_mfma_f32_16x16x32_bf16 v[18:21], v[204:207], v[106:109], v[22:25]
	v_mfma_f32_16x16x32_bf16 v[22:25], v[208:211], v[130:133], v[18:21]
	v_mfma_f32_16x16x32_bf16 v[18:21], v[186:189], v[134:137], v[54:57]
	v_mfma_f32_16x16x32_bf16 v[54:57], v[192:195], v[162:165], v[18:21]
	v_mfma_f32_16x16x32_bf16 v[18:21], v[204:207], v[134:137], v[98:101]
	v_mfma_f32_16x16x32_bf16 v[162:165], v[208:211], v[162:165], v[18:21]
	v_mfma_f32_16x16x32_bf16 v[18:21], v[186:189], v[166:169], v[102:105]
	v_mfma_f32_16x16x32_bf16 v[232:235], v[192:195], v[170:173], v[18:21]
	v_mfma_f32_16x16x32_bf16 v[18:21], v[204:207], v[166:169], v[110:113]
	v_mfma_f32_16x16x32_bf16 v[166:169], v[208:211], v[170:173], v[18:21]
	v_mfma_f32_16x16x32_bf16 v[18:21], v[186:189], v[174:177], v[90:93]
	v_mfma_f32_16x16x32_bf16 v[170:173], v[192:195], v[178:181], v[18:21]
	v_mfma_f32_16x16x32_bf16 v[18:21], v[204:207], v[174:177], v[94:97]
	v_mfma_f32_16x16x32_bf16 v[174:177], v[208:211], v[178:181], v[18:21]
	s_barrier
	s_nop 4
	ds_read_b128 v[18:21], v236
	ds_read_b128 v[178:181], v236 offset:1024
	ds_read_b128 v[186:189], v236 offset:2048
	ds_read_b128 v[192:195], v236 offset:3072
	s_add_u32 s14, s8, 0x40000
	s_addc_u32 s15, s9, 0
	s_mov_b32 m0, s19
	ds_read_b128 v[94:97], v4 offset:32768
	ds_read_b128 v[102:105], v4 offset:33792
	ds_read_b128 v[110:113], v4 offset:34816
	ds_read_b128 v[118:121], v4 offset:35840
	ds_read_b128 v[204:207], v4 offset:36864
	ds_read_b128 v[208:211], v4 offset:37888
	ds_read_b128 v[236:239], v4 offset:38912
	ds_read_b128 v[240:243], v4 offset:39936
	global_load_lds_dwordx4 v0, s[14:15]
	s_mov_b32 m0, s20
	s_nop 0
	global_load_lds_dwordx4 v2, s[14:15]
	s_waitcnt lgkmcnt(8)
	s_barrier
	s_waitcnt lgkmcnt(0)
	s_waitcnt lgkmcnt(0)
	v_mfma_f32_16x16x32_bf16 v[58:61], v[18:21], v[94:97], v[58:61]
	v_mfma_f32_16x16x32_bf16 v[150:153], v[178:181], v[102:105], v[58:61]
	v_mfma_f32_16x16x32_bf16 v[58:61], v[186:189], v[94:97], v[62:65]
	v_mfma_f32_16x16x32_bf16 v[138:141], v[192:195], v[102:105], v[58:61]
	v_mfma_f32_16x16x32_bf16 v[58:61], v[18:21], v[110:113], v[66:69]
	v_mfma_f32_16x16x32_bf16 v[130:133], v[178:181], v[118:121], v[58:61]
	v_mfma_f32_16x16x32_bf16 v[58:61], v[186:189], v[110:113], v[70:73]
	v_mfma_f32_16x16x32_bf16 v[122:125], v[192:195], v[118:121], v[58:61]
	v_mfma_f32_16x16x32_bf16 v[58:61], v[18:21], v[204:207], v[74:77]
	v_mfma_f32_16x16x32_bf16 v[114:117], v[178:181], v[208:211], v[58:61]
	v_mfma_f32_16x16x32_bf16 v[58:61], v[186:189], v[204:207], v[78:81]
	v_mfma_f32_16x16x32_bf16 v[106:109], v[192:195], v[208:211], v[58:61]
	v_mfma_f32_16x16x32_bf16 v[58:61], v[18:21], v[236:239], v[82:85]
	v_mfma_f32_16x16x32_bf16 v[98:101], v[178:181], v[240:243], v[58:61]
	v_mfma_f32_16x16x32_bf16 v[58:61], v[186:189], v[236:239], v[86:89]
	v_mfma_f32_16x16x32_bf16 v[90:93], v[192:195], v[240:243], v[58:61]
	s_barrier
	s_mov_b32 m0, s39
	v_lshl_add_u64 v[2:3], v[190:191], 0, s[70:71]
	ds_read_b128 v[244:247], v5
	ds_read_b128 v[196:199], v5 offset:1024
	s_nop 0
	ds_read_b128 v[58:61], v5 offset:2048
	ds_read_b128 v[62:65], v5 offset:3072
	global_load_lds_dwordx4 v[2:3], off
	v_lshl_add_u64 v[2:3], v[248:249], 0, s[70:71]
	s_mov_b32 m0, s37
	s_nop 0
	global_load_lds_dwordx4 v[2:3], off
	s_barrier
	s_waitcnt lgkmcnt(0)
	s_waitcnt lgkmcnt(0)
	v_mfma_f32_16x16x32_bf16 v[26:29], v[58:61], v[94:97], v[26:29]
	v_mfma_f32_16x16x32_bf16 v[142:145], v[62:65], v[102:105], v[26:29]
	v_mfma_f32_16x16x32_bf16 v[26:29], v[244:247], v[110:113], v[30:33]
	v_mfma_f32_16x16x32_bf16 v[134:137], v[196:199], v[118:121], v[26:29]
	v_mfma_f32_16x16x32_bf16 v[26:29], v[58:61], v[110:113], v[34:37]
	v_mfma_f32_16x16x32_bf16 v[126:129], v[62:65], v[118:121], v[26:29]
	v_mfma_f32_16x16x32_bf16 v[26:29], v[244:247], v[204:207], v[38:41]
	v_mfma_f32_16x16x32_bf16 v[118:121], v[196:199], v[208:211], v[26:29]
	v_mfma_f32_16x16x32_bf16 v[26:29], v[58:61], v[204:207], v[42:45]
	v_mfma_f32_16x16x32_bf16 v[66:69], v[244:247], v[94:97], v[212:215]
	v_mfma_f32_16x16x32_bf16 v[110:113], v[62:65], v[208:211], v[26:29]
	v_mfma_f32_16x16x32_bf16 v[26:29], v[244:247], v[236:239], v[46:49]
	v_mfma_f32_16x16x32_bf16 v[154:157], v[196:199], v[102:105], v[66:69]
	v_mfma_f32_16x16x32_bf16 v[102:105], v[196:199], v[240:243], v[26:29]
	v_mfma_f32_16x16x32_bf16 v[26:29], v[58:61], v[236:239], v[50:53]
	v_mfma_f32_16x16x32_bf16 v[94:97], v[62:65], v[240:243], v[26:29]
	s_mov_b32 m0, s21
	v_lshl_add_u64 v[2:3], v[202:203], 0, s[70:71]
	s_barrier
	s_nop 2
	ds_read_b128 v[26:29], v4 offset:49152
	ds_read_b128 v[30:33], v4 offset:50176
	ds_read_b128 v[34:37], v4 offset:51200
	ds_read_b128 v[42:45], v4 offset:52224
	ds_read_b128 v[46:49], v4 offset:53248
	ds_read_b128 v[204:207], v4 offset:54272
	ds_read_b128 v[208:211], v4 offset:55296
	ds_read_b128 v[212:215], v4 offset:56320
	global_load_lds_dwordx4 v[2:3], off
	v_lshl_add_u64 v[2:3], v[200:201], 0, s[70:71]
	s_mov_b32 m0, s22
	s_nop 0
	global_load_lds_dwordx4 v[2:3], off
	s_barrier
	s_waitcnt lgkmcnt(0)
	s_waitcnt lgkmcnt(0)
	v_mfma_f32_16x16x32_bf16 v[2:5], v[18:21], v[26:29], v[182:185]
	v_mfma_f32_16x16x32_bf16 v[82:85], v[178:181], v[30:33], v[2:5]
	v_mfma_f32_16x16x32_bf16 v[2:5], v[186:189], v[26:29], v[216:219]
	v_mfma_f32_16x16x32_bf16 v[74:77], v[192:195], v[30:33], v[2:5]
	v_mfma_f32_16x16x32_bf16 v[2:5], v[18:21], v[34:37], v[146:149]
	v_mfma_f32_16x16x32_bf16 v[66:69], v[178:181], v[42:45], v[2:5]
	v_mfma_f32_16x16x32_bf16 v[2:5], v[186:189], v[34:37], v[220:223]
	v_mfma_f32_16x16x32_bf16 v[182:185], v[192:195], v[42:45], v[2:5]
	v_mfma_f32_16x16x32_bf16 v[2:5], v[18:21], v[46:49], v[224:227]
	v_mfma_f32_16x16x32_bf16 v[50:53], v[178:181], v[204:207], v[2:5]
	v_mfma_f32_16x16x32_bf16 v[2:5], v[186:189], v[46:49], v[158:161]
	v_mfma_f32_16x16x32_bf16 v[38:41], v[192:195], v[204:207], v[2:5]
	v_mfma_f32_16x16x32_bf16 v[2:5], v[18:21], v[208:211], v[10:13]
	v_mfma_f32_16x16x32_bf16 v[18:21], v[178:181], v[212:215], v[2:5]
	v_mfma_f32_16x16x32_bf16 v[2:5], v[186:189], v[208:211], v[14:17]
	v_mfma_f32_16x16x32_bf16 v[2:5], v[192:195], v[212:215], v[2:5]
	s_barrier
	s_add_u32 s14, s10, 0x10080
	s_addc_u32 s15, s11, 0
	s_mov_b32 m0, s16
	s_nop 0
	global_load_lds_dwordx4 v6, s[14:15]
	s_mov_b32 m0, s17
	s_nop 0
	global_load_lds_dwordx4 v8, s[14:15]
	s_waitcnt vmcnt(6)
	s_barrier
	v_mfma_f32_16x16x32_bf16 v[6:9], v[244:247], v[26:29], v[228:231]
	v_mfma_f32_16x16x32_bf16 v[86:89], v[196:199], v[30:33], v[6:9]
	v_mfma_f32_16x16x32_bf16 v[6:9], v[58:61], v[26:29], v[22:25]
	v_mfma_f32_16x16x32_bf16 v[78:81], v[62:65], v[30:33], v[6:9]
	v_mfma_f32_16x16x32_bf16 v[6:9], v[244:247], v[34:37], v[54:57]
	v_mfma_f32_16x16x32_bf16 v[70:73], v[196:199], v[42:45], v[6:9]
	v_mfma_f32_16x16x32_bf16 v[6:9], v[58:61], v[34:37], v[162:165]
	v_mfma_f32_16x16x32_bf16 v[178:181], v[62:65], v[42:45], v[6:9]
	v_mfma_f32_16x16x32_bf16 v[6:9], v[244:247], v[46:49], v[232:235]
	v_mfma_f32_16x16x32_bf16 v[54:57], v[196:199], v[204:207], v[6:9]
	v_mfma_f32_16x16x32_bf16 v[6:9], v[58:61], v[46:49], v[166:169]
	v_mfma_f32_16x16x32_bf16 v[42:45], v[62:65], v[204:207], v[6:9]
	v_mfma_f32_16x16x32_bf16 v[6:9], v[244:247], v[208:211], v[170:173]
	v_mfma_f32_16x16x32_bf16 v[22:25], v[196:199], v[212:215], v[6:9]
	v_mfma_f32_16x16x32_bf16 v[6:9], v[58:61], v[208:211], v[174:177]
	v_mfma_f32_16x16x32_bf16 v[6:9], v[62:65], v[212:215], v[6:9]
	s_barrier
	v_mbcnt_lo_u32_b32 v0, -1, 0
	v_mbcnt_hi_u32_b32 v0, -1, v0
	v_readlane_b32 s16, v254, 23
	v_lshrrev_b32_e32 v10, 1, v0
	v_and_b32_e32 v10, 24, v10
	v_lshl_or_b32 v10, s28, 7, v10
	v_or_b32_e32 v34, s16, v10
	v_ashrrev_i32_e32 v35, 31, v34
	v_lshlrev_b64 v[14:15], 2, v[34:35]
	s_mov_b32 s14, s48
	s_mov_b32 s15, s49
	v_lshl_add_u64 v[16:17], s[4:5], 0, v[14:15]
	global_load_dwordx4 v[10:13], v[16:17], off offset:16
	global_load_dwordx4 v[26:29], v[16:17], off
	v_lshl_add_u64 v[30:31], s[6:7], 0, v[14:15]
	v_lshl_add_u64 v[36:37], s[14:15], 0, v[14:15]
	global_load_dwordx4 v[14:17], v[30:31], off offset:16
	s_nop 0
	global_load_dwordx4 v[30:33], v[30:31], off
	s_mov_b64 s[16:17], 0x15182400
	v_lshl_add_u64 v[58:59], v[36:37], 0, s[16:17]
	s_add_u32 s16, s14, 0xe400000
	s_addc_u32 s17, s15, 0
	s_lshl_b32 s27, s27, 8
	s_add_i32 s27, s27, s42
	v_and_or_b32 v164, v0, 15, s27
	v_ashrrev_i32_e32 v165, 31, v164
	v_lshlrev_b64 v[158:159], 11, v[164:165]
	v_lshl_add_u64 v[46:47], s[16:17], 0, v[158:159]
	v_lshlrev_b64 v[34:35], 1, v[34:35]
	v_lshl_add_u64 v[46:47], v[46:47], 0, v[34:35]
	v_lshl_add_u64 v[166:167], s[16:17], 0, v[34:35]
	v_lshl_add_u64 v[34:35], s[14:15], 0, v[34:35]
	s_mov_b64 s[14:15], 0x4180000
	v_lshl_add_u64 v[160:161], v[34:35], 0, s[14:15]
	s_mov_b64 s[14:15], 0x8280000
	v_lshl_add_u64 v[162:163], v[34:35], 0, s[14:15]
	v_or_b32_e32 v34, 16, v164
	v_ashrrev_i32_e32 v35, 31, v34
	v_lshlrev_b64 v[168:169], 11, v[34:35]
	global_load_dwordx4 v[146:149], v[46:47], off
	s_mov_b32 s14, 0x15182000
	v_lshl_add_u64 v[170:171], v[166:167], 0, v[168:169]
	s_waitcnt vmcnt(0)
	v_add_f32_e32 v0, v150, v26
	v_med3_f32 v0, v0, s84, v250
	v_mul_f32_e32 v0, 0xbfb8aa3b, v0
	v_add_f32_e32 v34, v154, v30
	v_med3_f32 v35, v34, s84, v250
	v_exp_f32_e32 v34, v0
	v_mul_f32_e32 v0, 0xbfb8aa3b, v35
	v_exp_f32_e32 v60, v0
	v_add_f32_e32 v0, v151, v27
	v_med3_f32 v0, v0, s84, v250
	v_add_f32_e32 v35, v155, v31
	v_mul_f32_e32 v0, 0xbfb8aa3b, v0
	v_med3_f32 v46, v35, s84, v250
	v_exp_f32_e32 v35, v0
	v_mul_f32_e32 v0, 0xbfb8aa3b, v46
	v_exp_f32_e32 v61, v0
	v_pk_add_f32 v[62:63], v[34:35], 1.0 op_sel_hi:[1,0]
	v_add_co_u32_e32 v34, vcc, s14, v36
	s_nop 1
	v_addc_co_u32_e32 v35, vcc, 0, v37, vcc
	global_load_dwordx4 v[46:49], v[34:35], off offset:1024
	s_nop 0
	global_load_dwordx4 v[34:37], v[58:59], off offset:16
	v_pk_add_f32 v[58:59], v[60:61], 1.0 op_sel_hi:[1,0]
	s_nop 0
	v_pk_mul_f32 v[60:61], v[62:63], v[58:59]
	s_nop 0
	v_rcp_f32_e32 v60, v60
	v_rcp_f32_e32 v61, v61
	s_nop 0
	v_pk_mul_f32 v[58:59], v[58:59], v[60:61]
	v_pk_mul_f32 v[60:61], v[62:63], v[60:61]
	v_lshlrev_b32_e32 v62, 16, v146
	v_and_b32_e32 v63, 0xffff0000, v146
	s_waitcnt vmcnt(0)
	v_pk_mul_f32 v[150:151], v[46:47], v[58:59]
	s_nop 0
	v_add_f32_e32 v0, v150, v150
	v_exp_f32_e32 v0, v0
	s_nop 0
	v_sub_f32_e32 v0, 1.0, v0
	v_max_f32_e32 v0, 0, v0
	v_sqrt_f32_e32 v58, v0
	v_add_f32_e32 v0, v151, v151
	v_exp_f32_e32 v0, v0
	s_nop 0
	v_sub_f32_e32 v0, 1.0, v0
	v_max_f32_e32 v0, 0, v0
	v_sqrt_f32_e32 v59, v0
	v_add_f32_e32 v0, v152, v28
	v_med3_f32 v0, v0, s84, v250
	v_mul_f32_e32 v0, 0xbfb8aa3b, v0
	v_pk_mul_f32 v[58:59], v[60:61], v[58:59]
	s_nop 0
	v_pk_mul_f32 v[154:155], v[58:59], v[62:63]
	v_add_f32_e32 v58, v156, v32
	v_med3_f32 v59, v58, s84, v250
	v_exp_f32_e32 v58, v0
	v_mul_f32_e32 v0, 0xbfb8aa3b, v59
	v_exp_f32_e32 v60, v0
	v_add_f32_e32 v0, v153, v29
	v_med3_f32 v0, v0, s84, v250
	v_add_f32_e32 v59, v157, v33
	v_med3_f32 v61, v59, s84, v250
	v_mul_f32_e32 v0, 0xbfb8aa3b, v0
	v_exp_f32_e32 v59, v0
	v_mul_f32_e32 v0, 0xbfb8aa3b, v61
	v_exp_f32_e32 v61, v0
	v_pk_add_f32 v[58:59], v[58:59], 1.0 op_sel_hi:[1,0]
	v_pk_add_f32 v[60:61], v[60:61], 1.0 op_sel_hi:[1,0]
	s_nop 0
	v_pk_mul_f32 v[62:63], v[58:59], v[60:61]
	s_nop 0
	v_rcp_f32_e32 v62, v62
	v_rcp_f32_e32 v63, v63
	s_nop 0
	v_pk_mul_f32 v[60:61], v[60:61], v[62:63]
	s_nop 0
	v_pk_mul_f32 v[152:153], v[48:49], v[60:61]
	v_pk_mul_f32 v[58:59], v[58:59], v[62:63]
	v_add_f32_e32 v0, v152, v152
	v_exp_f32_e32 v0, v0
	v_lshlrev_b32_e32 v62, 16, v147
	v_and_b32_e32 v63, 0xffff0000, v147
	v_sub_f32_e32 v0, 1.0, v0
	v_max_f32_e32 v0, 0, v0
	v_sqrt_f32_e32 v60, v0
	v_add_f32_e32 v0, v153, v153
	v_exp_f32_e32 v0, v0
	s_nop 0
	v_sub_f32_e32 v0, 1.0, v0
	v_max_f32_e32 v0, 0, v0
	v_sqrt_f32_e32 v61, v0
	v_add_f32_e32 v0, v138, v10
	v_med3_f32 v0, v0, s84, v250
	v_mul_f32_e32 v0, 0xbfb8aa3b, v0
	v_pk_mul_f32 v[58:59], v[58:59], v[60:61]
	s_nop 0
	v_pk_mul_f32 v[146:147], v[58:59], v[62:63]
	v_add_f32_e32 v58, v142, v14
	v_med3_f32 v59, v58, s84, v250
	v_exp_f32_e32 v58, v0
	v_mul_f32_e32 v0, 0xbfb8aa3b, v59
	v_exp_f32_e32 v60, v0
	v_add_f32_e32 v0, v139, v11
	v_med3_f32 v0, v0, s84, v250
	v_add_f32_e32 v59, v143, v15
	v_med3_f32 v61, v59, s84, v250
	v_mul_f32_e32 v0, 0xbfb8aa3b, v0
	v_exp_f32_e32 v59, v0
	v_mul_f32_e32 v0, 0xbfb8aa3b, v61
	v_exp_f32_e32 v61, v0
	v_pk_add_f32 v[58:59], v[58:59], 1.0 op_sel_hi:[1,0]
	v_pk_add_f32 v[60:61], v[60:61], 1.0 op_sel_hi:[1,0]
	s_nop 0
	v_pk_mul_f32 v[62:63], v[58:59], v[60:61]
	s_nop 0
	v_rcp_f32_e32 v62, v62
	v_rcp_f32_e32 v63, v63
	s_nop 0
	v_pk_mul_f32 v[60:61], v[60:61], v[62:63]
	s_nop 0
	v_pk_mul_f32 v[60:61], v[34:35], v[60:61]
	v_pk_mul_f32 v[58:59], v[58:59], v[62:63]
	v_add_f32_e32 v0, v60, v60
	v_exp_f32_e32 v0, v0
	v_lshlrev_b32_e32 v62, 16, v148
	v_and_b32_e32 v63, 0xffff0000, v148
	v_sub_f32_e32 v0, 1.0, v0
	v_max_f32_e32 v0, 0, v0
	v_sqrt_f32_e32 v64, v0
	v_add_f32_e32 v0, v61, v61
	v_exp_f32_e32 v0, v0
	s_nop 0
	v_sub_f32_e32 v0, 1.0, v0
	v_max_f32_e32 v0, 0, v0
	v_sqrt_f32_e32 v65, v0
	v_add_f32_e32 v0, v140, v12
	v_med3_f32 v0, v0, s84, v250
	v_mul_f32_e32 v0, 0xbfb8aa3b, v0
	v_pk_mul_f32 v[58:59], v[58:59], v[64:65]
	s_nop 0
	v_pk_mul_f32 v[64:65], v[58:59], v[62:63]
	v_add_f32_e32 v58, v144, v16
	v_med3_f32 v59, v58, s84, v250
	v_exp_f32_e32 v58, v0
	v_mul_f32_e32 v0, 0xbfb8aa3b, v59
	v_exp_f32_e32 v62, v0
	v_add_f32_e32 v0, v141, v13
	v_med3_f32 v0, v0, s84, v250
	v_add_f32_e32 v59, v145, v17
	v_mul_f32_e32 v0, 0xbfb8aa3b, v0
	v_med3_f32 v63, v59, s84, v250
	v_exp_f32_e32 v59, v0
	v_mul_f32_e32 v0, 0xbfb8aa3b, v63
	v_exp_f32_e32 v63, v0
	v_pk_add_f32 v[58:59], v[58:59], 1.0 op_sel_hi:[1,0]
	global_load_dwordx4 v[142:145], v[170:171], off
	v_pk_add_f32 v[62:63], v[62:63], 1.0 op_sel_hi:[1,0]
	v_cvt_pk_bf16_f32 v60, v60, v61
	v_pk_mul_f32 v[138:139], v[58:59], v[62:63]
	v_cvt_pk_bf16_f32 v64, v64, v65
	v_rcp_f32_e32 v138, v138
	v_rcp_f32_e32 v139, v139
	s_nop 0
	v_pk_mul_f32 v[62:63], v[62:63], v[138:139]
	s_nop 0
	v_pk_mul_f32 v[62:63], v[36:37], v[62:63]
	v_pk_mul_f32 v[58:59], v[58:59], v[138:139]
	v_add_f32_e32 v0, v62, v62
	v_exp_f32_e32 v0, v0
	v_lshlrev_b32_e32 v138, 16, v149
	v_and_b32_e32 v139, 0xffff0000, v149
	v_cvt_pk_bf16_f32 v61, v62, v63
	v_sub_f32_e32 v0, 1.0, v0
	v_max_f32_e32 v0, 0, v0
	v_sqrt_f32_e32 v140, v0
	v_add_f32_e32 v0, v63, v63
	v_exp_f32_e32 v0, v0
	v_cvt_pk_bf16_f32 v62, v154, v155
	v_cvt_pk_bf16_f32 v63, v146, v147
	v_sub_f32_e32 v0, 1.0, v0
	v_max_f32_e32 v0, 0, v0
	v_sqrt_f32_e32 v141, v0
	s_nop 0
	v_pk_mul_f32 v[58:59], v[58:59], v[140:141]
	s_nop 0
	v_pk_mul_f32 v[138:139], v[58:59], v[138:139]
	v_cvt_pk_bf16_f32 v58, v150, v151
	v_cvt_pk_bf16_f32 v59, v152, v153
	v_cvt_pk_bf16_f32 v65, v138, v139
	v_lshl_add_u64 v[138:139], v[160:161], 0, v[158:159]
	global_store_dwordx4 v[138:139], v[58:61], off
	s_nop 1
	v_lshl_add_u64 v[58:59], v[162:163], 0, v[158:159]
	global_store_dwordx4 v[58:59], v[62:65], off
	v_or_b32_e32 v58, 32, v164
	v_ashrrev_i32_e32 v59, 31, v58
	v_lshlrev_b64 v[146:147], 11, v[58:59]
	v_lshl_add_u64 v[58:59], v[166:167], 0, v[146:147]
	v_add_f32_e32 v0, v130, v26
	global_load_dwordx4 v[138:141], v[58:59], off
	v_med3_f32 v0, v0, s84, v250
	v_add_f32_e32 v58, v134, v30
	v_med3_f32 v59, v58, s84, v250
	v_mul_f32_e32 v0, 0xbfb8aa3b, v0
	v_exp_f32_e32 v58, v0
	v_mul_f32_e32 v0, 0xbfb8aa3b, v59
	v_exp_f32_e32 v60, v0
	v_add_f32_e32 v0, v131, v27
	v_med3_f32 v0, v0, s84, v250
	v_add_f32_e32 v59, v135, v31
	v_med3_f32 v61, v59, s84, v250
	v_mul_f32_e32 v0, 0xbfb8aa3b, v0
	v_exp_f32_e32 v59, v0
	v_mul_f32_e32 v0, 0xbfb8aa3b, v61
	v_exp_f32_e32 v61, v0
	v_pk_add_f32 v[58:59], v[58:59], 1.0 op_sel_hi:[1,0]
	v_pk_add_f32 v[60:61], v[60:61], 1.0 op_sel_hi:[1,0]
	s_nop 0
	v_pk_mul_f32 v[62:63], v[58:59], v[60:61]
	s_nop 0
	v_rcp_f32_e32 v62, v62
	v_rcp_f32_e32 v63, v63
	s_nop 0
	v_pk_mul_f32 v[60:61], v[60:61], v[62:63]
	s_nop 0
	v_pk_mul_f32 v[130:131], v[46:47], v[60:61]
	v_pk_mul_f32 v[58:59], v[58:59], v[62:63]
	v_add_f32_e32 v0, v130, v130
	v_exp_f32_e32 v0, v0
	s_waitcnt vmcnt(0)
	v_lshlrev_b32_e32 v62, 16, v142
	v_and_b32_e32 v63, 0xffff0000, v142
	v_sub_f32_e32 v0, 1.0, v0
	v_max_f32_e32 v0, 0, v0
	v_sqrt_f32_e32 v60, v0
	v_add_f32_e32 v0, v131, v131
	v_exp_f32_e32 v0, v0
	s_nop 0
	v_sub_f32_e32 v0, 1.0, v0
	v_max_f32_e32 v0, 0, v0
	v_sqrt_f32_e32 v61, v0
	v_add_f32_e32 v0, v132, v28
	v_med3_f32 v0, v0, s84, v250
	v_mul_f32_e32 v0, 0xbfb8aa3b, v0
	v_pk_mul_f32 v[58:59], v[58:59], v[60:61]
	s_nop 0
	v_pk_mul_f32 v[134:135], v[58:59], v[62:63]
	v_add_f32_e32 v58, v136, v32
	v_med3_f32 v59, v58, s84, v250
	v_exp_f32_e32 v58, v0
	v_mul_f32_e32 v0, 0xbfb8aa3b, v59
	v_exp_f32_e32 v60, v0
	v_add_f32_e32 v0, v133, v29
	v_med3_f32 v0, v0, s84, v250
	v_add_f32_e32 v59, v137, v33
	v_med3_f32 v61, v59, s84, v250
	v_mul_f32_e32 v0, 0xbfb8aa3b, v0
	v_exp_f32_e32 v59, v0
	v_mul_f32_e32 v0, 0xbfb8aa3b, v61
	v_exp_f32_e32 v61, v0
	v_pk_add_f32 v[58:59], v[58:59], 1.0 op_sel_hi:[1,0]
	v_pk_add_f32 v[60:61], v[60:61], 1.0 op_sel_hi:[1,0]
	s_nop 0
	v_pk_mul_f32 v[62:63], v[58:59], v[60:61]
	s_nop 0
	v_rcp_f32_e32 v62, v62
	v_rcp_f32_e32 v63, v63
	s_nop 0
	v_pk_mul_f32 v[60:61], v[60:61], v[62:63]
	s_nop 0
	v_pk_mul_f32 v[132:133], v[48:49], v[60:61]
	v_pk_mul_f32 v[58:59], v[58:59], v[62:63]
	v_add_f32_e32 v0, v132, v132
	v_exp_f32_e32 v0, v0
	v_lshlrev_b32_e32 v62, 16, v143
	v_and_b32_e32 v63, 0xffff0000, v143
	v_sub_f32_e32 v0, 1.0, v0
	v_max_f32_e32 v0, 0, v0
	v_sqrt_f32_e32 v60, v0
	v_add_f32_e32 v0, v133, v133
	v_exp_f32_e32 v0, v0
	s_nop 0
	v_sub_f32_e32 v0, 1.0, v0
	v_max_f32_e32 v0, 0, v0
	v_sqrt_f32_e32 v61, v0
	v_add_f32_e32 v0, v122, v10
	v_med3_f32 v0, v0, s84, v250
	v_mul_f32_e32 v0, 0xbfb8aa3b, v0
	v_pk_mul_f32 v[58:59], v[58:59], v[60:61]
	s_nop 0
	v_pk_mul_f32 v[136:137], v[58:59], v[62:63]
	v_add_f32_e32 v58, v126, v14
	v_med3_f32 v59, v58, s84, v250
	v_exp_f32_e32 v58, v0
	v_mul_f32_e32 v0, 0xbfb8aa3b, v59
	v_exp_f32_e32 v60, v0
	v_add_f32_e32 v0, v123, v11
	v_med3_f32 v0, v0, s84, v250
	v_add_f32_e32 v59, v127, v15
	v_med3_f32 v61, v59, s84, v250
	v_mul_f32_e32 v0, 0xbfb8aa3b, v0
	v_exp_f32_e32 v59, v0
	v_mul_f32_e32 v0, 0xbfb8aa3b, v61
	v_exp_f32_e32 v61, v0
	v_pk_add_f32 v[58:59], v[58:59], 1.0 op_sel_hi:[1,0]
	v_pk_add_f32 v[60:61], v[60:61], 1.0 op_sel_hi:[1,0]
	s_nop 0
	v_pk_mul_f32 v[62:63], v[58:59], v[60:61]
	s_nop 0
	v_rcp_f32_e32 v62, v62
	v_rcp_f32_e32 v63, v63
	s_nop 0
	v_pk_mul_f32 v[60:61], v[60:61], v[62:63]
	s_nop 0
	v_pk_mul_f32 v[60:61], v[34:35], v[60:61]
	v_pk_mul_f32 v[58:59], v[58:59], v[62:63]
	v_add_f32_e32 v0, v60, v60
	v_exp_f32_e32 v0, v0
	v_lshlrev_b32_e32 v62, 16, v144
	v_and_b32_e32 v63, 0xffff0000, v144
	v_cvt_pk_bf16_f32 v60, v60, v61
	v_sub_f32_e32 v0, 1.0, v0
	v_max_f32_e32 v0, 0, v0
	v_sqrt_f32_e32 v64, v0
	v_add_f32_e32 v0, v61, v61
	v_exp_f32_e32 v0, v0
	s_nop 0
	v_sub_f32_e32 v0, 1.0, v0
	v_max_f32_e32 v0, 0, v0
	v_sqrt_f32_e32 v65, v0
	v_add_f32_e32 v0, v124, v12
	v_med3_f32 v0, v0, s84, v250
	v_mul_f32_e32 v0, 0xbfb8aa3b, v0
	v_pk_mul_f32 v[58:59], v[58:59], v[64:65]
	s_nop 0
	v_pk_mul_f32 v[64:65], v[58:59], v[62:63]
	v_add_f32_e32 v58, v128, v16
	v_med3_f32 v59, v58, s84, v250
	v_exp_f32_e32 v58, v0
	v_mul_f32_e32 v0, 0xbfb8aa3b, v59
	v_exp_f32_e32 v62, v0
	v_add_f32_e32 v0, v125, v13
	v_med3_f32 v0, v0, s84, v250
	v_add_f32_e32 v59, v129, v17
	v_med3_f32 v63, v59, s84, v250
	v_mul_f32_e32 v0, 0xbfb8aa3b, v0
	v_exp_f32_e32 v59, v0
	v_mul_f32_e32 v0, 0xbfb8aa3b, v63
	v_exp_f32_e32 v63, v0
	v_cvt_pk_bf16_f32 v64, v64, v65
	v_pk_add_f32 v[58:59], v[58:59], 1.0 op_sel_hi:[1,0]
	v_pk_add_f32 v[62:63], v[62:63], 1.0 op_sel_hi:[1,0]
	s_nop 0
	v_pk_mul_f32 v[122:123], v[58:59], v[62:63]
	s_nop 0
	v_rcp_f32_e32 v122, v122
	v_rcp_f32_e32 v123, v123
	s_nop 0
	v_pk_mul_f32 v[62:63], v[62:63], v[122:123]
	s_nop 0
	v_pk_mul_f32 v[62:63], v[36:37], v[62:63]
	v_pk_mul_f32 v[58:59], v[58:59], v[122:123]
	v_add_f32_e32 v0, v62, v62
	v_exp_f32_e32 v0, v0
	v_lshlrev_b32_e32 v122, 16, v145
	v_and_b32_e32 v123, 0xffff0000, v145
	v_cvt_pk_bf16_f32 v61, v62, v63
	v_sub_f32_e32 v0, 1.0, v0
	v_max_f32_e32 v0, 0, v0
	v_sqrt_f32_e32 v124, v0
	v_add_f32_e32 v0, v63, v63
	v_exp_f32_e32 v0, v0
	v_cvt_pk_bf16_f32 v62, v134, v135
	v_cvt_pk_bf16_f32 v63, v136, v137
	v_sub_f32_e32 v0, 1.0, v0
	v_max_f32_e32 v0, 0, v0
	v_sqrt_f32_e32 v125, v0
	s_nop 0
	v_pk_mul_f32 v[58:59], v[58:59], v[124:125]
	s_nop 0
	v_pk_mul_f32 v[122:123], v[58:59], v[122:123]
	v_cvt_pk_bf16_f32 v58, v130, v131
	v_cvt_pk_bf16_f32 v59, v132, v133
	v_cvt_pk_bf16_f32 v65, v122, v123
	v_lshl_add_u64 v[122:123], v[160:161], 0, v[168:169]
	global_store_dwordx4 v[122:123], v[58:61], off
	s_nop 1
	v_lshl_add_u64 v[58:59], v[162:163], 0, v[168:169]
	global_store_dwordx4 v[58:59], v[62:65], off
	v_or_b32_e32 v58, 48, v164
	v_ashrrev_i32_e32 v59, 31, v58
	v_lshlrev_b64 v[126:127], 11, v[58:59]
	v_lshl_add_u64 v[58:59], v[166:167], 0, v[126:127]
	v_add_f32_e32 v0, v114, v26
	global_load_dwordx4 v[122:125], v[58:59], off
	v_med3_f32 v0, v0, s84, v250
	v_add_f32_e32 v58, v118, v30
	v_med3_f32 v59, v58, s84, v250
	v_mul_f32_e32 v0, 0xbfb8aa3b, v0
	v_exp_f32_e32 v58, v0
	v_mul_f32_e32 v0, 0xbfb8aa3b, v59
	v_exp_f32_e32 v60, v0
	v_add_f32_e32 v0, v115, v27
	v_med3_f32 v0, v0, s84, v250
	v_add_f32_e32 v59, v119, v31
	v_med3_f32 v61, v59, s84, v250
	v_mul_f32_e32 v0, 0xbfb8aa3b, v0
	v_exp_f32_e32 v59, v0
	v_mul_f32_e32 v0, 0xbfb8aa3b, v61
	v_exp_f32_e32 v61, v0
	v_pk_add_f32 v[58:59], v[58:59], 1.0 op_sel_hi:[1,0]
	v_pk_add_f32 v[60:61], v[60:61], 1.0 op_sel_hi:[1,0]
	s_nop 0
	v_pk_mul_f32 v[62:63], v[58:59], v[60:61]
	s_nop 0
	v_rcp_f32_e32 v62, v62
	v_rcp_f32_e32 v63, v63
	s_nop 0
	v_pk_mul_f32 v[60:61], v[60:61], v[62:63]
	s_nop 0
	v_pk_mul_f32 v[114:115], v[46:47], v[60:61]
	v_pk_mul_f32 v[58:59], v[58:59], v[62:63]
	v_add_f32_e32 v0, v114, v114
	v_exp_f32_e32 v0, v0
	v_lshlrev_b32_e32 v62, 16, v138
	v_and_b32_e32 v63, 0xffff0000, v138
	v_sub_f32_e32 v0, 1.0, v0
	v_max_f32_e32 v0, 0, v0
	v_sqrt_f32_e32 v60, v0
	v_add_f32_e32 v0, v115, v115
	v_exp_f32_e32 v0, v0
	s_nop 0
	v_sub_f32_e32 v0, 1.0, v0
	v_max_f32_e32 v0, 0, v0
	v_sqrt_f32_e32 v61, v0
	v_add_f32_e32 v0, v116, v28
	v_med3_f32 v0, v0, s84, v250
	v_mul_f32_e32 v0, 0xbfb8aa3b, v0
	v_pk_mul_f32 v[58:59], v[58:59], v[60:61]
	s_nop 0
	v_pk_mul_f32 v[118:119], v[58:59], v[62:63]
	v_add_f32_e32 v58, v120, v32
	v_med3_f32 v59, v58, s84, v250
	v_exp_f32_e32 v58, v0
	v_mul_f32_e32 v0, 0xbfb8aa3b, v59
	v_exp_f32_e32 v60, v0
	v_add_f32_e32 v0, v117, v29
	v_med3_f32 v0, v0, s84, v250
	v_add_f32_e32 v59, v121, v33
	v_med3_f32 v61, v59, s84, v250
	v_mul_f32_e32 v0, 0xbfb8aa3b, v0
	v_exp_f32_e32 v59, v0
	v_mul_f32_e32 v0, 0xbfb8aa3b, v61
	v_exp_f32_e32 v61, v0
	v_pk_add_f32 v[58:59], v[58:59], 1.0 op_sel_hi:[1,0]
	v_pk_add_f32 v[60:61], v[60:61], 1.0 op_sel_hi:[1,0]
	s_nop 0
	v_pk_mul_f32 v[62:63], v[58:59], v[60:61]
	s_nop 0
	v_rcp_f32_e32 v62, v62
	v_rcp_f32_e32 v63, v63
	s_nop 0
	v_pk_mul_f32 v[60:61], v[60:61], v[62:63]
	s_nop 0
	v_pk_mul_f32 v[116:117], v[48:49], v[60:61]
	v_pk_mul_f32 v[58:59], v[58:59], v[62:63]
	v_add_f32_e32 v0, v116, v116
	v_exp_f32_e32 v0, v0
	v_lshlrev_b32_e32 v62, 16, v139
	v_and_b32_e32 v63, 0xffff0000, v139
	v_sub_f32_e32 v0, 1.0, v0
	v_max_f32_e32 v0, 0, v0
	v_sqrt_f32_e32 v60, v0
	v_add_f32_e32 v0, v117, v117
	v_exp_f32_e32 v0, v0
	s_nop 0
	v_sub_f32_e32 v0, 1.0, v0
	v_max_f32_e32 v0, 0, v0
	v_sqrt_f32_e32 v61, v0
	v_add_f32_e32 v0, v106, v10
	v_med3_f32 v0, v0, s84, v250
	v_mul_f32_e32 v0, 0xbfb8aa3b, v0
	v_pk_mul_f32 v[58:59], v[58:59], v[60:61]
	s_nop 0
	v_pk_mul_f32 v[120:121], v[58:59], v[62:63]
	v_add_f32_e32 v58, v110, v14
	v_med3_f32 v59, v58, s84, v250
	v_exp_f32_e32 v58, v0
	v_mul_f32_e32 v0, 0xbfb8aa3b, v59
	v_exp_f32_e32 v60, v0
	v_add_f32_e32 v0, v107, v11
	v_med3_f32 v0, v0, s84, v250
	v_add_f32_e32 v59, v111, v15
	v_med3_f32 v61, v59, s84, v250
	v_mul_f32_e32 v0, 0xbfb8aa3b, v0
	v_exp_f32_e32 v59, v0
	v_mul_f32_e32 v0, 0xbfb8aa3b, v61
	v_exp_f32_e32 v61, v0
	v_pk_add_f32 v[58:59], v[58:59], 1.0 op_sel_hi:[1,0]
	v_pk_add_f32 v[60:61], v[60:61], 1.0 op_sel_hi:[1,0]
	s_nop 0
	v_pk_mul_f32 v[62:63], v[58:59], v[60:61]
	s_nop 0
	v_rcp_f32_e32 v62, v62
	v_rcp_f32_e32 v63, v63
	s_nop 0
	v_pk_mul_f32 v[60:61], v[60:61], v[62:63]
	s_nop 0
	v_pk_mul_f32 v[60:61], v[34:35], v[60:61]
	v_pk_mul_f32 v[58:59], v[58:59], v[62:63]
	v_add_f32_e32 v0, v60, v60
	v_exp_f32_e32 v0, v0
	v_lshlrev_b32_e32 v62, 16, v140
	v_and_b32_e32 v63, 0xffff0000, v140
	v_cvt_pk_bf16_f32 v60, v60, v61
	v_sub_f32_e32 v0, 1.0, v0
	v_max_f32_e32 v0, 0, v0
	v_sqrt_f32_e32 v64, v0
	v_add_f32_e32 v0, v61, v61
	v_exp_f32_e32 v0, v0
	s_nop 0
	v_sub_f32_e32 v0, 1.0, v0
	v_max_f32_e32 v0, 0, v0
	v_sqrt_f32_e32 v65, v0
	v_add_f32_e32 v0, v108, v12
	v_med3_f32 v0, v0, s84, v250
	v_mul_f32_e32 v0, 0xbfb8aa3b, v0
	v_pk_mul_f32 v[58:59], v[58:59], v[64:65]
	s_nop 0
	v_pk_mul_f32 v[64:65], v[58:59], v[62:63]
	v_add_f32_e32 v58, v112, v16
	v_med3_f32 v59, v58, s84, v250
	v_exp_f32_e32 v58, v0
	v_mul_f32_e32 v0, 0xbfb8aa3b, v59
	v_exp_f32_e32 v62, v0
	v_add_f32_e32 v0, v109, v13
	v_med3_f32 v0, v0, s84, v250
	v_add_f32_e32 v59, v113, v17
	v_med3_f32 v63, v59, s84, v250
	v_mul_f32_e32 v0, 0xbfb8aa3b, v0
	v_exp_f32_e32 v59, v0
	v_mul_f32_e32 v0, 0xbfb8aa3b, v63
	v_exp_f32_e32 v63, v0
	v_cvt_pk_bf16_f32 v64, v64, v65
	v_pk_add_f32 v[58:59], v[58:59], 1.0 op_sel_hi:[1,0]
	v_pk_add_f32 v[62:63], v[62:63], 1.0 op_sel_hi:[1,0]
	s_nop 0
	v_pk_mul_f32 v[106:107], v[58:59], v[62:63]
	s_nop 0
	v_rcp_f32_e32 v106, v106
	v_rcp_f32_e32 v107, v107
	s_nop 0
	v_pk_mul_f32 v[62:63], v[62:63], v[106:107]
	s_nop 0
	v_pk_mul_f32 v[62:63], v[36:37], v[62:63]
	v_pk_mul_f32 v[58:59], v[58:59], v[106:107]
	v_add_f32_e32 v0, v62, v62
	v_exp_f32_e32 v0, v0
	v_lshlrev_b32_e32 v106, 16, v141
	v_and_b32_e32 v107, 0xffff0000, v141
	v_cvt_pk_bf16_f32 v61, v62, v63
	v_sub_f32_e32 v0, 1.0, v0
	v_max_f32_e32 v0, 0, v0
	v_sqrt_f32_e32 v108, v0
	v_add_f32_e32 v0, v63, v63
	v_exp_f32_e32 v0, v0
	v_cvt_pk_bf16_f32 v62, v118, v119
	v_cvt_pk_bf16_f32 v63, v120, v121
	v_sub_f32_e32 v0, 1.0, v0
	v_max_f32_e32 v0, 0, v0
	v_sqrt_f32_e32 v109, v0
	s_nop 0
	v_pk_mul_f32 v[58:59], v[58:59], v[108:109]
	s_nop 0
	v_pk_mul_f32 v[106:107], v[58:59], v[106:107]
	v_cvt_pk_bf16_f32 v58, v114, v115
	v_cvt_pk_bf16_f32 v59, v116, v117
	v_cvt_pk_bf16_f32 v65, v106, v107
	v_lshl_add_u64 v[106:107], v[160:161], 0, v[146:147]
	global_store_dwordx4 v[106:107], v[58:61], off
	s_nop 1
	v_lshl_add_u64 v[58:59], v[162:163], 0, v[146:147]
	global_store_dwordx4 v[58:59], v[62:65], off
	s_mov_b64 s[14:15], 0x40000
	v_lshl_add_u64 v[110:111], v[158:159], 0, s[14:15]
	v_lshl_add_u64 v[58:59], v[166:167], 0, v[110:111]
	v_add_f32_e32 v0, v98, v26
	global_load_dwordx4 v[106:109], v[58:59], off
	v_med3_f32 v0, v0, s84, v250
	v_add_f32_e32 v58, v102, v30
	v_med3_f32 v59, v58, s84, v250
	v_mul_f32_e32 v0, 0xbfb8aa3b, v0
	v_exp_f32_e32 v58, v0
	v_mul_f32_e32 v0, 0xbfb8aa3b, v59
	v_exp_f32_e32 v60, v0
	v_add_f32_e32 v0, v99, v27
	v_med3_f32 v0, v0, s84, v250
	v_add_f32_e32 v59, v103, v31
	v_med3_f32 v61, v59, s84, v250
	v_mul_f32_e32 v0, 0xbfb8aa3b, v0
	v_exp_f32_e32 v59, v0
	v_mul_f32_e32 v0, 0xbfb8aa3b, v61
	v_exp_f32_e32 v61, v0
	v_pk_add_f32 v[58:59], v[58:59], 1.0 op_sel_hi:[1,0]
	v_pk_add_f32 v[60:61], v[60:61], 1.0 op_sel_hi:[1,0]
	s_nop 0
	v_pk_mul_f32 v[62:63], v[58:59], v[60:61]
	s_nop 0
	v_rcp_f32_e32 v62, v62
	v_rcp_f32_e32 v63, v63
	s_nop 0
	v_pk_mul_f32 v[60:61], v[60:61], v[62:63]
	s_nop 0
	v_pk_mul_f32 v[98:99], v[46:47], v[60:61]
	v_pk_mul_f32 v[58:59], v[58:59], v[62:63]
	v_add_f32_e32 v0, v98, v98
	v_exp_f32_e32 v0, v0
	s_waitcnt vmcnt(0)
	v_lshlrev_b32_e32 v62, 16, v122
	v_and_b32_e32 v63, 0xffff0000, v122
	v_sub_f32_e32 v0, 1.0, v0
	v_max_f32_e32 v0, 0, v0
	v_sqrt_f32_e32 v60, v0
	v_add_f32_e32 v0, v99, v99
	v_exp_f32_e32 v0, v0
	s_nop 0
	v_sub_f32_e32 v0, 1.0, v0
	v_max_f32_e32 v0, 0, v0
	v_sqrt_f32_e32 v61, v0
	v_add_f32_e32 v0, v100, v28
	v_med3_f32 v0, v0, s84, v250
	v_mul_f32_e32 v0, 0xbfb8aa3b, v0
	v_pk_mul_f32 v[58:59], v[58:59], v[60:61]
	s_nop 0
	v_pk_mul_f32 v[102:103], v[58:59], v[62:63]
	v_add_f32_e32 v58, v104, v32
	v_med3_f32 v59, v58, s84, v250
	v_exp_f32_e32 v58, v0
	v_mul_f32_e32 v0, 0xbfb8aa3b, v59
	v_exp_f32_e32 v60, v0
	v_add_f32_e32 v0, v101, v29
	v_med3_f32 v0, v0, s84, v250
	v_add_f32_e32 v59, v105, v33
	v_med3_f32 v61, v59, s84, v250
	v_mul_f32_e32 v0, 0xbfb8aa3b, v0
	v_exp_f32_e32 v59, v0
	v_mul_f32_e32 v0, 0xbfb8aa3b, v61
	v_exp_f32_e32 v61, v0
	v_pk_add_f32 v[58:59], v[58:59], 1.0 op_sel_hi:[1,0]
	v_pk_add_f32 v[60:61], v[60:61], 1.0 op_sel_hi:[1,0]
	s_nop 0
	v_pk_mul_f32 v[62:63], v[58:59], v[60:61]
	s_nop 0
	v_rcp_f32_e32 v62, v62
	v_rcp_f32_e32 v63, v63
	s_nop 0
	v_pk_mul_f32 v[60:61], v[60:61], v[62:63]
	s_nop 0
	v_pk_mul_f32 v[100:101], v[48:49], v[60:61]
	v_pk_mul_f32 v[58:59], v[58:59], v[62:63]
	v_add_f32_e32 v0, v100, v100
	v_exp_f32_e32 v0, v0
	v_lshlrev_b32_e32 v62, 16, v123
	v_and_b32_e32 v63, 0xffff0000, v123
	v_sub_f32_e32 v0, 1.0, v0
	v_max_f32_e32 v0, 0, v0
	v_sqrt_f32_e32 v60, v0
	v_add_f32_e32 v0, v101, v101
	v_exp_f32_e32 v0, v0
	s_nop 0
	v_sub_f32_e32 v0, 1.0, v0
	v_max_f32_e32 v0, 0, v0
	v_sqrt_f32_e32 v61, v0
	v_add_f32_e32 v0, v90, v10
	v_med3_f32 v0, v0, s84, v250
	v_mul_f32_e32 v0, 0xbfb8aa3b, v0
	v_pk_mul_f32 v[58:59], v[58:59], v[60:61]
	s_nop 0
	v_pk_mul_f32 v[104:105], v[58:59], v[62:63]
	v_add_f32_e32 v58, v94, v14
	v_med3_f32 v59, v58, s84, v250
	v_exp_f32_e32 v58, v0
	v_mul_f32_e32 v0, 0xbfb8aa3b, v59
	v_exp_f32_e32 v60, v0
	v_add_f32_e32 v0, v91, v11
	v_med3_f32 v0, v0, s84, v250
	v_add_f32_e32 v59, v95, v15
	v_med3_f32 v61, v59, s84, v250
	v_mul_f32_e32 v0, 0xbfb8aa3b, v0
	v_exp_f32_e32 v59, v0
	v_mul_f32_e32 v0, 0xbfb8aa3b, v61
	v_exp_f32_e32 v61, v0
	v_pk_add_f32 v[58:59], v[58:59], 1.0 op_sel_hi:[1,0]
	v_pk_add_f32 v[60:61], v[60:61], 1.0 op_sel_hi:[1,0]
	s_nop 0
	v_pk_mul_f32 v[62:63], v[58:59], v[60:61]
	s_nop 0
	v_rcp_f32_e32 v62, v62
	v_rcp_f32_e32 v63, v63
	s_nop 0
	v_pk_mul_f32 v[60:61], v[60:61], v[62:63]
	s_nop 0
	v_pk_mul_f32 v[60:61], v[34:35], v[60:61]
	v_pk_mul_f32 v[58:59], v[58:59], v[62:63]
	v_add_f32_e32 v0, v60, v60
	v_exp_f32_e32 v0, v0
	v_lshlrev_b32_e32 v62, 16, v124
	v_and_b32_e32 v63, 0xffff0000, v124
	v_cvt_pk_bf16_f32 v60, v60, v61
	v_sub_f32_e32 v0, 1.0, v0
	v_max_f32_e32 v0, 0, v0
	v_sqrt_f32_e32 v64, v0
	v_add_f32_e32 v0, v61, v61
	v_exp_f32_e32 v0, v0
	s_nop 0
	v_sub_f32_e32 v0, 1.0, v0
	v_max_f32_e32 v0, 0, v0
	v_sqrt_f32_e32 v65, v0
	v_add_f32_e32 v0, v92, v12
	v_med3_f32 v0, v0, s84, v250
	v_mul_f32_e32 v0, 0xbfb8aa3b, v0
	v_pk_mul_f32 v[58:59], v[58:59], v[64:65]
	s_nop 0
	v_pk_mul_f32 v[64:65], v[58:59], v[62:63]
	v_add_f32_e32 v58, v96, v16
	v_med3_f32 v59, v58, s84, v250
	v_exp_f32_e32 v58, v0
	v_mul_f32_e32 v0, 0xbfb8aa3b, v59
	v_exp_f32_e32 v62, v0
	v_add_f32_e32 v0, v93, v13
	v_med3_f32 v0, v0, s84, v250
	v_add_f32_e32 v59, v97, v17
	v_med3_f32 v63, v59, s84, v250
	v_mul_f32_e32 v0, 0xbfb8aa3b, v0
	v_exp_f32_e32 v59, v0
	v_mul_f32_e32 v0, 0xbfb8aa3b, v63
	v_exp_f32_e32 v63, v0
	v_cvt_pk_bf16_f32 v64, v64, v65
	v_pk_add_f32 v[58:59], v[58:59], 1.0 op_sel_hi:[1,0]
	v_pk_add_f32 v[62:63], v[62:63], 1.0 op_sel_hi:[1,0]
	s_nop 0
	v_pk_mul_f32 v[90:91], v[58:59], v[62:63]
	s_nop 0
	v_rcp_f32_e32 v90, v90
	v_rcp_f32_e32 v91, v91
	s_nop 0
	v_pk_mul_f32 v[62:63], v[62:63], v[90:91]
	s_nop 0
	v_pk_mul_f32 v[62:63], v[36:37], v[62:63]
	v_pk_mul_f32 v[58:59], v[58:59], v[90:91]
	v_add_f32_e32 v0, v62, v62
	v_exp_f32_e32 v0, v0
	v_lshlrev_b32_e32 v90, 16, v125
	v_and_b32_e32 v91, 0xffff0000, v125
	v_cvt_pk_bf16_f32 v61, v62, v63
	v_sub_f32_e32 v0, 1.0, v0
	v_max_f32_e32 v0, 0, v0
	v_sqrt_f32_e32 v92, v0
	v_add_f32_e32 v0, v63, v63
	v_exp_f32_e32 v0, v0
	v_cvt_pk_bf16_f32 v62, v102, v103
	v_cvt_pk_bf16_f32 v63, v104, v105
	v_sub_f32_e32 v0, 1.0, v0
	v_max_f32_e32 v0, 0, v0
	v_sqrt_f32_e32 v93, v0
	s_nop 0
	v_pk_mul_f32 v[58:59], v[58:59], v[92:93]
	s_nop 0
	v_pk_mul_f32 v[90:91], v[58:59], v[90:91]
	v_cvt_pk_bf16_f32 v58, v98, v99
	v_cvt_pk_bf16_f32 v59, v100, v101
	v_cvt_pk_bf16_f32 v65, v90, v91
	v_lshl_add_u64 v[90:91], v[160:161], 0, v[126:127]
	global_store_dwordx4 v[90:91], v[58:61], off
	s_nop 1
	v_lshl_add_u64 v[58:59], v[162:163], 0, v[126:127]
	global_store_dwordx4 v[58:59], v[62:65], off
	v_add_u32_e32 v58, 0x90, v164
	v_ashrrev_i32_e32 v59, 31, v58
	v_lshlrev_b64 v[58:59], 11, v[58:59]
	v_lshl_add_u64 v[58:59], v[166:167], 0, v[58:59]
	v_add_f32_e32 v0, v82, v26
	global_load_dwordx4 v[90:93], v[58:59], off
	v_med3_f32 v0, v0, s84, v250
	v_add_f32_e32 v58, v86, v30
	v_med3_f32 v59, v58, s84, v250
	v_mul_f32_e32 v0, 0xbfb8aa3b, v0
	v_exp_f32_e32 v58, v0
	v_mul_f32_e32 v0, 0xbfb8aa3b, v59
	v_exp_f32_e32 v60, v0
	v_add_f32_e32 v0, v83, v27
	v_med3_f32 v0, v0, s84, v250
	v_add_f32_e32 v59, v87, v31
	v_med3_f32 v61, v59, s84, v250
	v_mul_f32_e32 v0, 0xbfb8aa3b, v0
	v_exp_f32_e32 v59, v0
	v_mul_f32_e32 v0, 0xbfb8aa3b, v61
	v_exp_f32_e32 v61, v0
	v_pk_add_f32 v[58:59], v[58:59], 1.0 op_sel_hi:[1,0]
	v_pk_add_f32 v[60:61], v[60:61], 1.0 op_sel_hi:[1,0]
	s_nop 0
	v_pk_mul_f32 v[62:63], v[58:59], v[60:61]
	s_nop 0
	v_rcp_f32_e32 v62, v62
	v_rcp_f32_e32 v63, v63
	s_nop 0
	v_pk_mul_f32 v[60:61], v[60:61], v[62:63]
	s_nop 0
	v_pk_mul_f32 v[82:83], v[46:47], v[60:61]
	v_pk_mul_f32 v[58:59], v[58:59], v[62:63]
	v_add_f32_e32 v0, v82, v82
	v_exp_f32_e32 v0, v0
	v_lshlrev_b32_e32 v62, 16, v106
	v_and_b32_e32 v63, 0xffff0000, v106
	v_sub_f32_e32 v0, 1.0, v0
	v_max_f32_e32 v0, 0, v0
	v_sqrt_f32_e32 v60, v0
	v_add_f32_e32 v0, v83, v83
	v_exp_f32_e32 v0, v0
	s_nop 0
	v_sub_f32_e32 v0, 1.0, v0
	v_max_f32_e32 v0, 0, v0
	v_sqrt_f32_e32 v61, v0
	v_add_f32_e32 v0, v84, v28
	v_med3_f32 v0, v0, s84, v250
	v_mul_f32_e32 v0, 0xbfb8aa3b, v0
	v_pk_mul_f32 v[58:59], v[58:59], v[60:61]
	s_nop 0
	v_pk_mul_f32 v[86:87], v[58:59], v[62:63]
	v_add_f32_e32 v58, v88, v32
	v_med3_f32 v59, v58, s84, v250
	v_exp_f32_e32 v58, v0
	v_mul_f32_e32 v0, 0xbfb8aa3b, v59
	v_exp_f32_e32 v60, v0
	v_add_f32_e32 v0, v85, v29
	v_med3_f32 v0, v0, s84, v250
	v_add_f32_e32 v59, v89, v33
	v_med3_f32 v61, v59, s84, v250
	v_mul_f32_e32 v0, 0xbfb8aa3b, v0
	v_exp_f32_e32 v59, v0
	v_mul_f32_e32 v0, 0xbfb8aa3b, v61
	v_exp_f32_e32 v61, v0
	v_pk_add_f32 v[58:59], v[58:59], 1.0 op_sel_hi:[1,0]
	v_pk_add_f32 v[60:61], v[60:61], 1.0 op_sel_hi:[1,0]
	s_nop 0
	v_pk_mul_f32 v[62:63], v[58:59], v[60:61]
	s_nop 0
	v_rcp_f32_e32 v62, v62
	v_rcp_f32_e32 v63, v63
	s_nop 0
	v_pk_mul_f32 v[60:61], v[60:61], v[62:63]
	s_nop 0
	v_pk_mul_f32 v[84:85], v[48:49], v[60:61]
	v_pk_mul_f32 v[58:59], v[58:59], v[62:63]
	v_add_f32_e32 v0, v84, v84
	v_exp_f32_e32 v0, v0
	v_lshlrev_b32_e32 v62, 16, v107
	v_and_b32_e32 v63, 0xffff0000, v107
	v_sub_f32_e32 v0, 1.0, v0
	v_max_f32_e32 v0, 0, v0
	v_sqrt_f32_e32 v60, v0
	v_add_f32_e32 v0, v85, v85
	v_exp_f32_e32 v0, v0
	s_nop 0
	v_sub_f32_e32 v0, 1.0, v0
	v_max_f32_e32 v0, 0, v0
	v_sqrt_f32_e32 v61, v0
	v_add_f32_e32 v0, v74, v10
	v_med3_f32 v0, v0, s84, v250
	v_mul_f32_e32 v0, 0xbfb8aa3b, v0
	v_pk_mul_f32 v[58:59], v[58:59], v[60:61]
	s_nop 0
	v_pk_mul_f32 v[88:89], v[58:59], v[62:63]
	v_add_f32_e32 v58, v78, v14
	v_med3_f32 v59, v58, s84, v250
	v_exp_f32_e32 v58, v0
	v_mul_f32_e32 v0, 0xbfb8aa3b, v59
	v_exp_f32_e32 v60, v0
	v_add_f32_e32 v0, v75, v11
	v_med3_f32 v0, v0, s84, v250
	v_add_f32_e32 v59, v79, v15
	v_med3_f32 v61, v59, s84, v250
	v_mul_f32_e32 v0, 0xbfb8aa3b, v0
	v_exp_f32_e32 v59, v0
	v_mul_f32_e32 v0, 0xbfb8aa3b, v61
	v_exp_f32_e32 v61, v0
	v_pk_add_f32 v[58:59], v[58:59], 1.0 op_sel_hi:[1,0]
	v_pk_add_f32 v[60:61], v[60:61], 1.0 op_sel_hi:[1,0]
	s_nop 0
	v_pk_mul_f32 v[62:63], v[58:59], v[60:61]
	s_nop 0
	v_rcp_f32_e32 v62, v62
	v_rcp_f32_e32 v63, v63
	s_nop 0
	v_pk_mul_f32 v[60:61], v[60:61], v[62:63]
	s_nop 0
	v_pk_mul_f32 v[60:61], v[34:35], v[60:61]
	v_pk_mul_f32 v[58:59], v[58:59], v[62:63]
	v_add_f32_e32 v0, v60, v60
	v_exp_f32_e32 v0, v0
	v_lshlrev_b32_e32 v62, 16, v108
	v_and_b32_e32 v63, 0xffff0000, v108
	v_cvt_pk_bf16_f32 v60, v60, v61
	v_sub_f32_e32 v0, 1.0, v0
	v_max_f32_e32 v0, 0, v0
	v_sqrt_f32_e32 v64, v0
	v_add_f32_e32 v0, v61, v61
	v_exp_f32_e32 v0, v0
	s_nop 0
	v_sub_f32_e32 v0, 1.0, v0
	v_max_f32_e32 v0, 0, v0
	v_sqrt_f32_e32 v65, v0
	v_add_f32_e32 v0, v76, v12
	v_med3_f32 v0, v0, s84, v250
	v_mul_f32_e32 v0, 0xbfb8aa3b, v0
	v_pk_mul_f32 v[58:59], v[58:59], v[64:65]
	s_nop 0
	v_pk_mul_f32 v[64:65], v[58:59], v[62:63]
	v_add_f32_e32 v58, v80, v16
	v_med3_f32 v59, v58, s84, v250
	v_exp_f32_e32 v58, v0
	v_mul_f32_e32 v0, 0xbfb8aa3b, v59
	v_exp_f32_e32 v62, v0
	v_add_f32_e32 v0, v77, v13
	v_med3_f32 v0, v0, s84, v250
	v_add_f32_e32 v59, v81, v17
	v_med3_f32 v63, v59, s84, v250
	v_mul_f32_e32 v0, 0xbfb8aa3b, v0
	v_exp_f32_e32 v59, v0
	v_mul_f32_e32 v0, 0xbfb8aa3b, v63
	v_exp_f32_e32 v63, v0
	v_cvt_pk_bf16_f32 v64, v64, v65
	v_pk_add_f32 v[58:59], v[58:59], 1.0 op_sel_hi:[1,0]
	v_pk_add_f32 v[62:63], v[62:63], 1.0 op_sel_hi:[1,0]
	s_nop 0
	v_pk_mul_f32 v[74:75], v[58:59], v[62:63]
	s_nop 0
	v_rcp_f32_e32 v74, v74
	v_rcp_f32_e32 v75, v75
	s_nop 0
	v_pk_mul_f32 v[62:63], v[62:63], v[74:75]
	s_nop 0
	v_pk_mul_f32 v[62:63], v[36:37], v[62:63]
	v_pk_mul_f32 v[58:59], v[58:59], v[74:75]
	v_add_f32_e32 v0, v62, v62
	v_exp_f32_e32 v0, v0
	v_lshlrev_b32_e32 v74, 16, v109
	v_and_b32_e32 v75, 0xffff0000, v109
	v_cvt_pk_bf16_f32 v61, v62, v63
	v_sub_f32_e32 v0, 1.0, v0
	v_max_f32_e32 v0, 0, v0
	v_sqrt_f32_e32 v76, v0
	v_add_f32_e32 v0, v63, v63
	v_exp_f32_e32 v0, v0
	v_cvt_pk_bf16_f32 v62, v86, v87
	v_cvt_pk_bf16_f32 v63, v88, v89
	v_sub_f32_e32 v0, 1.0, v0
	v_max_f32_e32 v0, 0, v0
	v_sqrt_f32_e32 v77, v0
	s_nop 0
	v_pk_mul_f32 v[58:59], v[58:59], v[76:77]
	s_nop 0
	v_pk_mul_f32 v[74:75], v[58:59], v[74:75]
	v_cvt_pk_bf16_f32 v58, v82, v83
	v_cvt_pk_bf16_f32 v59, v84, v85
	v_cvt_pk_bf16_f32 v65, v74, v75
	v_lshl_add_u64 v[74:75], v[160:161], 0, v[110:111]
	global_store_dwordx4 v[74:75], v[58:61], off
	s_nop 1
	v_lshl_add_u64 v[58:59], v[162:163], 0, v[110:111]
	global_store_dwordx4 v[58:59], v[62:65], off
	v_add_u32_e32 v58, 0xa0, v164
	v_ashrrev_i32_e32 v59, 31, v58
	v_lshlrev_b64 v[58:59], 11, v[58:59]
	v_lshl_add_u64 v[58:59], v[166:167], 0, v[58:59]
	v_add_f32_e32 v0, v66, v26
	global_load_dwordx4 v[74:77], v[58:59], off
	v_med3_f32 v0, v0, s84, v250
	v_add_f32_e32 v58, v70, v30
	v_med3_f32 v59, v58, s84, v250
	v_mul_f32_e32 v0, 0xbfb8aa3b, v0
	v_exp_f32_e32 v58, v0
	v_mul_f32_e32 v0, 0xbfb8aa3b, v59
	v_exp_f32_e32 v60, v0
	v_add_f32_e32 v0, v67, v27
	v_med3_f32 v0, v0, s84, v250
	v_add_f32_e32 v59, v71, v31
	v_med3_f32 v61, v59, s84, v250
	v_mul_f32_e32 v0, 0xbfb8aa3b, v0
	v_exp_f32_e32 v59, v0
	v_mul_f32_e32 v0, 0xbfb8aa3b, v61
	v_exp_f32_e32 v61, v0
	s_mov_b64 s[14:15], 0x48000
	v_pk_add_f32 v[58:59], v[58:59], 1.0 op_sel_hi:[1,0]
	v_pk_add_f32 v[60:61], v[60:61], 1.0 op_sel_hi:[1,0]
	s_nop 0
	v_pk_mul_f32 v[62:63], v[58:59], v[60:61]
	s_nop 0
	v_rcp_f32_e32 v62, v62
	v_rcp_f32_e32 v63, v63
	s_nop 0
	v_pk_mul_f32 v[60:61], v[60:61], v[62:63]
	s_nop 0
	v_pk_mul_f32 v[66:67], v[46:47], v[60:61]
	v_pk_mul_f32 v[58:59], v[58:59], v[62:63]
	v_add_f32_e32 v0, v66, v66
	v_exp_f32_e32 v0, v0
	s_waitcnt vmcnt(0)
	v_lshlrev_b32_e32 v62, 16, v90
	v_and_b32_e32 v63, 0xffff0000, v90
	v_sub_f32_e32 v0, 1.0, v0
	v_max_f32_e32 v0, 0, v0
	v_sqrt_f32_e32 v60, v0
	v_add_f32_e32 v0, v67, v67
	v_exp_f32_e32 v0, v0
	s_nop 0
	v_sub_f32_e32 v0, 1.0, v0
	v_max_f32_e32 v0, 0, v0
	v_sqrt_f32_e32 v61, v0
	v_add_f32_e32 v0, v68, v28
	v_med3_f32 v0, v0, s84, v250
	v_mul_f32_e32 v0, 0xbfb8aa3b, v0
	v_pk_mul_f32 v[58:59], v[58:59], v[60:61]
	s_nop 0
	v_pk_mul_f32 v[70:71], v[58:59], v[62:63]
	v_add_f32_e32 v58, v72, v32
	v_med3_f32 v59, v58, s84, v250
	v_exp_f32_e32 v58, v0
	v_mul_f32_e32 v0, 0xbfb8aa3b, v59
	v_exp_f32_e32 v60, v0
	v_add_f32_e32 v0, v69, v29
	v_med3_f32 v0, v0, s84, v250
	v_add_f32_e32 v59, v73, v33
	v_med3_f32 v61, v59, s84, v250
	v_mul_f32_e32 v0, 0xbfb8aa3b, v0
	v_exp_f32_e32 v59, v0
	v_mul_f32_e32 v0, 0xbfb8aa3b, v61
	v_exp_f32_e32 v61, v0
	v_pk_add_f32 v[58:59], v[58:59], 1.0 op_sel_hi:[1,0]
	v_pk_add_f32 v[60:61], v[60:61], 1.0 op_sel_hi:[1,0]
	s_nop 0
	v_pk_mul_f32 v[62:63], v[58:59], v[60:61]
	s_nop 0
	v_rcp_f32_e32 v62, v62
	v_rcp_f32_e32 v63, v63
	s_nop 0
	v_pk_mul_f32 v[60:61], v[60:61], v[62:63]
	s_nop 0
	v_pk_mul_f32 v[68:69], v[48:49], v[60:61]
	v_pk_mul_f32 v[58:59], v[58:59], v[62:63]
	v_add_f32_e32 v0, v68, v68
	v_exp_f32_e32 v0, v0
	v_lshlrev_b32_e32 v62, 16, v91
	v_and_b32_e32 v63, 0xffff0000, v91
	v_sub_f32_e32 v0, 1.0, v0
	v_max_f32_e32 v0, 0, v0
	v_sqrt_f32_e32 v60, v0
	v_add_f32_e32 v0, v69, v69
	v_exp_f32_e32 v0, v0
	s_nop 0
	v_sub_f32_e32 v0, 1.0, v0
	v_max_f32_e32 v0, 0, v0
	v_sqrt_f32_e32 v61, v0
	v_add_f32_e32 v0, v182, v10
	v_med3_f32 v0, v0, s84, v250
	v_mul_f32_e32 v0, 0xbfb8aa3b, v0
	v_pk_mul_f32 v[58:59], v[58:59], v[60:61]
	s_nop 0
	v_pk_mul_f32 v[72:73], v[58:59], v[62:63]
	v_add_f32_e32 v58, v178, v14
	v_med3_f32 v59, v58, s84, v250
	v_exp_f32_e32 v58, v0
	v_mul_f32_e32 v0, 0xbfb8aa3b, v59
	v_exp_f32_e32 v60, v0
	v_add_f32_e32 v0, v183, v11
	v_med3_f32 v0, v0, s84, v250
	v_add_f32_e32 v59, v179, v15
	v_med3_f32 v61, v59, s84, v250
	v_mul_f32_e32 v0, 0xbfb8aa3b, v0
	v_exp_f32_e32 v59, v0
	v_mul_f32_e32 v0, 0xbfb8aa3b, v61
	v_exp_f32_e32 v61, v0
	v_pk_add_f32 v[58:59], v[58:59], 1.0 op_sel_hi:[1,0]
	v_pk_add_f32 v[60:61], v[60:61], 1.0 op_sel_hi:[1,0]
	s_nop 0
	v_pk_mul_f32 v[62:63], v[58:59], v[60:61]
	s_nop 0
	v_rcp_f32_e32 v62, v62
	v_rcp_f32_e32 v63, v63
	s_nop 0
	v_pk_mul_f32 v[60:61], v[60:61], v[62:63]
	s_nop 0
	v_pk_mul_f32 v[60:61], v[34:35], v[60:61]
	v_pk_mul_f32 v[58:59], v[58:59], v[62:63]
	v_add_f32_e32 v0, v60, v60
	v_exp_f32_e32 v0, v0
	v_lshlrev_b32_e32 v62, 16, v92
	v_and_b32_e32 v63, 0xffff0000, v92
	v_cvt_pk_bf16_f32 v60, v60, v61
	v_sub_f32_e32 v0, 1.0, v0
	v_max_f32_e32 v0, 0, v0
	v_sqrt_f32_e32 v64, v0
	v_add_f32_e32 v0, v61, v61
	v_exp_f32_e32 v0, v0
	s_nop 0
	v_sub_f32_e32 v0, 1.0, v0
	v_max_f32_e32 v0, 0, v0
	v_sqrt_f32_e32 v65, v0
	v_add_f32_e32 v0, v184, v12
	v_med3_f32 v0, v0, s84, v250
	v_mul_f32_e32 v0, 0xbfb8aa3b, v0
	v_pk_mul_f32 v[58:59], v[58:59], v[64:65]
	s_nop 0
	v_pk_mul_f32 v[64:65], v[58:59], v[62:63]
	v_add_f32_e32 v58, v180, v16
	v_med3_f32 v59, v58, s84, v250
	v_exp_f32_e32 v58, v0
	v_mul_f32_e32 v0, 0xbfb8aa3b, v59
	v_exp_f32_e32 v62, v0
	v_add_f32_e32 v0, v185, v13
	v_med3_f32 v0, v0, s84, v250
	v_add_f32_e32 v59, v181, v17
	v_med3_f32 v63, v59, s84, v250
	v_mul_f32_e32 v0, 0xbfb8aa3b, v0
	v_exp_f32_e32 v59, v0
	v_mul_f32_e32 v0, 0xbfb8aa3b, v63
	v_exp_f32_e32 v63, v0
	v_cvt_pk_bf16_f32 v64, v64, v65
	v_pk_add_f32 v[58:59], v[58:59], 1.0 op_sel_hi:[1,0]
	v_pk_add_f32 v[62:63], v[62:63], 1.0 op_sel_hi:[1,0]
	s_nop 0
	v_pk_mul_f32 v[78:79], v[58:59], v[62:63]
	s_nop 0
	v_rcp_f32_e32 v78, v78
	v_rcp_f32_e32 v79, v79
	s_nop 0
	v_pk_mul_f32 v[62:63], v[62:63], v[78:79]
	s_nop 0
	v_pk_mul_f32 v[62:63], v[36:37], v[62:63]
	v_pk_mul_f32 v[58:59], v[58:59], v[78:79]
	v_add_f32_e32 v0, v62, v62
	v_exp_f32_e32 v0, v0
	v_lshlrev_b32_e32 v78, 16, v93
	v_and_b32_e32 v79, 0xffff0000, v93
	v_cvt_pk_bf16_f32 v61, v62, v63
	v_sub_f32_e32 v0, 1.0, v0
	v_max_f32_e32 v0, 0, v0
	v_sqrt_f32_e32 v80, v0
	v_add_f32_e32 v0, v63, v63
	v_exp_f32_e32 v0, v0
	v_cvt_pk_bf16_f32 v62, v70, v71
	v_cvt_pk_bf16_f32 v63, v72, v73
	v_sub_f32_e32 v0, 1.0, v0
	v_max_f32_e32 v0, 0, v0
	v_sqrt_f32_e32 v81, v0
	s_nop 0
	v_pk_mul_f32 v[58:59], v[58:59], v[80:81]
	s_nop 0
	v_pk_mul_f32 v[78:79], v[58:59], v[78:79]
	v_cvt_pk_bf16_f32 v58, v66, v67
	v_lshl_add_u64 v[66:67], v[158:159], 0, s[14:15]
	v_cvt_pk_bf16_f32 v59, v68, v69
	v_lshl_add_u64 v[68:69], v[160:161], 0, v[66:67]
	v_cvt_pk_bf16_f32 v65, v78, v79
	global_store_dwordx4 v[68:69], v[58:61], off
	s_nop 1
	v_lshl_add_u64 v[58:59], v[162:163], 0, v[66:67]
	global_store_dwordx4 v[58:59], v[62:65], off
	v_add_f32_e32 v0, v50, v26
	v_med3_f32 v0, v0, s84, v250
	v_add_f32_e32 v50, v54, v30
	v_med3_f32 v54, v50, s84, v250
	v_mul_f32_e32 v0, 0xbfb8aa3b, v0
	v_exp_f32_e32 v50, v0
	v_mul_f32_e32 v0, 0xbfb8aa3b, v54
	v_exp_f32_e32 v54, v0
	v_add_f32_e32 v0, v51, v27
	v_med3_f32 v0, v0, s84, v250
	v_add_f32_e32 v51, v55, v31
	v_med3_f32 v55, v51, s84, v250
	v_mul_f32_e32 v0, 0xbfb8aa3b, v0
	v_exp_f32_e32 v51, v0
	v_mul_f32_e32 v0, 0xbfb8aa3b, v55
	v_exp_f32_e32 v55, v0
	v_add_u32_e32 v58, 0xb0, v164
	v_pk_add_f32 v[62:63], v[50:51], 1.0 op_sel_hi:[1,0]
	v_ashrrev_i32_e32 v59, 31, v58
	v_pk_add_f32 v[50:51], v[54:55], 1.0 op_sel_hi:[1,0]
	v_lshlrev_b64 v[58:59], 11, v[58:59]
	v_pk_mul_f32 v[54:55], v[62:63], v[50:51]
	v_lshl_add_u64 v[58:59], v[166:167], 0, v[58:59]
	v_rcp_f32_e32 v54, v54
	v_rcp_f32_e32 v55, v55
	global_load_dwordx4 v[58:61], v[58:59], off
	s_mov_b64 s[14:15], 0x50000
	v_pk_mul_f32 v[50:51], v[50:51], v[54:55]
	s_nop 0
	v_pk_mul_f32 v[50:51], v[46:47], v[50:51]
	v_pk_mul_f32 v[54:55], v[62:63], v[54:55]
	v_add_f32_e32 v0, v50, v50
	v_exp_f32_e32 v0, v0
	v_lshlrev_b32_e32 v62, 16, v74
	v_and_b32_e32 v63, 0xffff0000, v74
	v_sub_f32_e32 v0, 1.0, v0
	v_max_f32_e32 v0, 0, v0
	v_sqrt_f32_e32 v64, v0
	v_add_f32_e32 v0, v51, v51
	v_exp_f32_e32 v0, v0
	s_nop 0
	v_sub_f32_e32 v0, 1.0, v0
	v_max_f32_e32 v0, 0, v0
	v_sqrt_f32_e32 v65, v0
	v_add_f32_e32 v0, v52, v28
	v_med3_f32 v0, v0, s84, v250
	v_add_f32_e32 v52, v56, v32
	v_med3_f32 v56, v52, s84, v250
	v_mul_f32_e32 v0, 0xbfb8aa3b, v0
	v_exp_f32_e32 v52, v0
	v_mul_f32_e32 v0, 0xbfb8aa3b, v56
	v_exp_f32_e32 v56, v0
	v_add_f32_e32 v0, v53, v29
	v_med3_f32 v0, v0, s84, v250
	v_add_f32_e32 v53, v57, v33
	v_med3_f32 v57, v53, s84, v250
	v_mul_f32_e32 v0, 0xbfb8aa3b, v0
	v_exp_f32_e32 v53, v0
	v_mul_f32_e32 v0, 0xbfb8aa3b, v57
	v_exp_f32_e32 v57, v0
	v_pk_mul_f32 v[54:55], v[54:55], v[64:65]
	s_nop 0
	v_pk_mul_f32 v[54:55], v[54:55], v[62:63]
	v_pk_add_f32 v[62:63], v[52:53], 1.0 op_sel_hi:[1,0]
	v_pk_add_f32 v[52:53], v[56:57], 1.0 op_sel_hi:[1,0]
	s_nop 0
	v_pk_mul_f32 v[56:57], v[62:63], v[52:53]
	s_nop 0
	v_rcp_f32_e32 v56, v56
	v_rcp_f32_e32 v57, v57
	s_nop 0
	v_pk_mul_f32 v[52:53], v[52:53], v[56:57]
	s_nop 0
	v_pk_mul_f32 v[52:53], v[48:49], v[52:53]
	v_pk_mul_f32 v[56:57], v[62:63], v[56:57]
	v_add_f32_e32 v0, v52, v52
	v_exp_f32_e32 v0, v0
	v_lshlrev_b32_e32 v62, 16, v75
	v_and_b32_e32 v63, 0xffff0000, v75
	v_sub_f32_e32 v0, 1.0, v0
	v_max_f32_e32 v0, 0, v0
	v_sqrt_f32_e32 v64, v0
	v_add_f32_e32 v0, v53, v53
	v_exp_f32_e32 v0, v0
	s_nop 0
	v_sub_f32_e32 v0, 1.0, v0
	v_max_f32_e32 v0, 0, v0
	v_sqrt_f32_e32 v65, v0
	v_add_f32_e32 v0, v38, v10
	v_med3_f32 v0, v0, s84, v250
	v_add_f32_e32 v38, v42, v14
	v_med3_f32 v42, v38, s84, v250
	v_mul_f32_e32 v0, 0xbfb8aa3b, v0
	v_exp_f32_e32 v38, v0
	v_mul_f32_e32 v0, 0xbfb8aa3b, v42
	v_exp_f32_e32 v42, v0
	v_add_f32_e32 v0, v39, v11
	v_med3_f32 v0, v0, s84, v250
	v_add_f32_e32 v39, v43, v15
	v_med3_f32 v43, v39, s84, v250
	v_mul_f32_e32 v0, 0xbfb8aa3b, v0
	v_exp_f32_e32 v39, v0
	v_mul_f32_e32 v0, 0xbfb8aa3b, v43
	v_exp_f32_e32 v43, v0
	v_pk_mul_f32 v[56:57], v[56:57], v[64:65]
	v_pk_add_f32 v[38:39], v[38:39], 1.0 op_sel_hi:[1,0]
	v_pk_mul_f32 v[56:57], v[56:57], v[62:63]
	v_pk_add_f32 v[42:43], v[42:43], 1.0 op_sel_hi:[1,0]
	s_nop 0
	v_pk_mul_f32 v[62:63], v[38:39], v[42:43]
	s_nop 0
	v_rcp_f32_e32 v62, v62
	v_rcp_f32_e32 v63, v63
	s_nop 0
	v_pk_mul_f32 v[42:43], v[42:43], v[62:63]
	s_nop 0
	v_pk_mul_f32 v[42:43], v[34:35], v[42:43]
	v_pk_mul_f32 v[38:39], v[38:39], v[62:63]
	v_add_f32_e32 v0, v42, v42
	v_exp_f32_e32 v0, v0
	v_lshlrev_b32_e32 v62, 16, v76
	v_and_b32_e32 v63, 0xffff0000, v76
	v_sub_f32_e32 v0, 1.0, v0
	v_max_f32_e32 v0, 0, v0
	v_sqrt_f32_e32 v64, v0
	v_add_f32_e32 v0, v43, v43
	v_exp_f32_e32 v0, v0
	s_nop 0
	v_sub_f32_e32 v0, 1.0, v0
	v_max_f32_e32 v0, 0, v0
	v_sqrt_f32_e32 v65, v0
	v_add_f32_e32 v0, v40, v12
	v_med3_f32 v0, v0, s84, v250
	v_mul_f32_e32 v0, 0xbfb8aa3b, v0
	v_pk_mul_f32 v[38:39], v[38:39], v[64:65]
	s_nop 0
	v_pk_mul_f32 v[62:63], v[38:39], v[62:63]
	v_add_f32_e32 v38, v44, v16
	v_med3_f32 v39, v38, s84, v250
	v_exp_f32_e32 v38, v0
	v_mul_f32_e32 v0, 0xbfb8aa3b, v39
	v_exp_f32_e32 v40, v0
	v_add_f32_e32 v0, v41, v13
	v_med3_f32 v0, v0, s84, v250
	v_add_f32_e32 v39, v45, v17
	v_med3_f32 v41, v39, s84, v250
	v_mul_f32_e32 v0, 0xbfb8aa3b, v0
	v_exp_f32_e32 v39, v0
	v_mul_f32_e32 v0, 0xbfb8aa3b, v41
	v_exp_f32_e32 v41, v0
	v_pk_add_f32 v[38:39], v[38:39], 1.0 op_sel_hi:[1,0]
	v_pk_add_f32 v[40:41], v[40:41], 1.0 op_sel_hi:[1,0]
	s_nop 0
	v_pk_mul_f32 v[44:45], v[38:39], v[40:41]
	s_nop 0
	v_rcp_f32_e32 v44, v44
	v_rcp_f32_e32 v45, v45
	s_nop 0
	v_pk_mul_f32 v[40:41], v[40:41], v[44:45]
	s_nop 0
	v_pk_mul_f32 v[64:65], v[36:37], v[40:41]
	v_pk_mul_f32 v[38:39], v[38:39], v[44:45]
	v_add_f32_e32 v0, v64, v64
	v_exp_f32_e32 v0, v0
	v_lshlrev_b32_e32 v44, 16, v77
	v_and_b32_e32 v45, 0xffff0000, v77
	v_sub_f32_e32 v0, 1.0, v0
	v_max_f32_e32 v0, 0, v0
	v_sqrt_f32_e32 v40, v0
	v_add_f32_e32 v0, v65, v65
	v_exp_f32_e32 v0, v0
	s_nop 0
	v_sub_f32_e32 v0, 1.0, v0
	v_max_f32_e32 v0, 0, v0
	v_sqrt_f32_e32 v41, v0
	s_nop 0
	v_pk_mul_f32 v[38:39], v[38:39], v[40:41]
	s_nop 0
	v_pk_mul_f32 v[66:67], v[38:39], v[44:45]
	v_cvt_pk_bf16_f32 v38, v50, v51
	v_lshl_add_u64 v[50:51], v[158:159], 0, s[14:15]
	v_cvt_pk_bf16_f32 v39, v52, v53
	v_cvt_pk_bf16_f32 v40, v42, v43
	v_cvt_pk_bf16_f32 v41, v64, v65
	v_lshl_add_u64 v[52:53], v[160:161], 0, v[50:51]
	v_cvt_pk_bf16_f32 v42, v54, v55
	v_cvt_pk_bf16_f32 v43, v56, v57
	v_cvt_pk_bf16_f32 v44, v62, v63
	v_cvt_pk_bf16_f32 v45, v66, v67
	global_store_dwordx4 v[52:53], v[38:41], off
	s_nop 1
	v_lshl_add_u64 v[38:39], v[162:163], 0, v[50:51]
	global_store_dwordx4 v[38:39], v[42:45], off
	v_add_f32_e32 v0, v18, v26
	v_med3_f32 v0, v0, s84, v250
	v_add_f32_e32 v18, v22, v30
	v_med3_f32 v22, v18, s84, v250
	v_mul_f32_e32 v0, 0xbfb8aa3b, v0
	v_exp_f32_e32 v18, v0
	v_mul_f32_e32 v0, 0xbfb8aa3b, v22
	v_exp_f32_e32 v22, v0
	v_add_f32_e32 v0, v19, v27
	v_med3_f32 v0, v0, s84, v250
	v_add_f32_e32 v19, v23, v31
	v_med3_f32 v23, v19, s84, v250
	v_mul_f32_e32 v0, 0xbfb8aa3b, v0
	v_exp_f32_e32 v19, v0
	v_mul_f32_e32 v0, 0xbfb8aa3b, v23
	v_exp_f32_e32 v23, v0
	v_add_f32_e32 v20, v20, v28
	v_pk_add_f32 v[18:19], v[18:19], 1.0 op_sel_hi:[1,0]
	v_add_f32_e32 v24, v24, v32
	v_pk_add_f32 v[22:23], v[22:23], 1.0 op_sel_hi:[1,0]
	v_add_f32_e32 v21, v21, v29
	v_pk_mul_f32 v[26:27], v[18:19], v[22:23]
	v_add_f32_e32 v25, v25, v33
	v_rcp_f32_e32 v26, v26
	v_rcp_f32_e32 v27, v27
	v_med3_f32 v20, v20, s84, v250
	v_med3_f32 v24, v24, s84, v250
	v_med3_f32 v21, v21, s84, v250
	v_pk_mul_f32 v[22:23], v[22:23], v[26:27]
	v_med3_f32 v25, v25, s84, v250
	v_pk_mul_f32 v[22:23], v[46:47], v[22:23]
	v_mul_f32_e32 v20, 0xbfb8aa3b, v20
	v_add_f32_e32 v0, v22, v22
	v_exp_f32_e32 v0, v0
	v_mul_f32_e32 v24, 0xbfb8aa3b, v24
	v_mul_f32_e32 v21, 0xbfb8aa3b, v21
	v_mul_f32_e32 v25, 0xbfb8aa3b, v25
	v_exp_f32_e32 v20, v20
	v_exp_f32_e32 v24, v24
	v_exp_f32_e32 v21, v21
	v_exp_f32_e32 v25, v25
	v_sub_f32_e32 v0, 1.0, v0
	v_max_f32_e32 v0, 0, v0
	v_pk_add_f32 v[20:21], v[20:21], 1.0 op_sel_hi:[1,0]
	v_pk_add_f32 v[24:25], v[24:25], 1.0 op_sel_hi:[1,0]
	v_sqrt_f32_e32 v30, v0
	v_add_f32_e32 v0, v23, v23
	v_pk_mul_f32 v[28:29], v[20:21], v[24:25]
	v_exp_f32_e32 v0, v0
	v_rcp_f32_e32 v28, v28
	v_rcp_f32_e32 v29, v29
	v_add_f32_e32 v2, v2, v10
	v_sub_f32_e32 v0, 1.0, v0
	v_max_f32_e32 v0, 0, v0
	v_pk_mul_f32 v[24:25], v[24:25], v[28:29]
	v_sqrt_f32_e32 v31, v0
	v_pk_mul_f32 v[24:25], v[48:49], v[24:25]
	v_add_f32_e32 v6, v6, v14
	v_add_f32_e32 v0, v24, v24
	v_exp_f32_e32 v0, v0
	v_add_f32_e32 v3, v3, v11
	v_add_f32_e32 v7, v7, v15
	v_med3_f32 v2, v2, s84, v250
	v_med3_f32 v6, v6, s84, v250
	v_med3_f32 v3, v3, s84, v250
	v_med3_f32 v7, v7, s84, v250
	v_mul_f32_e32 v2, 0xbfb8aa3b, v2
	v_mul_f32_e32 v6, 0xbfb8aa3b, v6
	v_mul_f32_e32 v3, 0xbfb8aa3b, v3
	v_mul_f32_e32 v7, 0xbfb8aa3b, v7
	v_pk_mul_f32 v[18:19], v[18:19], v[26:27]
	v_sub_f32_e32 v0, 1.0, v0
	v_exp_f32_e32 v2, v2
	v_exp_f32_e32 v6, v6
	v_exp_f32_e32 v3, v3
	v_exp_f32_e32 v7, v7
	s_waitcnt vmcnt(0)
	v_lshlrev_b32_e32 v26, 16, v58
	v_and_b32_e32 v27, 0xffff0000, v58
	v_pk_mul_f32 v[18:19], v[18:19], v[30:31]
	v_max_f32_e32 v0, 0, v0
	v_pk_mul_f32 v[18:19], v[18:19], v[26:27]
	v_sqrt_f32_e32 v26, v0
	v_add_f32_e32 v0, v25, v25
	v_exp_f32_e32 v0, v0
	v_pk_add_f32 v[2:3], v[2:3], 1.0 op_sel_hi:[1,0]
	v_pk_add_f32 v[6:7], v[6:7], 1.0 op_sel_hi:[1,0]
	v_add_f32_e32 v4, v4, v12
	v_pk_mul_f32 v[14:15], v[2:3], v[6:7]
	v_sub_f32_e32 v0, 1.0, v0
	v_rcp_f32_e32 v14, v14
	v_rcp_f32_e32 v15, v15
	v_max_f32_e32 v0, 0, v0
	v_sqrt_f32_e32 v27, v0
	v_add_f32_e32 v8, v8, v16
	v_add_f32_e32 v5, v5, v13
	v_add_f32_e32 v9, v9, v17
	v_pk_mul_f32 v[6:7], v[6:7], v[14:15]
	v_med3_f32 v4, v4, s84, v250
	v_med3_f32 v8, v8, s84, v250
	v_med3_f32 v5, v5, s84, v250
	v_med3_f32 v9, v9, s84, v250
	v_pk_mul_f32 v[6:7], v[34:35], v[6:7]
	v_mul_f32_e32 v4, 0xbfb8aa3b, v4
	v_mul_f32_e32 v8, 0xbfb8aa3b, v8
	v_mul_f32_e32 v5, 0xbfb8aa3b, v5
	v_mul_f32_e32 v9, 0xbfb8aa3b, v9
	v_pk_mul_f32 v[20:21], v[20:21], v[28:29]
	v_add_f32_e32 v0, v6, v6
	v_exp_f32_e32 v4, v4
	v_exp_f32_e32 v8, v8
	v_exp_f32_e32 v5, v5
	v_exp_f32_e32 v9, v9
	v_lshlrev_b32_e32 v10, 16, v59
	v_exp_f32_e32 v0, v0
	v_and_b32_e32 v11, 0xffff0000, v59
	v_pk_mul_f32 v[20:21], v[20:21], v[26:27]
	v_pk_add_f32 v[4:5], v[4:5], 1.0 op_sel_hi:[1,0]
	v_pk_mul_f32 v[10:11], v[20:21], v[10:11]
	v_add_f32_e32 v20, v7, v7
	v_exp_f32_e32 v21, v20
	v_pk_add_f32 v[8:9], v[8:9], 1.0 op_sel_hi:[1,0]
	v_sub_f32_e32 v0, 1.0, v0
	v_pk_mul_f32 v[12:13], v[4:5], v[8:9]
	v_max_f32_e32 v0, 0, v0
	v_rcp_f32_e32 v12, v12
	v_rcp_f32_e32 v13, v13
	v_sqrt_f32_e32 v20, v0
	v_sub_f32_e32 v0, 1.0, v21
	v_max_f32_e32 v0, 0, v0
	v_sqrt_f32_e32 v21, v0
	v_pk_mul_f32 v[8:9], v[8:9], v[12:13]
	v_pk_mul_f32 v[2:3], v[2:3], v[14:15]
	v_pk_mul_f32 v[8:9], v[36:37], v[8:9]
	v_lshlrev_b32_e32 v14, 16, v60
	v_add_f32_e32 v0, v8, v8
	v_and_b32_e32 v15, 0xffff0000, v60
	v_pk_mul_f32 v[2:3], v[2:3], v[20:21]
	v_exp_f32_e32 v0, v0
	v_pk_mul_f32 v[14:15], v[2:3], v[14:15]
	v_add_f32_e32 v2, v9, v9
	v_exp_f32_e32 v3, v2
	v_sub_f32_e32 v0, 1.0, v0
	v_max_f32_e32 v0, 0, v0
	v_sqrt_f32_e32 v2, v0
	v_sub_f32_e32 v0, 1.0, v3
	v_max_f32_e32 v0, 0, v0
	v_sqrt_f32_e32 v3, v0
	v_pk_mul_f32 v[4:5], v[4:5], v[12:13]
	v_lshlrev_b32_e32 v12, 16, v61
	v_and_b32_e32 v13, 0xffff0000, v61
	v_pk_mul_f32 v[2:3], v[4:5], v[2:3]
	s_mov_b64 s[14:15], 0x58000
	v_pk_mul_f32 v[12:13], v[2:3], v[12:13]
	v_cvt_pk_bf16_f32 v4, v6, v7
	v_cvt_pk_bf16_f32 v7, v10, v11
	v_lshl_add_u64 v[10:11], v[158:159], 0, s[14:15]
	v_cvt_pk_bf16_f32 v2, v22, v23
	v_cvt_pk_bf16_f32 v3, v24, v25
	v_cvt_pk_bf16_f32 v5, v8, v9
	v_cvt_pk_bf16_f32 v9, v12, v13
	v_lshl_add_u64 v[12:13], v[160:161], 0, v[10:11]
	v_cvt_pk_bf16_f32 v6, v18, v19
	v_cvt_pk_bf16_f32 v8, v14, v15
	global_store_dwordx4 v[12:13], v[2:5], off
	s_mov_b64 s[14:15], -1
	v_readfirstlane_b32 s16, v0
	v_lshl_add_u64 v[2:3], v[162:163], 0, v[10:11]
	s_andn2_b64 vcc, exec, s[12:13]
	v_readfirstlane_b32 s12, v0
	global_store_dwordx4 v[2:3], v[6:9], off
	s_cbranch_vccnz .LBB0_309
	v_mbcnt_lo_u32_b32 v3, -1, 0
	v_mbcnt_hi_u32_b32 v3, -1, v3
	s_nop 0
	v_mov_b32_e32 v9, 1
	v_lshl_add_u32 v2, v3, 4, s53
	v_ashrrev_i32_e32 v0, 31, v2
	v_lshrrev_b32_e32 v0, 22, v0
	v_add_u32_e32 v0, v2, v0
	v_ashrrev_i32_e32 v0, 10, v0
	v_mul_i32_i24_e32 v4, 0x400, v0
	v_sub_u32_e32 v4, v2, v4
	v_lshrrev_b32_e32 v5, 4, v4
	v_bitop3_b32 v4, v5, v4, 32 bitop3:0x6c
	v_ashrrev_i32_e32 v6, 31, v4
	v_lshrrev_b32_e32 v6, 26, v6
	v_add_u32_e32 v6, v4, v6
	v_lshlrev_b32_e32 v5, 3, v0
	v_ashrrev_i32_e32 v7, 6, v6
	v_and_b32_e32 v6, 0xc0, v6
	v_and_b32_e32 v5, -16, v5
	v_lshlrev_b32_e32 v0, 5, v0
	v_sub_u32_e32 v4, v4, v6
	v_add_u32_e32 v5, v7, v5
	v_and_b32_e32 v0, 32, v0
	v_ashrrev_i16_sdwa v4, v9, sext(v4) dst_sel:DWORD dst_unused:UNUSED_PAD src0_sel:DWORD src1_sel:BYTE_0
	v_add_u32_sdwa v0, v0, sext(v4) dst_sel:DWORD dst_unused:UNUSED_PAD src0_sel:DWORD src1_sel:WORD_0
	v_lshlrev_b32_e32 v4, 11, v5
	v_add_u32_e32 v2, 0x2000, v2
	v_lshl_add_u32 v0, v0, 1, v4
	v_ashrrev_i32_e32 v4, 31, v2
	v_lshrrev_b32_e32 v4, 22, v4
	v_add_u32_e32 v4, v2, v4
	v_ashrrev_i32_e32 v4, 10, v4
	v_mad_u64_u32 v[6:7], s[12:13], v5, s44, v[0:1]
	v_mul_i32_i24_e32 v5, 0x400, v4
	v_sub_u32_e32 v2, v2, v5
	v_lshrrev_b32_e32 v5, 4, v2
	v_bitop3_b32 v2, v5, v2, 32 bitop3:0x6c
	v_ashrrev_i32_e32 v7, 31, v2
	v_lshrrev_b32_e32 v7, 26, v7
	v_add_u32_e32 v7, v2, v7
	v_ashrrev_i32_e32 v8, 6, v7
	v_and_b32_e32 v7, 0xffc0, v7
	v_sub_u32_e32 v2, v2, v7
	v_lshrrev_b16_e32 v7, 7, v2
	v_lshlrev_b32_e32 v5, 3, v4
	v_and_b32_e32 v7, 1, v7
	v_and_b32_e32 v5, -16, v5
	v_lshlrev_b32_e32 v4, 5, v4
	v_add_u16_e32 v2, v2, v7
	v_add_u32_e32 v5, v8, v5
	v_and_b32_e32 v4, 32, v4
	v_ashrrev_i16_sdwa v2, v9, sext(v2) dst_sel:DWORD dst_unused:UNUSED_PAD src0_sel:DWORD src1_sel:BYTE_0
	v_add_u32_sdwa v2, v4, sext(v2) dst_sel:DWORD dst_unused:UNUSED_PAD src0_sel:DWORD src1_sel:WORD_0
	v_lshlrev_b32_e32 v4, 11, v5
	v_lshl_add_u32 v2, v2, 1, v4
	v_mad_u64_u32 v[8:9], s[12:13], v5, s44, v[2:3]
	v_and_b32_e32 v4, 15, v3
	v_and_b32_e32 v5, 48, v3
	v_lshlrev_b32_e32 v3, 2, v3
	v_lshlrev_b32_e32 v4, 6, v4
	v_and_b32_e32 v3, 32, v3
	v_bitop3_b32 v3, v4, v3, v5 bitop3:0x36
	s_add_i32 s16, s26, s55
	s_add_i32 s12, s25, s43
	s_mov_b64 s[14:15], 0
	s_branch .LBB0_309

.Lat_nosq12:
.Lat_x_nostore:
	s_setprio 2
	s_cmp_gt_i32 s22, s25
	s_cbranch_scc1 .Lat_x_nopre
	s_mul_i32 s36, s24, 0x6400
	v_add_u32_e32 v0, s36, v230
	ds_read_b128 v[162:165], v0
	ds_read_b128 v[166:169], v0 offset:12800
	ds_read_b128 v[170:173], v0 offset:32
	ds_read_b128 v[174:177], v0 offset:12832
	ds_read_b128 v[178:181], v0 offset:64
	ds_read_b128 v[182:185], v0 offset:12864

.Lat_x_pref:
	s_setprio 0
	s_cmp_eq_u32 s35, 0
	s_cbranch_scc1 .Lat_pr_a
	s_setprio 1

.LBB0_561:
	v_readlane_b32 s20, v252, 51
	v_or_b32_e32 v3, s62, v4
	s_add_i32 s29, 0, 0x10000
	v_or_b32_e32 v4, s20, v4
	v_add_u32_e32 v16, s29, v4
	ds_read_b128 v[18:21], v16
	ds_read_b128 v[22:25], v16 offset:1024
	ds_read_b128 v[26:29], v16 offset:2048
	ds_read_b128 v[30:33], v16 offset:3072
	s_add_i32 s34, 0, 0x1c000
	v_add_u32_e32 v12, 0, v3
	s_add_i32 s30, 0, 0x14000
	s_add_i32 s31, 0, 0x18000
	v_add_u32_e32 v13, s34, v4
	v_add_u32_e32 v15, s30, v4
	v_add_u32_e32 v14, s31, v4
	s_add_u32 s20, s4, 0x18080
	s_addc_u32 s21, s5, 0
	s_add_i32 s35, s63, 0xc000
	s_mov_b32 m0, s35
	s_add_i32 s36, s63, 0xe000
	ds_read_b128 v[8:11], v12
	ds_read_b128 v[34:37], v12 offset:1024
	ds_read_b128 v[38:41], v12 offset:2048
	ds_read_b128 v[42:45], v12 offset:3072
	ds_read_b128 v[46:49], v12 offset:4096
	ds_read_b128 v[50:53], v12 offset:5120
	ds_read_b128 v[54:57], v12 offset:6144
	ds_read_b128 v[58:61], v12 offset:7168
	global_load_lds_dwordx4 v0, s[20:21]
	s_mov_b32 m0, s36
	v_mov_b32_e32 v3, v1
	s_waitcnt lgkmcnt(0)
	global_load_lds_dwordx4 v2, s[20:21]
	s_waitcnt lgkmcnt(8)
	s_barrier
	s_waitcnt lgkmcnt(0)
	s_waitcnt lgkmcnt(0)
	v_mfma_f32_16x16x32_bf16 v[4:7], v[18:21], v[8:11], 0
	v_mfma_f32_16x16x32_bf16 v[62:65], v[22:25], v[34:37], v[4:7]
	v_mfma_f32_16x16x32_bf16 v[4:7], v[26:29], v[8:11], 0
	v_mfma_f32_16x16x32_bf16 v[66:69], v[30:33], v[34:37], v[4:7]
	v_mfma_f32_16x16x32_bf16 v[4:7], v[18:21], v[38:41], 0
	s_waitcnt vmcnt(0)
	v_mfma_f32_16x16x32_bf16 v[70:73], v[22:25], v[42:45], v[4:7]
	v_mfma_f32_16x16x32_bf16 v[4:7], v[26:29], v[38:41], 0
	v_mfma_f32_16x16x32_bf16 v[74:77], v[30:33], v[42:45], v[4:7]
	v_mfma_f32_16x16x32_bf16 v[4:7], v[18:21], v[46:49], 0
	v_mfma_f32_16x16x32_bf16 v[78:81], v[22:25], v[50:53], v[4:7]
	v_mfma_f32_16x16x32_bf16 v[4:7], v[26:29], v[46:49], 0
	v_mfma_f32_16x16x32_bf16 v[82:85], v[30:33], v[50:53], v[4:7]
	v_mfma_f32_16x16x32_bf16 v[4:7], v[18:21], v[54:57], 0
	v_mfma_f32_16x16x32_bf16 v[86:89], v[22:25], v[58:61], v[4:7]
	v_mfma_f32_16x16x32_bf16 v[4:7], v[26:29], v[54:57], 0
	v_mfma_f32_16x16x32_bf16 v[90:93], v[30:33], v[58:61], v[4:7]
	s_barrier
	s_nop 4
	v_lshl_add_u64 v[4:5], s[18:19], 0, v[0:1]
	s_add_i32 s37, s29, s53
	v_lshl_add_u64 v[6:7], v[4:5], 0, s[76:77]
	s_mov_b32 m0, s37
	ds_read_b128 v[94:97], v15
	ds_read_b128 v[98:101], v15 offset:1024
	ds_read_b128 v[102:105], v15 offset:2048
	ds_read_b128 v[106:109], v15 offset:3072
	global_load_lds_dwordx4 v[6:7], off
	v_lshl_add_u64 v[6:7], s[18:19], 0, v[2:3]
	s_add_i32 s38, s37, 0x2000
	v_lshl_add_u64 v[110:111], v[6:7], 0, s[76:77]
	s_mov_b32 m0, s38
	s_nop 0
	global_load_lds_dwordx4 v[110:111], off
	s_barrier
	s_waitcnt lgkmcnt(0)
	s_waitcnt lgkmcnt(0)
	v_mfma_f32_16x16x32_bf16 v[110:113], v[94:97], v[8:11], 0
	v_mfma_f32_16x16x32_bf16 v[8:11], v[102:105], v[8:11], 0
	v_mfma_f32_16x16x32_bf16 v[110:113], v[98:101], v[34:37], v[110:113]
	v_mfma_f32_16x16x32_bf16 v[34:37], v[106:109], v[34:37], v[8:11]
	v_mfma_f32_16x16x32_bf16 v[8:11], v[94:97], v[38:41], 0
	v_mfma_f32_16x16x32_bf16 v[114:117], v[98:101], v[42:45], v[8:11]
	v_mfma_f32_16x16x32_bf16 v[8:11], v[102:105], v[38:41], 0
	v_mfma_f32_16x16x32_bf16 v[38:41], v[106:109], v[42:45], v[8:11]
	v_mfma_f32_16x16x32_bf16 v[8:11], v[94:97], v[46:49], 0
	v_mfma_f32_16x16x32_bf16 v[42:45], v[98:101], v[50:53], v[8:11]
	v_mfma_f32_16x16x32_bf16 v[8:11], v[102:105], v[46:49], 0
	v_mfma_f32_16x16x32_bf16 v[46:49], v[106:109], v[50:53], v[8:11]
	v_mfma_f32_16x16x32_bf16 v[8:11], v[94:97], v[54:57], 0
	v_mfma_f32_16x16x32_bf16 v[50:53], v[98:101], v[58:61], v[8:11]
	v_mfma_f32_16x16x32_bf16 v[8:11], v[102:105], v[54:57], 0
	v_mfma_f32_16x16x32_bf16 v[54:57], v[106:109], v[58:61], v[8:11]
	s_nop 5
	v_lshl_add_u64 v[8:9], s[4:5], 0, v[0:1]
	s_mov_b32 m0, s63
	v_lshl_add_u64 v[10:11], v[8:9], 0, s[76:77]
	s_barrier
	ds_read_b128 v[58:61], v12 offset:16384
	ds_read_b128 v[118:121], v12 offset:17408
	ds_read_b128 v[122:125], v12 offset:18432
	ds_read_b128 v[126:129], v12 offset:19456
	ds_read_b128 v[130:133], v12 offset:20480
	ds_read_b128 v[134:137], v12 offset:21504
	ds_read_b128 v[138:141], v12 offset:22528
	ds_read_b128 v[142:145], v12 offset:23552
	global_load_lds_dwordx4 v[10:11], off
	v_lshl_add_u64 v[10:11], s[4:5], 0, v[2:3]
	v_lshl_add_u64 v[146:147], v[10:11], 0, s[76:77]
	s_mov_b32 m0, s24
	s_nop 0
	global_load_lds_dwordx4 v[146:147], off
	s_barrier
	s_waitcnt lgkmcnt(0)
	s_waitcnt lgkmcnt(0)
	v_mfma_f32_16x16x32_bf16 v[146:149], v[18:21], v[58:61], 0
	v_mfma_f32_16x16x32_bf16 v[154:157], v[18:21], v[122:125], 0
	v_mfma_f32_16x16x32_bf16 v[162:165], v[18:21], v[130:133], 0
	v_mfma_f32_16x16x32_bf16 v[18:21], v[18:21], v[138:141], 0
	v_mfma_f32_16x16x32_bf16 v[146:149], v[22:25], v[118:121], v[146:149]
	v_mfma_f32_16x16x32_bf16 v[150:153], v[26:29], v[58:61], 0
	v_mfma_f32_16x16x32_bf16 v[154:157], v[22:25], v[126:129], v[154:157]
	v_mfma_f32_16x16x32_bf16 v[158:161], v[26:29], v[122:125], 0
	v_mfma_f32_16x16x32_bf16 v[162:165], v[22:25], v[134:137], v[162:165]
	v_mfma_f32_16x16x32_bf16 v[166:169], v[26:29], v[130:133], 0
	v_mfma_f32_16x16x32_bf16 v[18:21], v[22:25], v[142:145], v[18:21]
	v_mfma_f32_16x16x32_bf16 v[22:25], v[26:29], v[138:141], 0
	v_mfma_f32_16x16x32_bf16 v[150:153], v[30:33], v[118:121], v[150:153]
	v_mfma_f32_16x16x32_bf16 v[158:161], v[30:33], v[126:129], v[158:161]
	v_mfma_f32_16x16x32_bf16 v[166:169], v[30:33], v[134:137], v[166:169]
	v_mfma_f32_16x16x32_bf16 v[22:25], v[30:33], v[142:145], v[22:25]
	s_barrier
	s_add_u32 s20, s18, 0x18100
	s_addc_u32 s21, s19, 0
	s_add_i32 s39, s30, s53
	s_mov_b32 m0, s39
	s_add_i32 s43, s39, 0x2000
	global_load_lds_dwordx4 v0, s[20:21]
	s_mov_b32 m0, s43
	s_nop 0
	global_load_lds_dwordx4 v2, s[20:21]
	s_waitcnt vmcnt(6)
	s_barrier
	v_mfma_f32_16x16x32_bf16 v[26:29], v[94:97], v[58:61], 0
	v_mfma_f32_16x16x32_bf16 v[30:33], v[102:105], v[58:61], 0
	v_mfma_f32_16x16x32_bf16 v[26:29], v[98:101], v[118:121], v[26:29]
	v_mfma_f32_16x16x32_bf16 v[30:33], v[106:109], v[118:121], v[30:33]
	v_mfma_f32_16x16x32_bf16 v[58:61], v[94:97], v[122:125], 0
	v_mfma_f32_16x16x32_bf16 v[118:121], v[102:105], v[122:125], 0
	v_mfma_f32_16x16x32_bf16 v[122:125], v[94:97], v[130:133], 0
	v_mfma_f32_16x16x32_bf16 v[94:97], v[94:97], v[138:141], 0
	v_mfma_f32_16x16x32_bf16 v[58:61], v[98:101], v[126:129], v[58:61]
	v_mfma_f32_16x16x32_bf16 v[118:121], v[106:109], v[126:129], v[118:121]
	v_mfma_f32_16x16x32_bf16 v[122:125], v[98:101], v[134:137], v[122:125]
	v_mfma_f32_16x16x32_bf16 v[126:129], v[102:105], v[130:133], 0
	v_mfma_f32_16x16x32_bf16 v[94:97], v[98:101], v[142:145], v[94:97]
	v_mfma_f32_16x16x32_bf16 v[98:101], v[102:105], v[138:141], 0
	v_mfma_f32_16x16x32_bf16 v[126:129], v[106:109], v[134:137], v[126:129]
	v_mfma_f32_16x16x32_bf16 v[98:101], v[106:109], v[142:145], v[98:101]
	s_barrier
	ds_read_b128 v[102:105], v14
	ds_read_b128 v[106:109], v14 offset:1024
	ds_read_b128 v[130:133], v14 offset:2048
	ds_read_b128 v[134:137], v14 offset:3072
	s_add_u32 s20, s4, 0x18100
	s_addc_u32 s21, s5, 0
	s_mov_b32 m0, s25
	ds_read_b128 v[138:141], v12 offset:32768
	ds_read_b128 v[142:145], v12 offset:33792
	ds_read_b128 v[170:173], v12 offset:34816
	ds_read_b128 v[174:177], v12 offset:35840
	ds_read_b128 v[178:181], v12 offset:36864
	ds_read_b128 v[182:185], v12 offset:37888
	ds_read_b128 v[186:189], v12 offset:38912
	ds_read_b128 v[204:207], v12 offset:39936
	global_load_lds_dwordx4 v0, s[20:21]
	s_mov_b32 m0, s26
	s_nop 0
	global_load_lds_dwordx4 v2, s[20:21]
	s_waitcnt lgkmcnt(8)
	s_barrier
	s_waitcnt lgkmcnt(0)
	s_waitcnt lgkmcnt(0)
	v_mfma_f32_16x16x32_bf16 v[62:65], v[102:105], v[138:141], v[62:65]
	v_mfma_f32_16x16x32_bf16 v[66:69], v[130:133], v[138:141], v[66:69]
	v_mfma_f32_16x16x32_bf16 v[74:77], v[130:133], v[170:173], v[74:77]
	v_mfma_f32_16x16x32_bf16 v[86:89], v[102:105], v[186:189], v[86:89]
	v_mfma_f32_16x16x32_bf16 v[90:93], v[130:133], v[186:189], v[90:93]
	v_mfma_f32_16x16x32_bf16 v[62:65], v[106:109], v[142:145], v[62:65]
	v_mfma_f32_16x16x32_bf16 v[66:69], v[134:137], v[142:145], v[66:69]
	v_mfma_f32_16x16x32_bf16 v[70:73], v[102:105], v[170:173], v[70:73]
	v_mfma_f32_16x16x32_bf16 v[74:77], v[134:137], v[174:177], v[74:77]
	v_mfma_f32_16x16x32_bf16 v[78:81], v[102:105], v[178:181], v[78:81]
	v_mfma_f32_16x16x32_bf16 v[82:85], v[130:133], v[178:181], v[82:85]
	v_mfma_f32_16x16x32_bf16 v[86:89], v[106:109], v[204:207], v[86:89]
	v_mfma_f32_16x16x32_bf16 v[90:93], v[134:137], v[204:207], v[90:93]
	v_mfma_f32_16x16x32_bf16 v[70:73], v[106:109], v[174:177], v[70:73]
	v_mfma_f32_16x16x32_bf16 v[78:81], v[106:109], v[182:185], v[78:81]
	v_mfma_f32_16x16x32_bf16 v[82:85], v[134:137], v[182:185], v[82:85]
	s_barrier
	s_mov_b64 s[20:21], 0x180
	s_add_i32 s46, s31, s53
	v_lshl_add_u64 v[192:193], v[4:5], 0, s[20:21]
	s_mov_b32 m0, s46
	s_add_i32 s47, s46, 0x2000
	ds_read_b128 v[208:211], v13
	ds_read_b128 v[212:215], v13 offset:1024
	ds_read_b128 v[216:219], v13 offset:2048
	ds_read_b128 v[220:223], v13 offset:3072
	global_load_lds_dwordx4 v[192:193], off
	v_lshl_add_u64 v[192:193], v[6:7], 0, s[20:21]
	s_mov_b32 m0, s47
	s_nop 0
	global_load_lds_dwordx4 v[192:193], off
	s_barrier
	s_waitcnt lgkmcnt(0)
	s_waitcnt lgkmcnt(0)
	v_mfma_f32_16x16x32_bf16 v[110:113], v[208:211], v[138:141], v[110:113]
	v_mfma_f32_16x16x32_bf16 v[34:37], v[216:219], v[138:141], v[34:37]
	v_mfma_f32_16x16x32_bf16 v[114:117], v[208:211], v[170:173], v[114:117]
	v_mfma_f32_16x16x32_bf16 v[38:41], v[216:219], v[170:173], v[38:41]
	v_mfma_f32_16x16x32_bf16 v[42:45], v[208:211], v[178:181], v[42:45]
	v_mfma_f32_16x16x32_bf16 v[46:49], v[216:219], v[178:181], v[46:49]
	v_mfma_f32_16x16x32_bf16 v[50:53], v[208:211], v[186:189], v[50:53]
	v_mfma_f32_16x16x32_bf16 v[54:57], v[216:219], v[186:189], v[54:57]
	v_mfma_f32_16x16x32_bf16 v[110:113], v[212:215], v[142:145], v[110:113]
	v_mfma_f32_16x16x32_bf16 v[34:37], v[220:223], v[142:145], v[34:37]
	v_mfma_f32_16x16x32_bf16 v[114:117], v[212:215], v[174:177], v[114:117]
	v_mfma_f32_16x16x32_bf16 v[38:41], v[220:223], v[174:177], v[38:41]
	v_mfma_f32_16x16x32_bf16 v[42:45], v[212:215], v[182:185], v[42:45]
	v_mfma_f32_16x16x32_bf16 v[46:49], v[220:223], v[182:185], v[46:49]
	v_mfma_f32_16x16x32_bf16 v[50:53], v[212:215], v[204:207], v[50:53]
	v_mfma_f32_16x16x32_bf16 v[54:57], v[220:223], v[204:207], v[54:57]
	s_mov_b32 m0, s27
	v_lshl_add_u64 v[192:193], v[8:9], 0, s[20:21]
	s_barrier
	ds_read_b128 v[138:141], v12 offset:49152
	ds_read_b128 v[142:145], v12 offset:50176
	ds_read_b128 v[170:173], v12 offset:51200
	ds_read_b128 v[174:177], v12 offset:52224
	ds_read_b128 v[178:181], v12 offset:53248
	ds_read_b128 v[182:185], v12 offset:54272
	ds_read_b128 v[186:189], v12 offset:55296
	ds_read_b128 v[204:207], v12 offset:56320
	global_load_lds_dwordx4 v[192:193], off
	v_lshl_add_u64 v[192:193], v[10:11], 0, s[20:21]
	s_mov_b32 m0, s28
	s_nop 0
	global_load_lds_dwordx4 v[192:193], off
	s_barrier
	s_waitcnt lgkmcnt(0)
	s_waitcnt lgkmcnt(0)
	v_mfma_f32_16x16x32_bf16 v[146:149], v[102:105], v[138:141], v[146:149]
	v_mfma_f32_16x16x32_bf16 v[150:153], v[130:133], v[138:141], v[150:153]
	v_mfma_f32_16x16x32_bf16 v[154:157], v[102:105], v[170:173], v[154:157]
	v_mfma_f32_16x16x32_bf16 v[158:161], v[130:133], v[170:173], v[158:161]
	v_mfma_f32_16x16x32_bf16 v[162:165], v[102:105], v[178:181], v[162:165]
	v_mfma_f32_16x16x32_bf16 v[166:169], v[130:133], v[178:181], v[166:169]
	v_mfma_f32_16x16x32_bf16 v[22:25], v[130:133], v[186:189], v[22:25]
	v_mfma_f32_16x16x32_bf16 v[146:149], v[106:109], v[142:145], v[146:149]
	v_mfma_f32_16x16x32_bf16 v[150:153], v[134:137], v[142:145], v[150:153]
	v_mfma_f32_16x16x32_bf16 v[154:157], v[106:109], v[174:177], v[154:157]
	v_mfma_f32_16x16x32_bf16 v[158:161], v[134:137], v[174:177], v[158:161]
	v_mfma_f32_16x16x32_bf16 v[162:165], v[106:109], v[182:185], v[162:165]
	v_mfma_f32_16x16x32_bf16 v[166:169], v[134:137], v[182:185], v[166:169]
	v_mfma_f32_16x16x32_bf16 v[18:21], v[102:105], v[186:189], v[18:21]
	v_mfma_f32_16x16x32_bf16 v[22:25], v[134:137], v[204:207], v[22:25]
	v_mfma_f32_16x16x32_bf16 v[18:21], v[106:109], v[204:207], v[18:21]
	s_barrier
	s_add_u32 s20, s18, 0x18180
	s_addc_u32 s21, s19, 0
	s_add_i32 s52, s34, s53
	s_mov_b32 m0, s52
	s_add_i32 s60, s52, 0x2000
	global_load_lds_dwordx4 v0, s[20:21]
	s_mov_b32 m0, s60
	s_nop 0
	global_load_lds_dwordx4 v2, s[20:21]
	s_waitcnt vmcnt(6)
	s_barrier
	v_mfma_f32_16x16x32_bf16 v[26:29], v[208:211], v[138:141], v[26:29]
	v_mfma_f32_16x16x32_bf16 v[30:33], v[216:219], v[138:141], v[30:33]
	v_mfma_f32_16x16x32_bf16 v[58:61], v[208:211], v[170:173], v[58:61]
	v_mfma_f32_16x16x32_bf16 v[102:105], v[216:219], v[170:173], v[118:121]
	v_mfma_f32_16x16x32_bf16 v[106:109], v[208:211], v[178:181], v[122:125]
	v_mfma_f32_16x16x32_bf16 v[118:121], v[216:219], v[178:181], v[126:129]
	v_mfma_f32_16x16x32_bf16 v[94:97], v[208:211], v[186:189], v[94:97]
	v_mfma_f32_16x16x32_bf16 v[98:101], v[216:219], v[186:189], v[98:101]
	v_mfma_f32_16x16x32_bf16 v[26:29], v[212:215], v[142:145], v[26:29]
	v_mfma_f32_16x16x32_bf16 v[30:33], v[220:223], v[142:145], v[30:33]
	v_mfma_f32_16x16x32_bf16 v[58:61], v[212:215], v[174:177], v[58:61]
	v_mfma_f32_16x16x32_bf16 v[102:105], v[220:223], v[174:177], v[102:105]
	v_mfma_f32_16x16x32_bf16 v[106:109], v[212:215], v[182:185], v[106:109]
	v_mfma_f32_16x16x32_bf16 v[118:121], v[220:223], v[182:185], v[118:121]
	v_mfma_f32_16x16x32_bf16 v[94:97], v[212:215], v[204:207], v[94:97]
	v_mfma_f32_16x16x32_bf16 v[98:101], v[220:223], v[204:207], v[98:101]
	s_barrier
	ds_read_b128 v[122:125], v16
	ds_read_b128 v[126:129], v16 offset:1024
	ds_read_b128 v[130:133], v16 offset:2048
	ds_read_b128 v[134:137], v16 offset:3072
	s_add_u32 s20, s4, 0x18180
	s_addc_u32 s21, s5, 0
	s_mov_b32 m0, s35
	ds_read_b128 v[138:141], v12
	ds_read_b128 v[142:145], v12 offset:1024
	ds_read_b128 v[170:173], v12 offset:2048
	ds_read_b128 v[174:177], v12 offset:3072
	ds_read_b128 v[178:181], v12 offset:4096
	ds_read_b128 v[182:185], v12 offset:5120
	ds_read_b128 v[186:189], v12 offset:6144
	ds_read_b128 v[204:207], v12 offset:7168
	global_load_lds_dwordx4 v0, s[20:21]
	s_mov_b32 m0, s36
	s_nop 0
	global_load_lds_dwordx4 v2, s[20:21]
	s_waitcnt lgkmcnt(8)
	s_barrier
	s_waitcnt lgkmcnt(0)
	s_waitcnt lgkmcnt(0)
	v_mfma_f32_16x16x32_bf16 v[62:65], v[122:125], v[138:141], v[62:65]
	v_mfma_f32_16x16x32_bf16 v[66:69], v[130:133], v[138:141], v[66:69]
	v_mfma_f32_16x16x32_bf16 v[74:77], v[130:133], v[170:173], v[74:77]
	v_mfma_f32_16x16x32_bf16 v[86:89], v[122:125], v[186:189], v[86:89]
	v_mfma_f32_16x16x32_bf16 v[90:93], v[130:133], v[186:189], v[90:93]
	v_mfma_f32_16x16x32_bf16 v[62:65], v[126:129], v[142:145], v[62:65]
	v_mfma_f32_16x16x32_bf16 v[66:69], v[134:137], v[142:145], v[66:69]
	v_mfma_f32_16x16x32_bf16 v[70:73], v[122:125], v[170:173], v[70:73]
	v_mfma_f32_16x16x32_bf16 v[74:77], v[134:137], v[174:177], v[74:77]
	v_mfma_f32_16x16x32_bf16 v[78:81], v[122:125], v[178:181], v[78:81]
	v_mfma_f32_16x16x32_bf16 v[82:85], v[130:133], v[178:181], v[82:85]
	v_mfma_f32_16x16x32_bf16 v[86:89], v[126:129], v[204:207], v[86:89]
	v_mfma_f32_16x16x32_bf16 v[90:93], v[134:137], v[204:207], v[90:93]
	v_mfma_f32_16x16x32_bf16 v[70:73], v[126:129], v[174:177], v[70:73]
	v_mfma_f32_16x16x32_bf16 v[78:81], v[126:129], v[182:185], v[78:81]
	v_mfma_f32_16x16x32_bf16 v[82:85], v[134:137], v[182:185], v[82:85]
	s_barrier
	s_mov_b64 s[20:21], 0x200
	s_mov_b32 m0, s37
	v_lshl_add_u64 v[192:193], v[4:5], 0, s[20:21]
	ds_read_b128 v[208:211], v15
	ds_read_b128 v[212:215], v15 offset:1024
	ds_read_b128 v[216:219], v15 offset:2048
	ds_read_b128 v[220:223], v15 offset:3072
	global_load_lds_dwordx4 v[192:193], off
	v_lshl_add_u64 v[192:193], v[6:7], 0, s[20:21]
	s_mov_b32 m0, s38
	s_nop 0
	global_load_lds_dwordx4 v[192:193], off
	s_barrier
	s_waitcnt lgkmcnt(0)
	s_waitcnt lgkmcnt(0)
	v_mfma_f32_16x16x32_bf16 v[110:113], v[208:211], v[138:141], v[110:113]
	v_mfma_f32_16x16x32_bf16 v[34:37], v[216:219], v[138:141], v[34:37]
	v_mfma_f32_16x16x32_bf16 v[114:117], v[208:211], v[170:173], v[114:117]
	v_mfma_f32_16x16x32_bf16 v[38:41], v[216:219], v[170:173], v[38:41]
	v_mfma_f32_16x16x32_bf16 v[42:45], v[208:211], v[178:181], v[42:45]
	v_mfma_f32_16x16x32_bf16 v[46:49], v[216:219], v[178:181], v[46:49]
	v_mfma_f32_16x16x32_bf16 v[50:53], v[208:211], v[186:189], v[50:53]
	v_mfma_f32_16x16x32_bf16 v[54:57], v[216:219], v[186:189], v[54:57]
	v_mfma_f32_16x16x32_bf16 v[110:113], v[212:215], v[142:145], v[110:113]
	v_mfma_f32_16x16x32_bf16 v[34:37], v[220:223], v[142:145], v[34:37]
	v_mfma_f32_16x16x32_bf16 v[114:117], v[212:215], v[174:177], v[114:117]
	v_mfma_f32_16x16x32_bf16 v[38:41], v[220:223], v[174:177], v[38:41]
	v_mfma_f32_16x16x32_bf16 v[42:45], v[212:215], v[182:185], v[42:45]
	v_mfma_f32_16x16x32_bf16 v[46:49], v[220:223], v[182:185], v[46:49]
	v_mfma_f32_16x16x32_bf16 v[50:53], v[212:215], v[204:207], v[50:53]
	v_mfma_f32_16x16x32_bf16 v[54:57], v[220:223], v[204:207], v[54:57]
	s_mov_b32 m0, s63
	v_lshl_add_u64 v[192:193], v[8:9], 0, s[20:21]
	s_barrier
	ds_read_b128 v[138:141], v12 offset:16384
	ds_read_b128 v[142:145], v12 offset:17408
	ds_read_b128 v[170:173], v12 offset:18432
	ds_read_b128 v[174:177], v12 offset:19456
	ds_read_b128 v[178:181], v12 offset:20480
	ds_read_b128 v[182:185], v12 offset:21504
	ds_read_b128 v[186:189], v12 offset:22528
	ds_read_b128 v[204:207], v12 offset:23552
	global_load_lds_dwordx4 v[192:193], off
	v_lshl_add_u64 v[192:193], v[10:11], 0, s[20:21]
	s_mov_b32 m0, s24
	s_nop 0
	global_load_lds_dwordx4 v[192:193], off
	s_barrier
	s_waitcnt lgkmcnt(0)
	s_waitcnt lgkmcnt(0)
	v_mfma_f32_16x16x32_bf16 v[146:149], v[122:125], v[138:141], v[146:149]
	v_mfma_f32_16x16x32_bf16 v[150:153], v[130:133], v[138:141], v[150:153]
	v_mfma_f32_16x16x32_bf16 v[154:157], v[122:125], v[170:173], v[154:157]
	v_mfma_f32_16x16x32_bf16 v[158:161], v[130:133], v[170:173], v[158:161]
	v_mfma_f32_16x16x32_bf16 v[162:165], v[122:125], v[178:181], v[162:165]
	v_mfma_f32_16x16x32_bf16 v[166:169], v[130:133], v[178:181], v[166:169]
	v_mfma_f32_16x16x32_bf16 v[22:25], v[130:133], v[186:189], v[22:25]
	v_mfma_f32_16x16x32_bf16 v[146:149], v[126:129], v[142:145], v[146:149]
	v_mfma_f32_16x16x32_bf16 v[150:153], v[134:137], v[142:145], v[150:153]
	v_mfma_f32_16x16x32_bf16 v[154:157], v[126:129], v[174:177], v[154:157]
	v_mfma_f32_16x16x32_bf16 v[158:161], v[134:137], v[174:177], v[158:161]
	v_mfma_f32_16x16x32_bf16 v[162:165], v[126:129], v[182:185], v[162:165]
	v_mfma_f32_16x16x32_bf16 v[166:169], v[134:137], v[182:185], v[166:169]
	v_mfma_f32_16x16x32_bf16 v[18:21], v[122:125], v[186:189], v[18:21]
	v_mfma_f32_16x16x32_bf16 v[22:25], v[134:137], v[204:207], v[22:25]
	v_mfma_f32_16x16x32_bf16 v[18:21], v[126:129], v[204:207], v[18:21]
	s_barrier
	s_add_u32 s20, s18, 0x18200
	s_addc_u32 s21, s19, 0
	s_mov_b32 m0, s39
	s_nop 0
	global_load_lds_dwordx4 v0, s[20:21]
	s_mov_b32 m0, s43
	s_nop 0
	global_load_lds_dwordx4 v2, s[20:21]
	s_waitcnt vmcnt(6)
	s_barrier
	v_mfma_f32_16x16x32_bf16 v[26:29], v[208:211], v[138:141], v[26:29]
	v_mfma_f32_16x16x32_bf16 v[30:33], v[216:219], v[138:141], v[30:33]
	v_mfma_f32_16x16x32_bf16 v[58:61], v[208:211], v[170:173], v[58:61]
	v_mfma_f32_16x16x32_bf16 v[102:105], v[216:219], v[170:173], v[102:105]
	v_mfma_f32_16x16x32_bf16 v[106:109], v[208:211], v[178:181], v[106:109]
	v_mfma_f32_16x16x32_bf16 v[118:121], v[216:219], v[178:181], v[118:121]
	v_mfma_f32_16x16x32_bf16 v[94:97], v[208:211], v[186:189], v[94:97]
	v_mfma_f32_16x16x32_bf16 v[98:101], v[216:219], v[186:189], v[98:101]
	v_mfma_f32_16x16x32_bf16 v[26:29], v[212:215], v[142:145], v[26:29]
	v_mfma_f32_16x16x32_bf16 v[30:33], v[220:223], v[142:145], v[30:33]
	v_mfma_f32_16x16x32_bf16 v[58:61], v[212:215], v[174:177], v[58:61]
	v_mfma_f32_16x16x32_bf16 v[102:105], v[220:223], v[174:177], v[102:105]
	v_mfma_f32_16x16x32_bf16 v[106:109], v[212:215], v[182:185], v[106:109]
	v_mfma_f32_16x16x32_bf16 v[118:121], v[220:223], v[182:185], v[118:121]
	v_mfma_f32_16x16x32_bf16 v[94:97], v[212:215], v[204:207], v[94:97]
	v_mfma_f32_16x16x32_bf16 v[98:101], v[220:223], v[204:207], v[98:101]
	s_barrier
	ds_read_b128 v[122:125], v14
	ds_read_b128 v[126:129], v14 offset:1024
	ds_read_b128 v[130:133], v14 offset:2048
	ds_read_b128 v[134:137], v14 offset:3072
	s_add_u32 s20, s4, 0x18200
	s_addc_u32 s21, s5, 0
	s_mov_b32 m0, s25
	ds_read_b128 v[138:141], v12 offset:32768
	ds_read_b128 v[142:145], v12 offset:33792
	ds_read_b128 v[170:173], v12 offset:34816
	ds_read_b128 v[174:177], v12 offset:35840
	ds_read_b128 v[178:181], v12 offset:36864
	ds_read_b128 v[182:185], v12 offset:37888
	ds_read_b128 v[186:189], v12 offset:38912
	ds_read_b128 v[204:207], v12 offset:39936
	global_load_lds_dwordx4 v0, s[20:21]
	s_mov_b32 m0, s26
	s_nop 0
	global_load_lds_dwordx4 v2, s[20:21]
	s_waitcnt lgkmcnt(8)
	s_barrier
	s_waitcnt lgkmcnt(0)
	s_waitcnt lgkmcnt(0)
	v_mfma_f32_16x16x32_bf16 v[62:65], v[122:125], v[138:141], v[62:65]
	v_mfma_f32_16x16x32_bf16 v[66:69], v[130:133], v[138:141], v[66:69]
	v_mfma_f32_16x16x32_bf16 v[74:77], v[130:133], v[170:173], v[74:77]
	v_mfma_f32_16x16x32_bf16 v[86:89], v[122:125], v[186:189], v[86:89]
	v_mfma_f32_16x16x32_bf16 v[90:93], v[130:133], v[186:189], v[90:93]
	v_mfma_f32_16x16x32_bf16 v[62:65], v[126:129], v[142:145], v[62:65]
	v_mfma_f32_16x16x32_bf16 v[66:69], v[134:137], v[142:145], v[66:69]
	v_mfma_f32_16x16x32_bf16 v[70:73], v[122:125], v[170:173], v[70:73]
	v_mfma_f32_16x16x32_bf16 v[74:77], v[134:137], v[174:177], v[74:77]
	v_mfma_f32_16x16x32_bf16 v[78:81], v[122:125], v[178:181], v[78:81]
	v_mfma_f32_16x16x32_bf16 v[82:85], v[130:133], v[178:181], v[82:85]
	v_mfma_f32_16x16x32_bf16 v[86:89], v[126:129], v[204:207], v[86:89]
	v_mfma_f32_16x16x32_bf16 v[90:93], v[134:137], v[204:207], v[90:93]
	v_mfma_f32_16x16x32_bf16 v[70:73], v[126:129], v[174:177], v[70:73]
	v_mfma_f32_16x16x32_bf16 v[78:81], v[126:129], v[182:185], v[78:81]
	v_mfma_f32_16x16x32_bf16 v[82:85], v[134:137], v[182:185], v[82:85]
	s_barrier
	s_mov_b64 s[20:21], 0x280
	s_mov_b32 m0, s46
	v_lshl_add_u64 v[4:5], v[4:5], 0, s[20:21]
	ds_read_b128 v[208:211], v13
	ds_read_b128 v[212:215], v13 offset:1024
	ds_read_b128 v[216:219], v13 offset:2048
	ds_read_b128 v[220:223], v13 offset:3072
	global_load_lds_dwordx4 v[4:5], off
	v_lshl_add_u64 v[4:5], v[6:7], 0, s[20:21]
	s_mov_b32 m0, s47
	s_nop 0
	global_load_lds_dwordx4 v[4:5], off
	s_barrier
	s_waitcnt lgkmcnt(0)
	s_waitcnt lgkmcnt(0)
	v_mfma_f32_16x16x32_bf16 v[4:7], v[208:211], v[138:141], v[110:113]
	v_mfma_f32_16x16x32_bf16 v[34:37], v[216:219], v[138:141], v[34:37]
	v_mfma_f32_16x16x32_bf16 v[110:113], v[208:211], v[170:173], v[114:117]
	v_mfma_f32_16x16x32_bf16 v[38:41], v[216:219], v[170:173], v[38:41]
	v_mfma_f32_16x16x32_bf16 v[42:45], v[208:211], v[178:181], v[42:45]
	v_mfma_f32_16x16x32_bf16 v[46:49], v[216:219], v[178:181], v[46:49]
	v_mfma_f32_16x16x32_bf16 v[50:53], v[208:211], v[186:189], v[50:53]
	v_mfma_f32_16x16x32_bf16 v[54:57], v[216:219], v[186:189], v[54:57]
	v_mfma_f32_16x16x32_bf16 v[34:37], v[220:223], v[142:145], v[34:37]
	v_mfma_f32_16x16x32_bf16 v[110:113], v[212:215], v[174:177], v[110:113]
	v_mfma_f32_16x16x32_bf16 v[38:41], v[220:223], v[174:177], v[38:41]
	v_mfma_f32_16x16x32_bf16 v[42:45], v[212:215], v[182:185], v[42:45]
	v_mfma_f32_16x16x32_bf16 v[46:49], v[220:223], v[182:185], v[46:49]
	v_mfma_f32_16x16x32_bf16 v[50:53], v[212:215], v[204:207], v[50:53]
	v_mfma_f32_16x16x32_bf16 v[54:57], v[220:223], v[204:207], v[54:57]
	v_mfma_f32_16x16x32_bf16 v[4:7], v[212:215], v[142:145], v[4:7]
	s_mov_b32 m0, s27
	v_lshl_add_u64 v[8:9], v[8:9], 0, s[20:21]
	s_barrier
	ds_read_b128 v[114:117], v12 offset:49152
	ds_read_b128 v[138:141], v12 offset:50176
	ds_read_b128 v[142:145], v12 offset:51200
	ds_read_b128 v[170:173], v12 offset:52224
	ds_read_b128 v[174:177], v12 offset:53248
	ds_read_b128 v[178:181], v12 offset:54272
	ds_read_b128 v[182:185], v12 offset:55296
	ds_read_b128 v[186:189], v12 offset:56320
	global_load_lds_dwordx4 v[8:9], off
	v_lshl_add_u64 v[8:9], v[10:11], 0, s[20:21]
	s_mov_b32 m0, s28
	s_nop 0
	global_load_lds_dwordx4 v[8:9], off
	s_barrier
	s_waitcnt lgkmcnt(0)
	s_waitcnt lgkmcnt(0)
	v_mfma_f32_16x16x32_bf16 v[8:11], v[122:125], v[114:117], v[146:149]
	v_mfma_f32_16x16x32_bf16 v[146:149], v[130:133], v[114:117], v[150:153]
	v_mfma_f32_16x16x32_bf16 v[150:153], v[122:125], v[142:145], v[154:157]
	v_mfma_f32_16x16x32_bf16 v[154:157], v[130:133], v[142:145], v[158:161]
	v_mfma_f32_16x16x32_bf16 v[158:161], v[122:125], v[174:177], v[162:165]
	v_mfma_f32_16x16x32_bf16 v[162:165], v[130:133], v[174:177], v[166:169]
	v_mfma_f32_16x16x32_bf16 v[22:25], v[130:133], v[182:185], v[22:25]
	v_mfma_f32_16x16x32_bf16 v[8:11], v[126:129], v[138:141], v[8:11]
	v_mfma_f32_16x16x32_bf16 v[146:149], v[134:137], v[138:141], v[146:149]
	v_mfma_f32_16x16x32_bf16 v[150:153], v[126:129], v[170:173], v[150:153]
	v_mfma_f32_16x16x32_bf16 v[154:157], v[134:137], v[170:173], v[154:157]
	v_mfma_f32_16x16x32_bf16 v[158:161], v[126:129], v[178:181], v[158:161]
	v_mfma_f32_16x16x32_bf16 v[162:165], v[134:137], v[178:181], v[162:165]
	v_mfma_f32_16x16x32_bf16 v[18:21], v[122:125], v[182:185], v[18:21]
	v_mfma_f32_16x16x32_bf16 v[22:25], v[134:137], v[186:189], v[22:25]
	v_mfma_f32_16x16x32_bf16 v[18:21], v[126:129], v[186:189], v[18:21]
	s_barrier
	s_add_u32 s18, s18, 0x18280
	s_addc_u32 s19, s19, 0
	s_mov_b32 m0, s52
	s_nop 0
	global_load_lds_dwordx4 v0, s[18:19]
	s_mov_b32 m0, s60
	s_nop 0
	global_load_lds_dwordx4 v2, s[18:19]
	s_waitcnt vmcnt(6)
	s_barrier
	v_mfma_f32_16x16x32_bf16 v[26:29], v[208:211], v[114:117], v[26:29]
	v_mfma_f32_16x16x32_bf16 v[30:33], v[216:219], v[114:117], v[30:33]
	v_mfma_f32_16x16x32_bf16 v[58:61], v[208:211], v[142:145], v[58:61]
	v_mfma_f32_16x16x32_bf16 v[102:105], v[216:219], v[142:145], v[102:105]
	v_mfma_f32_16x16x32_bf16 v[106:109], v[208:211], v[174:177], v[106:109]
	v_mfma_f32_16x16x32_bf16 v[114:117], v[216:219], v[174:177], v[118:121]
	v_mfma_f32_16x16x32_bf16 v[94:97], v[208:211], v[182:185], v[94:97]
	v_mfma_f32_16x16x32_bf16 v[98:101], v[216:219], v[182:185], v[98:101]
	v_mfma_f32_16x16x32_bf16 v[26:29], v[212:215], v[138:141], v[26:29]
	v_mfma_f32_16x16x32_bf16 v[30:33], v[220:223], v[138:141], v[30:33]
	v_mfma_f32_16x16x32_bf16 v[58:61], v[212:215], v[170:173], v[58:61]
	v_mfma_f32_16x16x32_bf16 v[102:105], v[220:223], v[170:173], v[102:105]
	v_mfma_f32_16x16x32_bf16 v[106:109], v[212:215], v[178:181], v[106:109]
	v_mfma_f32_16x16x32_bf16 v[114:117], v[220:223], v[178:181], v[114:117]
	v_mfma_f32_16x16x32_bf16 v[94:97], v[212:215], v[186:189], v[94:97]
	v_mfma_f32_16x16x32_bf16 v[98:101], v[220:223], v[186:189], v[98:101]
	s_barrier
	ds_read_b128 v[118:121], v16
	ds_read_b128 v[122:125], v16 offset:1024
	ds_read_b128 v[126:129], v16 offset:2048
	ds_read_b128 v[130:133], v16 offset:3072
	s_add_u32 s4, s4, 0x18280
	s_addc_u32 s5, s5, 0
	s_mov_b32 m0, s35
	ds_read_b128 v[134:137], v12
	ds_read_b128 v[138:141], v12 offset:1024
	ds_read_b128 v[142:145], v12 offset:2048
	ds_read_b128 v[166:169], v12 offset:3072
	ds_read_b128 v[170:173], v12 offset:4096
	ds_read_b128 v[174:177], v12 offset:5120
	ds_read_b128 v[178:181], v12 offset:6144
	ds_read_b128 v[182:185], v12 offset:7168
	global_load_lds_dwordx4 v0, s[4:5]
	s_mov_b32 m0, s36
	s_nop 0
	global_load_lds_dwordx4 v2, s[4:5]
	s_waitcnt lgkmcnt(8)
	s_barrier
	s_waitcnt lgkmcnt(0)
	s_waitcnt lgkmcnt(0)
	v_mfma_f32_16x16x32_bf16 v[62:65], v[118:121], v[134:137], v[62:65]
	v_mfma_f32_16x16x32_bf16 v[66:69], v[126:129], v[134:137], v[66:69]
	v_mfma_f32_16x16x32_bf16 v[74:77], v[126:129], v[142:145], v[74:77]
	v_mfma_f32_16x16x32_bf16 v[86:89], v[118:121], v[178:181], v[86:89]
	v_mfma_f32_16x16x32_bf16 v[90:93], v[126:129], v[178:181], v[90:93]
	v_mfma_f32_16x16x32_bf16 v[62:65], v[122:125], v[138:141], v[62:65]
	v_mfma_f32_16x16x32_bf16 v[66:69], v[130:133], v[138:141], v[66:69]
	v_mfma_f32_16x16x32_bf16 v[70:73], v[118:121], v[142:145], v[70:73]
	v_mfma_f32_16x16x32_bf16 v[74:77], v[130:133], v[166:169], v[74:77]
	v_mfma_f32_16x16x32_bf16 v[78:81], v[118:121], v[170:173], v[78:81]
	v_mfma_f32_16x16x32_bf16 v[82:85], v[126:129], v[170:173], v[82:85]
	v_mfma_f32_16x16x32_bf16 v[86:89], v[122:125], v[182:185], v[86:89]
	v_mfma_f32_16x16x32_bf16 v[90:93], v[130:133], v[182:185], v[90:93]
	v_mfma_f32_16x16x32_bf16 v[70:73], v[122:125], v[166:169], v[70:73]
	v_mfma_f32_16x16x32_bf16 v[78:81], v[122:125], v[174:177], v[78:81]
	v_mfma_f32_16x16x32_bf16 v[82:85], v[130:133], v[174:177], v[82:85]
	s_barrier
	s_mov_b32 m0, s37
	ds_read_b128 v[186:189], v15
	ds_read_b128 v[204:207], v15 offset:1024
	ds_read_b128 v[208:211], v15 offset:2048
	ds_read_b128 v[212:215], v15 offset:3072
	global_load_lds_dwordx4 v0, s[12:13]
	s_mov_b32 m0, s38
	v_lshl_add_u64 v[196:197], s[12:13], 0, v[0:1]
	global_load_lds_dwordx4 v2, s[12:13]
	s_barrier
	s_waitcnt lgkmcnt(0)
	v_lshl_add_u64 v[198:199], s[12:13], 0, v[2:3]
	s_waitcnt lgkmcnt(0)
	v_mfma_f32_16x16x32_bf16 v[34:37], v[208:211], v[134:137], v[34:37]
	v_mfma_f32_16x16x32_bf16 v[110:113], v[186:189], v[142:145], v[110:113]
	v_mfma_f32_16x16x32_bf16 v[38:41], v[208:211], v[142:145], v[38:41]
	v_mfma_f32_16x16x32_bf16 v[42:45], v[186:189], v[170:173], v[42:45]
	v_mfma_f32_16x16x32_bf16 v[46:49], v[208:211], v[170:173], v[46:49]
	v_mfma_f32_16x16x32_bf16 v[50:53], v[186:189], v[178:181], v[50:53]
	v_mfma_f32_16x16x32_bf16 v[54:57], v[208:211], v[178:181], v[54:57]
	v_mfma_f32_16x16x32_bf16 v[4:7], v[186:189], v[134:137], v[4:7]
	v_mfma_f32_16x16x32_bf16 v[34:37], v[212:215], v[138:141], v[34:37]
	v_mfma_f32_16x16x32_bf16 v[110:113], v[204:207], v[166:169], v[110:113]
	v_mfma_f32_16x16x32_bf16 v[38:41], v[212:215], v[166:169], v[38:41]
	v_mfma_f32_16x16x32_bf16 v[42:45], v[204:207], v[174:177], v[42:45]
	v_mfma_f32_16x16x32_bf16 v[46:49], v[212:215], v[174:177], v[46:49]
	v_mfma_f32_16x16x32_bf16 v[50:53], v[204:207], v[182:185], v[50:53]
	v_mfma_f32_16x16x32_bf16 v[54:57], v[212:215], v[182:185], v[54:57]
	v_mfma_f32_16x16x32_bf16 v[4:7], v[204:207], v[138:141], v[4:7]
	s_mov_b32 m0, s63
	s_barrier
	ds_read_b128 v[134:137], v12 offset:16384
	ds_read_b128 v[138:141], v12 offset:17408
	ds_read_b128 v[142:145], v12 offset:18432
	ds_read_b128 v[166:169], v12 offset:19456
	ds_read_b128 v[170:173], v12 offset:20480
	ds_read_b128 v[174:177], v12 offset:21504
	ds_read_b128 v[178:181], v12 offset:22528
	ds_read_b128 v[182:185], v12 offset:23552
	global_load_lds_dwordx4 v0, s[10:11]
	s_mov_b32 m0, s24
	v_lshl_add_u64 v[248:249], s[10:11], 0, v[0:1]
	global_load_lds_dwordx4 v2, s[10:11]
	s_barrier
	s_waitcnt lgkmcnt(0)
	v_lshl_add_u64 v[190:191], s[10:11], 0, v[2:3]
	s_waitcnt lgkmcnt(0)
	v_mfma_f32_16x16x32_bf16 v[146:149], v[126:129], v[134:137], v[146:149]
	v_mfma_f32_16x16x32_bf16 v[216:219], v[130:133], v[138:141], v[146:149]
	v_mfma_f32_16x16x32_bf16 v[146:149], v[118:121], v[142:145], v[150:153]
	v_mfma_f32_16x16x32_bf16 v[220:223], v[122:125], v[166:169], v[146:149]
	v_mfma_f32_16x16x32_bf16 v[146:149], v[126:129], v[142:145], v[154:157]
	v_mfma_f32_16x16x32_bf16 v[8:11], v[118:121], v[134:137], v[8:11]
	v_mfma_f32_16x16x32_bf16 v[224:227], v[130:133], v[166:169], v[146:149]
	v_mfma_f32_16x16x32_bf16 v[146:149], v[118:121], v[170:173], v[158:161]
	v_mfma_f32_16x16x32_bf16 v[16:19], v[118:121], v[178:181], v[18:21]
	v_mfma_f32_16x16x32_bf16 v[20:23], v[126:129], v[178:181], v[22:25]
	v_mfma_f32_16x16x32_bf16 v[8:11], v[122:125], v[138:141], v[8:11]
	v_mfma_f32_16x16x32_bf16 v[228:231], v[122:125], v[174:177], v[146:149]
	v_mfma_f32_16x16x32_bf16 v[146:149], v[126:129], v[170:173], v[162:165]
	v_mfma_f32_16x16x32_bf16 v[20:23], v[130:133], v[182:185], v[20:23]
	v_mfma_f32_16x16x32_bf16 v[232:235], v[130:133], v[174:177], v[146:149]
	v_mfma_f32_16x16x32_bf16 v[16:19], v[122:125], v[182:185], v[16:19]
	s_barrier
	s_add_u32 s4, s12, 0x18000
	s_addc_u32 s5, s13, 0
	s_mov_b32 m0, s39
	s_nop 0
	global_load_lds_dwordx4 v0, s[4:5]
	s_mov_b32 m0, s43
	s_nop 0
	global_load_lds_dwordx4 v2, s[4:5]
	s_waitcnt vmcnt(6)
	s_barrier
	v_mfma_f32_16x16x32_bf16 v[24:27], v[186:189], v[134:137], v[26:29]
	v_mfma_f32_16x16x32_bf16 v[28:31], v[208:211], v[134:137], v[30:33]
	v_mfma_f32_16x16x32_bf16 v[236:239], v[212:215], v[138:141], v[28:31]
	v_mfma_f32_16x16x32_bf16 v[28:31], v[186:189], v[142:145], v[58:61]
	v_mfma_f32_16x16x32_bf16 v[58:61], v[204:207], v[166:169], v[28:31]
	v_mfma_f32_16x16x32_bf16 v[28:31], v[208:211], v[142:145], v[102:105]
	v_mfma_f32_16x16x32_bf16 v[240:243], v[212:215], v[166:169], v[28:31]
	v_mfma_f32_16x16x32_bf16 v[28:31], v[186:189], v[170:173], v[106:109]
	v_mfma_f32_16x16x32_bf16 v[244:247], v[204:207], v[174:177], v[28:31]
	v_mfma_f32_16x16x32_bf16 v[28:31], v[208:211], v[170:173], v[114:117]
	v_mfma_f32_16x16x32_bf16 v[174:177], v[212:215], v[174:177], v[28:31]
	v_mfma_f32_16x16x32_bf16 v[28:31], v[186:189], v[178:181], v[94:97]
	v_mfma_f32_16x16x32_bf16 v[186:189], v[204:207], v[182:185], v[28:31]
	v_mfma_f32_16x16x32_bf16 v[28:31], v[208:211], v[178:181], v[98:101]
	v_mfma_f32_16x16x32_bf16 v[24:27], v[204:207], v[138:141], v[24:27]
	v_mfma_f32_16x16x32_bf16 v[178:181], v[212:215], v[182:185], v[28:31]
	s_barrier
	s_nop 3
	ds_read_b128 v[28:31], v14
	ds_read_b128 v[94:97], v14 offset:1024
	ds_read_b128 v[98:101], v14 offset:2048
	ds_read_b128 v[182:185], v14 offset:3072
	s_add_u32 s4, s10, 0x18000
	s_addc_u32 s5, s11, 0
	s_mov_b32 m0, s25
	ds_read_b128 v[102:105], v12 offset:32768
	ds_read_b128 v[106:109], v12 offset:33792
	ds_read_b128 v[114:117], v12 offset:34816
	ds_read_b128 v[126:129], v12 offset:35840
	ds_read_b128 v[204:207], v12 offset:36864
	ds_read_b128 v[208:211], v12 offset:37888
	ds_read_b128 v[212:215], v12 offset:38912
	ds_read_b128 v[192:195], v12 offset:39936
	global_load_lds_dwordx4 v0, s[4:5]
	s_mov_b32 m0, s26
	s_nop 0
	global_load_lds_dwordx4 v2, s[4:5]
	s_waitcnt lgkmcnt(8)
	s_barrier
	s_waitcnt lgkmcnt(0)
	s_waitcnt lgkmcnt(0)
	v_mfma_f32_16x16x32_bf16 v[62:65], v[28:31], v[102:105], v[62:65]
	v_mfma_f32_16x16x32_bf16 v[170:173], v[94:97], v[106:109], v[62:65]
	v_mfma_f32_16x16x32_bf16 v[62:65], v[98:101], v[102:105], v[66:69]
	v_mfma_f32_16x16x32_bf16 v[166:169], v[182:185], v[106:109], v[62:65]
	v_mfma_f32_16x16x32_bf16 v[62:65], v[28:31], v[114:117], v[70:73]
	v_mfma_f32_16x16x32_bf16 v[154:157], v[94:97], v[126:129], v[62:65]
	v_mfma_f32_16x16x32_bf16 v[62:65], v[98:101], v[114:117], v[74:77]
	v_mfma_f32_16x16x32_bf16 v[150:153], v[182:185], v[126:129], v[62:65]
	v_mfma_f32_16x16x32_bf16 v[62:65], v[28:31], v[204:207], v[78:81]
	v_mfma_f32_16x16x32_bf16 v[138:141], v[94:97], v[208:211], v[62:65]
	v_mfma_f32_16x16x32_bf16 v[62:65], v[98:101], v[204:207], v[82:85]
	v_mfma_f32_16x16x32_bf16 v[134:137], v[182:185], v[208:211], v[62:65]
	v_mfma_f32_16x16x32_bf16 v[62:65], v[28:31], v[212:215], v[86:89]
	v_mfma_f32_16x16x32_bf16 v[122:125], v[94:97], v[192:195], v[62:65]
	v_mfma_f32_16x16x32_bf16 v[62:65], v[98:101], v[212:215], v[90:93]
	v_mfma_f32_16x16x32_bf16 v[118:121], v[182:185], v[192:195], v[62:65]
	s_barrier
	s_mov_b32 m0, s46
	v_lshl_add_u64 v[14:15], v[196:197], 0, s[70:71]
	ds_read_b128 v[70:73], v13
	ds_read_b128 v[74:77], v13 offset:1024
	ds_read_b128 v[78:81], v13 offset:2048
	ds_read_b128 v[82:85], v13 offset:3072
	global_load_lds_dwordx4 v[14:15], off
	v_lshl_add_u64 v[14:15], v[198:199], 0, s[70:71]
	s_mov_b32 m0, s47
	s_nop 0
	global_load_lds_dwordx4 v[14:15], off
	s_barrier
	s_waitcnt lgkmcnt(0)
	s_waitcnt lgkmcnt(0)
	v_mfma_f32_16x16x32_bf16 v[4:7], v[70:73], v[102:105], v[4:7]
	v_mfma_f32_16x16x32_bf16 v[162:165], v[74:77], v[106:109], v[4:7]
	v_mfma_f32_16x16x32_bf16 v[4:7], v[78:81], v[102:105], v[34:37]
	v_mfma_f32_16x16x32_bf16 v[158:161], v[82:85], v[106:109], v[4:7]
	v_mfma_f32_16x16x32_bf16 v[4:7], v[70:73], v[114:117], v[110:113]
	v_mfma_f32_16x16x32_bf16 v[146:149], v[74:77], v[126:129], v[4:7]
	v_mfma_f32_16x16x32_bf16 v[4:7], v[78:81], v[114:117], v[38:41]
	v_mfma_f32_16x16x32_bf16 v[142:145], v[82:85], v[126:129], v[4:7]
	v_mfma_f32_16x16x32_bf16 v[4:7], v[70:73], v[204:207], v[42:45]
	v_mfma_f32_16x16x32_bf16 v[130:133], v[74:77], v[208:211], v[4:7]
	v_mfma_f32_16x16x32_bf16 v[4:7], v[78:81], v[204:207], v[46:49]
	v_mfma_f32_16x16x32_bf16 v[126:129], v[82:85], v[208:211], v[4:7]
	v_mfma_f32_16x16x32_bf16 v[4:7], v[70:73], v[212:215], v[50:53]
	v_mfma_f32_16x16x32_bf16 v[114:117], v[74:77], v[192:195], v[4:7]
	v_mfma_f32_16x16x32_bf16 v[4:7], v[78:81], v[212:215], v[54:57]
	v_mfma_f32_16x16x32_bf16 v[110:113], v[82:85], v[192:195], v[4:7]
	s_mov_b32 m0, s27
	v_lshl_add_u64 v[32:33], v[248:249], 0, s[70:71]
	s_barrier
	s_nop 2
	ds_read_b128 v[4:7], v12 offset:49152
	ds_read_b128 v[38:41], v12 offset:50176
	ds_read_b128 v[42:45], v12 offset:51200
	ds_read_b128 v[46:49], v12 offset:52224
	ds_read_b128 v[50:53], v12 offset:53248
	ds_read_b128 v[54:57], v12 offset:54272
	ds_read_b128 v[210:213], v12 offset:55296
	ds_read_b128 v[12:15], v12 offset:56320
	global_load_lds_dwordx4 v[32:33], off
	v_lshl_add_u64 v[32:33], v[190:191], 0, s[70:71]
	s_mov_b32 m0, s28
	s_nop 0
	global_load_lds_dwordx4 v[32:33], off
	s_barrier
	s_waitcnt lgkmcnt(0)
	s_waitcnt lgkmcnt(0)
	v_mfma_f32_16x16x32_bf16 v[8:11], v[28:31], v[4:7], v[8:11]
	v_mfma_f32_16x16x32_bf16 v[106:109], v[94:97], v[38:41], v[8:11]
	v_mfma_f32_16x16x32_bf16 v[8:11], v[98:101], v[4:7], v[216:219]
	v_mfma_f32_16x16x32_bf16 v[102:105], v[182:185], v[38:41], v[8:11]
	v_mfma_f32_16x16x32_bf16 v[8:11], v[28:31], v[42:45], v[220:223]
	v_mfma_f32_16x16x32_bf16 v[90:93], v[94:97], v[46:49], v[8:11]
	v_mfma_f32_16x16x32_bf16 v[8:11], v[98:101], v[42:45], v[224:227]
	v_mfma_f32_16x16x32_bf16 v[86:89], v[182:185], v[46:49], v[8:11]
	v_mfma_f32_16x16x32_bf16 v[8:11], v[28:31], v[50:53], v[228:231]
	v_mfma_f32_16x16x32_bf16 v[66:69], v[94:97], v[54:57], v[8:11]
	v_mfma_f32_16x16x32_bf16 v[8:11], v[98:101], v[50:53], v[232:235]
	v_mfma_f32_16x16x32_bf16 v[62:65], v[182:185], v[54:57], v[8:11]
	v_mfma_f32_16x16x32_bf16 v[8:11], v[28:31], v[210:213], v[16:19]
	v_mfma_f32_16x16x32_bf16 v[34:37], v[94:97], v[12:15], v[8:11]
	v_mfma_f32_16x16x32_bf16 v[8:11], v[98:101], v[210:213], v[20:23]
	v_mfma_f32_16x16x32_bf16 v[30:33], v[182:185], v[12:15], v[8:11]
	s_barrier
	s_add_u32 s4, s12, 0x18080
	s_addc_u32 s5, s13, 0
	s_mov_b32 m0, s52
	s_nop 0
	global_load_lds_dwordx4 v0, s[4:5]
	s_mov_b32 m0, s60
	s_nop 0
	global_load_lds_dwordx4 v2, s[4:5]
	s_waitcnt vmcnt(6)
	s_barrier
	v_mfma_f32_16x16x32_bf16 v[8:11], v[70:73], v[4:7], v[24:27]
	v_mfma_f32_16x16x32_bf16 v[2:5], v[78:81], v[4:7], v[236:239]
	v_mfma_f32_16x16x32_bf16 v[94:97], v[82:85], v[38:41], v[2:5]
	v_mfma_f32_16x16x32_bf16 v[2:5], v[70:73], v[42:45], v[58:61]
	v_mfma_f32_16x16x32_bf16 v[206:209], v[74:77], v[46:49], v[2:5]
	v_mfma_f32_16x16x32_bf16 v[2:5], v[78:81], v[42:45], v[240:243]
	v_mfma_f32_16x16x32_bf16 v[192:195], v[82:85], v[46:49], v[2:5]
	v_mfma_f32_16x16x32_bf16 v[2:5], v[70:73], v[50:53], v[244:247]
	v_mfma_f32_16x16x32_bf16 v[58:61], v[74:77], v[54:57], v[2:5]
	v_mfma_f32_16x16x32_bf16 v[2:5], v[78:81], v[50:53], v[174:177]
	v_mfma_f32_16x16x32_bf16 v[54:57], v[82:85], v[54:57], v[2:5]
	v_mfma_f32_16x16x32_bf16 v[2:5], v[70:73], v[210:213], v[186:189]
	v_mfma_f32_16x16x32_bf16 v[26:29], v[74:77], v[12:15], v[2:5]
	v_mfma_f32_16x16x32_bf16 v[2:5], v[78:81], v[210:213], v[178:181]
	v_mfma_f32_16x16x32_bf16 v[98:101], v[74:77], v[38:41], v[8:11]
	v_mfma_f32_16x16x32_bf16 v[22:25], v[82:85], v[12:15], v[2:5]
	s_mov_b32 s21, s49
	s_mov_b32 s20, s48
	s_barrier
	s_lshl_b32 s94, s17, 8
	v_readlane_b32 s95, v255, 15
	s_nop 0
	s_lshl_b32 s95, s95, 5
	s_add_i32 s95, s95, 0x20100
	v_mov_b32_e32 v200, s95
	v_mbcnt_lo_u32_b32 v187, -1, 0
	v_mbcnt_hi_u32_b32 v187, -1, v187
	s_add_u32 s18, s20, 0x14fa8000
	v_bfe_u32 v0, v187, 4, 2
	s_addc_u32 s19, s21, 0
	v_readlane_b32 s4, v255, 15
	s_add_u32 s22, s20, 0x14fe8800
	s_addc_u32 s23, s21, 0
	v_lshl_or_b32 v189, v0, 3, s4
	v_readlane_b32 s4, v255, 51
	s_mov_b32 s40, s51
	s_mov_b32 s41, s50
	v_lshl_or_b32 v188, v0, 2, s4
	s_lshl_b32 s4, s17, 8
	s_add_i32 s4, s4, s42
	v_and_or_b32 v174, v187, 15, s4
	v_ashrrev_i32_e32 v175, 31, v174
	v_lshl_add_u64 v[2:3], v[174:175], 2, s[20:21]
	s_mov_b64 s[4:5], 0x15049800
	v_lshl_add_u64 v[4:5], v[2:3], 0, s[4:5]
	s_mov_b32 s4, 0x15049000
	v_add_co_u32_e32 v2, vcc, s4, v2
	v_lshlrev_b32_e32 v0, 2, v189
	s_nop 0
	v_addc_co_u32_e32 v3, vcc, 0, v3, vcc
	global_load_dword v204, v[2:3], off offset:2048
	global_load_dword v186, v[4:5], off offset:64
	global_load_dword v184, v[4:5], off offset:128
	global_load_dword v183, v[4:5], off offset:192
	global_load_dword v182, v[4:5], off offset:512
	global_load_dword v181, v[4:5], off offset:576
	global_load_dword v180, v[4:5], off offset:640
	global_load_dword v175, v[4:5], off offset:704
	global_load_dwordx4 v[46:49], v0, s[8:9] offset:16
	global_load_dwordx4 v[50:53], v0, s[8:9]
	v_lshlrev_b32_e32 v0, 2, v188
	global_load_dwordx4 v[42:45], v0, s[8:9] offset:512
	global_load_dwordx4 v[38:41], v0, s[8:9] offset:640
	v_readlane_b32 s90, v255, 8
	v_readlane_b32 s91, v255, 9
	v_mov_b32_e32 v10, 0
	s_andn2_b64 vcc, exec, s[90:91]
	v_cndmask_b32_e64 v2, 0, 1, s[90:91]
	v_cmp_ne_u32_e64 s[4:5], 1, v2
	v_mov_b32_e32 v11, 0
	v_mov_b32_e32 v12, 0
	v_mov_b32_e32 v13, 0
	s_cbranch_vccnz .LBB0_563
	v_mul_hi_i32 v2, v174, s59
	v_lshrrev_b32_e32 v3, 31, v2
	v_ashrrev_i32_e32 v2, 7, v2
	v_add_u32_e32 v2, v2, v3
	v_mul_lo_u32 v2, v2, s33
	v_sub_u32_e32 v2, v174, v2
	v_lshlrev_b32_e32 v2, 5, v2
	v_ashrrev_i32_e32 v3, 31, v2
	v_lshlrev_b64 v[2:3], 2, v[2:3]
	v_lshl_add_u64 v[4:5], s[18:19], 0, v[2:3]
	v_lshl_add_u64 v[4:5], v[4:5], 0, v[0:1]
	v_lshl_add_u64 v[2:3], s[22:23], 0, v[2:3]
	v_lshl_add_u64 v[2:3], v[2:3], 0, v[0:1]
	global_load_dwordx4 v[10:13], v[4:5], off
	global_load_dwordx4 v[74:77], v[2:3], off

.LBB0_625:
	v_readlane_b32 s19, v252, 51
	v_or_b32_e32 v3, s62, v4
	s_nop 0
	v_or_b32_e32 v5, s19, v4
	v_add_u32_e32 v200, s29, v5
	ds_read_b128 v[6:9], v200
	ds_read_b128 v[10:13], v200 offset:1024
	ds_read_b128 v[14:17], v200 offset:2048
	ds_read_b128 v[18:21], v200 offset:3072
	v_add_u32_e32 v4, 0, v3
	v_add_u32_e32 v201, s30, v5
	v_add_u32_e32 v202, s31, v5
	v_add_u32_e32 v5, s34, v5
	s_add_u32 s20, s4, 0x10080
	s_mov_b32 m0, s35
	s_addc_u32 s21, s5, 0
	ds_read_b128 v[22:25], v4
	ds_read_b128 v[26:29], v4 offset:1024
	ds_read_b128 v[30:33], v4 offset:2048
	ds_read_b128 v[34:37], v4 offset:3072
	ds_read_b128 v[38:41], v4 offset:4096
	ds_read_b128 v[42:45], v4 offset:5120
	ds_read_b128 v[46:49], v4 offset:6144
	ds_read_b128 v[50:53], v4 offset:7168
	global_load_lds_dwordx4 v0, s[20:21]
	s_mov_b32 m0, s36
	v_mov_b32_e32 v3, v1
	global_load_lds_dwordx4 v2, s[20:21]
	s_waitcnt lgkmcnt(8)
	s_barrier
	s_waitcnt lgkmcnt(0)
	s_waitcnt lgkmcnt(0)
	v_mfma_f32_16x16x32_bf16 v[54:57], v[6:9], v[22:25], 0
	v_mfma_f32_16x16x32_bf16 v[58:61], v[14:17], v[22:25], 0
	v_mfma_f32_16x16x32_bf16 v[62:65], v[6:9], v[30:33], 0
	v_mfma_f32_16x16x32_bf16 v[66:69], v[14:17], v[30:33], 0
	s_waitcnt vmcnt(0)
	v_mfma_f32_16x16x32_bf16 v[70:73], v[6:9], v[38:41], 0
	v_mfma_f32_16x16x32_bf16 v[74:77], v[14:17], v[38:41], 0
	v_mfma_f32_16x16x32_bf16 v[78:81], v[6:9], v[46:49], 0
	v_mfma_f32_16x16x32_bf16 v[82:85], v[14:17], v[46:49], 0
	v_mfma_f32_16x16x32_bf16 v[54:57], v[10:13], v[26:29], v[54:57]
	v_mfma_f32_16x16x32_bf16 v[58:61], v[18:21], v[26:29], v[58:61]
	v_mfma_f32_16x16x32_bf16 v[62:65], v[10:13], v[34:37], v[62:65]
	v_mfma_f32_16x16x32_bf16 v[66:69], v[18:21], v[34:37], v[66:69]
	v_mfma_f32_16x16x32_bf16 v[70:73], v[10:13], v[42:45], v[70:73]
	v_mfma_f32_16x16x32_bf16 v[74:77], v[18:21], v[42:45], v[74:77]
	v_mfma_f32_16x16x32_bf16 v[78:81], v[10:13], v[50:53], v[78:81]
	v_mfma_f32_16x16x32_bf16 v[82:85], v[18:21], v[50:53], v[82:85]
	s_barrier
	v_lshl_add_u64 v[190:191], s[16:17], 0, v[0:1]
	s_mov_b32 m0, s37
	v_lshl_add_u64 v[102:103], v[190:191], 0, s[76:77]
	v_lshl_add_u64 v[196:197], s[16:17], 0, v[2:3]
	ds_read_b128 v[86:89], v201
	ds_read_b128 v[90:93], v201 offset:1024
	ds_read_b128 v[94:97], v201 offset:2048
	ds_read_b128 v[98:101], v201 offset:3072
	global_load_lds_dwordx4 v[102:103], off
	v_lshl_add_u64 v[102:103], v[196:197], 0, s[76:77]
	s_mov_b32 m0, s38
	s_nop 0
	global_load_lds_dwordx4 v[102:103], off
	s_barrier
	s_waitcnt lgkmcnt(0)
	s_waitcnt lgkmcnt(0)
	v_mfma_f32_16x16x32_bf16 v[102:105], v[86:89], v[22:25], 0
	v_mfma_f32_16x16x32_bf16 v[22:25], v[94:97], v[22:25], 0
	v_mfma_f32_16x16x32_bf16 v[102:105], v[90:93], v[26:29], v[102:105]
	v_mfma_f32_16x16x32_bf16 v[22:25], v[98:101], v[26:29], v[22:25]
	v_mfma_f32_16x16x32_bf16 v[26:29], v[86:89], v[30:33], 0
	v_mfma_f32_16x16x32_bf16 v[30:33], v[94:97], v[30:33], 0
	v_mfma_f32_16x16x32_bf16 v[26:29], v[90:93], v[34:37], v[26:29]
	v_mfma_f32_16x16x32_bf16 v[30:33], v[98:101], v[34:37], v[30:33]
	v_mfma_f32_16x16x32_bf16 v[34:37], v[86:89], v[38:41], 0
	v_mfma_f32_16x16x32_bf16 v[38:41], v[94:97], v[38:41], 0
	v_mfma_f32_16x16x32_bf16 v[34:37], v[90:93], v[42:45], v[34:37]
	v_mfma_f32_16x16x32_bf16 v[38:41], v[98:101], v[42:45], v[38:41]
	v_mfma_f32_16x16x32_bf16 v[42:45], v[86:89], v[46:49], 0
	v_mfma_f32_16x16x32_bf16 v[46:49], v[94:97], v[46:49], 0
	v_mfma_f32_16x16x32_bf16 v[42:45], v[90:93], v[50:53], v[42:45]
	v_mfma_f32_16x16x32_bf16 v[46:49], v[98:101], v[50:53], v[46:49]
	v_lshl_add_u64 v[198:199], s[4:5], 0, v[0:1]
	s_mov_b32 m0, s63
	v_lshl_add_u64 v[134:135], v[198:199], 0, s[76:77]
	v_lshl_add_u64 v[208:209], s[4:5], 0, v[2:3]
	s_barrier
	ds_read_b128 v[50:53], v4 offset:16384
	ds_read_b128 v[106:109], v4 offset:17408
	ds_read_b128 v[110:113], v4 offset:18432
	ds_read_b128 v[114:117], v4 offset:19456
	ds_read_b128 v[118:121], v4 offset:20480
	ds_read_b128 v[122:125], v4 offset:21504
	ds_read_b128 v[126:129], v4 offset:22528
	ds_read_b128 v[130:133], v4 offset:23552
	global_load_lds_dwordx4 v[134:135], off
	v_lshl_add_u64 v[134:135], v[208:209], 0, s[76:77]
	s_mov_b32 m0, s24
	s_nop 0
	global_load_lds_dwordx4 v[134:135], off
	s_barrier
	s_waitcnt lgkmcnt(0)
	s_waitcnt lgkmcnt(0)
	v_mfma_f32_16x16x32_bf16 v[134:137], v[6:9], v[50:53], 0
	v_mfma_f32_16x16x32_bf16 v[142:145], v[6:9], v[110:113], 0
	v_mfma_f32_16x16x32_bf16 v[150:153], v[6:9], v[118:121], 0
	v_mfma_f32_16x16x32_bf16 v[6:9], v[6:9], v[126:129], 0
	v_mfma_f32_16x16x32_bf16 v[134:137], v[10:13], v[106:109], v[134:137]
	v_mfma_f32_16x16x32_bf16 v[142:145], v[10:13], v[114:117], v[142:145]
	v_mfma_f32_16x16x32_bf16 v[150:153], v[10:13], v[122:125], v[150:153]
	v_mfma_f32_16x16x32_bf16 v[6:9], v[10:13], v[130:133], v[6:9]
	v_mfma_f32_16x16x32_bf16 v[10:13], v[14:17], v[126:129], 0
	v_mfma_f32_16x16x32_bf16 v[138:141], v[14:17], v[50:53], 0
	v_mfma_f32_16x16x32_bf16 v[146:149], v[14:17], v[110:113], 0
	v_mfma_f32_16x16x32_bf16 v[154:157], v[14:17], v[118:121], 0
	v_mfma_f32_16x16x32_bf16 v[10:13], v[18:21], v[130:133], v[10:13]
	v_mfma_f32_16x16x32_bf16 v[138:141], v[18:21], v[106:109], v[138:141]
	v_mfma_f32_16x16x32_bf16 v[146:149], v[18:21], v[114:117], v[146:149]
	v_mfma_f32_16x16x32_bf16 v[154:157], v[18:21], v[122:125], v[154:157]
	s_barrier
	s_add_u32 s20, s16, 0x10100
	s_addc_u32 s21, s17, 0
	s_mov_b32 m0, s39
	s_nop 0
	global_load_lds_dwordx4 v0, s[20:21]
	s_mov_b32 m0, s43
	s_nop 0
	global_load_lds_dwordx4 v2, s[20:21]
	s_waitcnt vmcnt(6)
	s_barrier
	v_mfma_f32_16x16x32_bf16 v[14:17], v[86:89], v[50:53], 0
	v_mfma_f32_16x16x32_bf16 v[18:21], v[94:97], v[50:53], 0
	v_mfma_f32_16x16x32_bf16 v[14:17], v[90:93], v[106:109], v[14:17]
	v_mfma_f32_16x16x32_bf16 v[18:21], v[98:101], v[106:109], v[18:21]
	v_mfma_f32_16x16x32_bf16 v[50:53], v[86:89], v[110:113], 0
	v_mfma_f32_16x16x32_bf16 v[106:109], v[94:97], v[110:113], 0
	v_mfma_f32_16x16x32_bf16 v[110:113], v[86:89], v[118:121], 0
	v_mfma_f32_16x16x32_bf16 v[86:89], v[86:89], v[126:129], 0
	v_mfma_f32_16x16x32_bf16 v[50:53], v[90:93], v[114:117], v[50:53]
	v_mfma_f32_16x16x32_bf16 v[106:109], v[98:101], v[114:117], v[106:109]
	v_mfma_f32_16x16x32_bf16 v[110:113], v[90:93], v[122:125], v[110:113]
	v_mfma_f32_16x16x32_bf16 v[114:117], v[94:97], v[118:121], 0
	v_mfma_f32_16x16x32_bf16 v[86:89], v[90:93], v[130:133], v[86:89]
	v_mfma_f32_16x16x32_bf16 v[90:93], v[94:97], v[126:129], 0
	v_mfma_f32_16x16x32_bf16 v[114:117], v[98:101], v[122:125], v[114:117]
	v_mfma_f32_16x16x32_bf16 v[90:93], v[98:101], v[130:133], v[90:93]
	s_barrier
	ds_read_b128 v[94:97], v202
	ds_read_b128 v[98:101], v202 offset:1024
	ds_read_b128 v[118:121], v202 offset:2048
	ds_read_b128 v[122:125], v202 offset:3072
	s_add_u32 s20, s4, 0x10100
	s_addc_u32 s21, s5, 0
	s_mov_b32 m0, s25
	ds_read_b128 v[126:129], v4 offset:32768
	ds_read_b128 v[130:133], v4 offset:33792
	ds_read_b128 v[158:161], v4 offset:34816
	ds_read_b128 v[162:165], v4 offset:35840
	ds_read_b128 v[166:169], v4 offset:36864
	ds_read_b128 v[170:173], v4 offset:37888
	ds_read_b128 v[174:177], v4 offset:38912
	ds_read_b128 v[178:181], v4 offset:39936
	global_load_lds_dwordx4 v0, s[20:21]
	s_mov_b32 m0, s26
	s_nop 0
	global_load_lds_dwordx4 v2, s[20:21]
	s_waitcnt lgkmcnt(8)
	s_barrier
	s_waitcnt lgkmcnt(0)
	s_waitcnt lgkmcnt(0)
	v_mfma_f32_16x16x32_bf16 v[54:57], v[94:97], v[126:129], v[54:57]
	v_mfma_f32_16x16x32_bf16 v[58:61], v[118:121], v[126:129], v[58:61]
	v_mfma_f32_16x16x32_bf16 v[62:65], v[94:97], v[158:161], v[62:65]
	v_mfma_f32_16x16x32_bf16 v[66:69], v[118:121], v[158:161], v[66:69]
	v_mfma_f32_16x16x32_bf16 v[70:73], v[94:97], v[166:169], v[70:73]
	v_mfma_f32_16x16x32_bf16 v[74:77], v[118:121], v[166:169], v[74:77]
	v_mfma_f32_16x16x32_bf16 v[78:81], v[94:97], v[174:177], v[78:81]
	v_mfma_f32_16x16x32_bf16 v[82:85], v[118:121], v[174:177], v[82:85]
	v_mfma_f32_16x16x32_bf16 v[54:57], v[98:101], v[130:133], v[54:57]
	v_mfma_f32_16x16x32_bf16 v[58:61], v[122:125], v[130:133], v[58:61]
	v_mfma_f32_16x16x32_bf16 v[62:65], v[98:101], v[162:165], v[62:65]
	v_mfma_f32_16x16x32_bf16 v[66:69], v[122:125], v[162:165], v[66:69]
	v_mfma_f32_16x16x32_bf16 v[70:73], v[98:101], v[170:173], v[70:73]
	v_mfma_f32_16x16x32_bf16 v[74:77], v[122:125], v[170:173], v[74:77]
	v_mfma_f32_16x16x32_bf16 v[78:81], v[98:101], v[178:181], v[78:81]
	v_mfma_f32_16x16x32_bf16 v[82:85], v[122:125], v[178:181], v[82:85]
	s_barrier
	s_mov_b64 s[20:21], 0x180
	s_mov_b32 m0, s46
	v_lshl_add_u64 v[190:191], v[190:191], 0, s[20:21]
	ds_read_b128 v[182:185], v5
	ds_read_b128 v[186:189], v5 offset:1024
	ds_read_b128 v[192:195], v5 offset:2048
	ds_read_b128 v[204:207], v5 offset:3072
	global_load_lds_dwordx4 v[190:191], off
	v_lshl_add_u64 v[190:191], v[196:197], 0, s[20:21]
	s_mov_b32 m0, s47
	s_nop 0
	global_load_lds_dwordx4 v[190:191], off
	s_barrier
	s_waitcnt lgkmcnt(0)
	s_waitcnt lgkmcnt(0)
	v_mfma_f32_16x16x32_bf16 v[102:105], v[182:185], v[126:129], v[102:105]
	v_mfma_f32_16x16x32_bf16 v[22:25], v[192:195], v[126:129], v[22:25]
	v_mfma_f32_16x16x32_bf16 v[26:29], v[182:185], v[158:161], v[26:29]
	v_mfma_f32_16x16x32_bf16 v[30:33], v[192:195], v[158:161], v[30:33]
	v_mfma_f32_16x16x32_bf16 v[34:37], v[182:185], v[166:169], v[34:37]
	v_mfma_f32_16x16x32_bf16 v[38:41], v[192:195], v[166:169], v[38:41]
	v_mfma_f32_16x16x32_bf16 v[42:45], v[182:185], v[174:177], v[42:45]
	v_mfma_f32_16x16x32_bf16 v[46:49], v[192:195], v[174:177], v[46:49]
	v_mfma_f32_16x16x32_bf16 v[102:105], v[186:189], v[130:133], v[102:105]
	v_mfma_f32_16x16x32_bf16 v[22:25], v[204:207], v[130:133], v[22:25]
	v_mfma_f32_16x16x32_bf16 v[26:29], v[186:189], v[162:165], v[26:29]
	v_mfma_f32_16x16x32_bf16 v[30:33], v[204:207], v[162:165], v[30:33]
	v_mfma_f32_16x16x32_bf16 v[34:37], v[186:189], v[170:173], v[34:37]
	v_mfma_f32_16x16x32_bf16 v[38:41], v[204:207], v[170:173], v[38:41]
	v_mfma_f32_16x16x32_bf16 v[42:45], v[186:189], v[178:181], v[42:45]
	v_mfma_f32_16x16x32_bf16 v[46:49], v[204:207], v[178:181], v[46:49]
	s_mov_b32 m0, s27
	v_lshl_add_u64 v[190:191], v[198:199], 0, s[20:21]
	s_barrier
	ds_read_b128 v[126:129], v4 offset:49152
	ds_read_b128 v[130:133], v4 offset:50176
	ds_read_b128 v[158:161], v4 offset:51200
	ds_read_b128 v[162:165], v4 offset:52224
	ds_read_b128 v[166:169], v4 offset:53248
	ds_read_b128 v[170:173], v4 offset:54272
	ds_read_b128 v[174:177], v4 offset:55296
	ds_read_b128 v[178:181], v4 offset:56320
	global_load_lds_dwordx4 v[190:191], off
	v_lshl_add_u64 v[190:191], v[208:209], 0, s[20:21]
	s_mov_b32 m0, s28
	s_nop 0
	global_load_lds_dwordx4 v[190:191], off
	s_barrier
	s_waitcnt lgkmcnt(0)
	s_waitcnt lgkmcnt(0)
	v_mfma_f32_16x16x32_bf16 v[150:153], v[94:97], v[166:169], v[150:153]
	v_mfma_f32_16x16x32_bf16 v[6:9], v[94:97], v[174:177], v[6:9]
	v_mfma_f32_16x16x32_bf16 v[10:13], v[118:121], v[174:177], v[10:13]
	v_mfma_f32_16x16x32_bf16 v[134:137], v[94:97], v[126:129], v[134:137]
	v_mfma_f32_16x16x32_bf16 v[138:141], v[118:121], v[126:129], v[138:141]
	v_mfma_f32_16x16x32_bf16 v[142:145], v[94:97], v[158:161], v[142:145]
	v_mfma_f32_16x16x32_bf16 v[146:149], v[118:121], v[158:161], v[146:149]
	v_mfma_f32_16x16x32_bf16 v[150:153], v[98:101], v[170:173], v[150:153]
	v_mfma_f32_16x16x32_bf16 v[154:157], v[118:121], v[166:169], v[154:157]
	v_mfma_f32_16x16x32_bf16 v[6:9], v[98:101], v[178:181], v[6:9]
	v_mfma_f32_16x16x32_bf16 v[10:13], v[122:125], v[178:181], v[10:13]
	v_mfma_f32_16x16x32_bf16 v[134:137], v[98:101], v[130:133], v[134:137]
	v_mfma_f32_16x16x32_bf16 v[138:141], v[122:125], v[130:133], v[138:141]
	v_mfma_f32_16x16x32_bf16 v[142:145], v[98:101], v[162:165], v[142:145]
	v_mfma_f32_16x16x32_bf16 v[146:149], v[122:125], v[162:165], v[146:149]
	v_mfma_f32_16x16x32_bf16 v[154:157], v[122:125], v[170:173], v[154:157]
	s_barrier
	s_add_u32 s16, s16, 0x10180
	s_addc_u32 s17, s17, 0
	s_mov_b32 m0, s52
	s_nop 0
	global_load_lds_dwordx4 v0, s[16:17]
	s_mov_b32 m0, s60
	s_nop 0
	global_load_lds_dwordx4 v2, s[16:17]
	s_waitcnt vmcnt(6)
	s_barrier
	v_mfma_f32_16x16x32_bf16 v[14:17], v[182:185], v[126:129], v[14:17]
	v_mfma_f32_16x16x32_bf16 v[18:21], v[192:195], v[126:129], v[18:21]
	v_mfma_f32_16x16x32_bf16 v[50:53], v[182:185], v[158:161], v[50:53]
	v_mfma_f32_16x16x32_bf16 v[94:97], v[192:195], v[158:161], v[106:109]
	v_mfma_f32_16x16x32_bf16 v[98:101], v[182:185], v[166:169], v[110:113]
	v_mfma_f32_16x16x32_bf16 v[106:109], v[192:195], v[166:169], v[114:117]
	v_mfma_f32_16x16x32_bf16 v[86:89], v[182:185], v[174:177], v[86:89]
	v_mfma_f32_16x16x32_bf16 v[90:93], v[192:195], v[174:177], v[90:93]
	v_mfma_f32_16x16x32_bf16 v[14:17], v[186:189], v[130:133], v[14:17]
	v_mfma_f32_16x16x32_bf16 v[18:21], v[204:207], v[130:133], v[18:21]
	v_mfma_f32_16x16x32_bf16 v[50:53], v[186:189], v[162:165], v[50:53]
	v_mfma_f32_16x16x32_bf16 v[94:97], v[204:207], v[162:165], v[94:97]
	v_mfma_f32_16x16x32_bf16 v[98:101], v[186:189], v[170:173], v[98:101]
	v_mfma_f32_16x16x32_bf16 v[106:109], v[204:207], v[170:173], v[106:109]
	v_mfma_f32_16x16x32_bf16 v[86:89], v[186:189], v[178:181], v[86:89]
	v_mfma_f32_16x16x32_bf16 v[90:93], v[204:207], v[178:181], v[90:93]
	s_barrier
	ds_read_b128 v[110:113], v200
	ds_read_b128 v[114:117], v200 offset:1024
	ds_read_b128 v[118:121], v200 offset:2048
	ds_read_b128 v[122:125], v200 offset:3072
	s_add_u32 s4, s4, 0x10180
	s_addc_u32 s5, s5, 0
	s_mov_b32 m0, s35
	ds_read_b128 v[126:129], v4
	ds_read_b128 v[130:133], v4 offset:1024
	ds_read_b128 v[158:161], v4 offset:2048
	ds_read_b128 v[162:165], v4 offset:3072
	ds_read_b128 v[166:169], v4 offset:4096
	ds_read_b128 v[170:173], v4 offset:5120
	ds_read_b128 v[174:177], v4 offset:6144
	ds_read_b128 v[178:181], v4 offset:7168
	global_load_lds_dwordx4 v0, s[4:5]
	s_mov_b32 m0, s36
	s_nop 0
	global_load_lds_dwordx4 v2, s[4:5]
	s_waitcnt lgkmcnt(8)
	s_barrier
	s_waitcnt lgkmcnt(0)
	s_waitcnt lgkmcnt(0)
	v_mfma_f32_16x16x32_bf16 v[54:57], v[110:113], v[126:129], v[54:57]
	v_mfma_f32_16x16x32_bf16 v[58:61], v[118:121], v[126:129], v[58:61]
	v_mfma_f32_16x16x32_bf16 v[62:65], v[110:113], v[158:161], v[62:65]
	v_mfma_f32_16x16x32_bf16 v[66:69], v[118:121], v[158:161], v[66:69]
	v_mfma_f32_16x16x32_bf16 v[70:73], v[110:113], v[166:169], v[70:73]
	v_mfma_f32_16x16x32_bf16 v[74:77], v[118:121], v[166:169], v[74:77]
	v_mfma_f32_16x16x32_bf16 v[78:81], v[110:113], v[174:177], v[78:81]
	v_mfma_f32_16x16x32_bf16 v[82:85], v[118:121], v[174:177], v[82:85]
	v_mfma_f32_16x16x32_bf16 v[54:57], v[114:117], v[130:133], v[54:57]
	v_mfma_f32_16x16x32_bf16 v[58:61], v[122:125], v[130:133], v[58:61]
	v_mfma_f32_16x16x32_bf16 v[62:65], v[114:117], v[162:165], v[62:65]
	v_mfma_f32_16x16x32_bf16 v[66:69], v[122:125], v[162:165], v[66:69]
	v_mfma_f32_16x16x32_bf16 v[70:73], v[114:117], v[170:173], v[70:73]
	v_mfma_f32_16x16x32_bf16 v[74:77], v[122:125], v[170:173], v[74:77]
	v_mfma_f32_16x16x32_bf16 v[78:81], v[114:117], v[178:181], v[78:81]
	v_mfma_f32_16x16x32_bf16 v[82:85], v[122:125], v[178:181], v[82:85]
	s_barrier
	s_mov_b32 m0, s37
	ds_read_b128 v[182:185], v201
	ds_read_b128 v[186:189], v201 offset:1024
	ds_read_b128 v[192:195], v201 offset:2048
	ds_read_b128 v[204:207], v201 offset:3072
	global_load_lds_dwordx4 v0, s[10:11]
	s_mov_b32 m0, s38
	v_lshl_add_u64 v[190:191], s[10:11], 0, v[0:1]
	global_load_lds_dwordx4 v2, s[10:11]
	s_barrier
	s_waitcnt lgkmcnt(0)
	v_lshl_add_u64 v[196:197], s[10:11], 0, v[2:3]
	s_waitcnt lgkmcnt(0)
	v_mfma_f32_16x16x32_bf16 v[102:105], v[182:185], v[126:129], v[102:105]
	v_mfma_f32_16x16x32_bf16 v[22:25], v[192:195], v[126:129], v[22:25]
	v_mfma_f32_16x16x32_bf16 v[26:29], v[182:185], v[158:161], v[26:29]
	v_mfma_f32_16x16x32_bf16 v[30:33], v[192:195], v[158:161], v[30:33]
	v_mfma_f32_16x16x32_bf16 v[34:37], v[182:185], v[166:169], v[34:37]
	v_mfma_f32_16x16x32_bf16 v[38:41], v[192:195], v[166:169], v[38:41]
	v_mfma_f32_16x16x32_bf16 v[42:45], v[182:185], v[174:177], v[42:45]
	v_mfma_f32_16x16x32_bf16 v[46:49], v[192:195], v[174:177], v[46:49]
	v_mfma_f32_16x16x32_bf16 v[102:105], v[186:189], v[130:133], v[102:105]
	v_mfma_f32_16x16x32_bf16 v[22:25], v[204:207], v[130:133], v[22:25]
	v_mfma_f32_16x16x32_bf16 v[26:29], v[186:189], v[162:165], v[26:29]
	v_mfma_f32_16x16x32_bf16 v[30:33], v[204:207], v[162:165], v[30:33]
	v_mfma_f32_16x16x32_bf16 v[34:37], v[186:189], v[170:173], v[34:37]
	v_mfma_f32_16x16x32_bf16 v[38:41], v[204:207], v[170:173], v[38:41]
	v_mfma_f32_16x16x32_bf16 v[42:45], v[186:189], v[178:181], v[42:45]
	v_mfma_f32_16x16x32_bf16 v[46:49], v[204:207], v[178:181], v[46:49]
	s_mov_b32 m0, s63
	s_barrier
	ds_read_b128 v[126:129], v4 offset:16384
	ds_read_b128 v[130:133], v4 offset:17408
	ds_read_b128 v[158:161], v4 offset:18432
	ds_read_b128 v[162:165], v4 offset:19456
	ds_read_b128 v[166:169], v4 offset:20480
	ds_read_b128 v[170:173], v4 offset:21504
	ds_read_b128 v[174:177], v4 offset:22528
	ds_read_b128 v[178:181], v4 offset:23552
	global_load_lds_dwordx4 v0, s[8:9]
	s_mov_b32 m0, s24
	v_lshl_add_u64 v[198:199], s[8:9], 0, v[0:1]
	global_load_lds_dwordx4 v2, s[8:9]
	s_barrier
	s_waitcnt lgkmcnt(0)
	v_lshl_add_u64 v[240:241], s[8:9], 0, v[2:3]
	s_waitcnt lgkmcnt(0)
	v_mfma_f32_16x16x32_bf16 v[150:153], v[110:113], v[166:169], v[150:153]
	v_mfma_f32_16x16x32_bf16 v[6:9], v[110:113], v[174:177], v[6:9]
	v_mfma_f32_16x16x32_bf16 v[10:13], v[118:121], v[174:177], v[10:13]
	v_mfma_f32_16x16x32_bf16 v[134:137], v[110:113], v[126:129], v[134:137]
	v_mfma_f32_16x16x32_bf16 v[138:141], v[118:121], v[126:129], v[138:141]
	v_mfma_f32_16x16x32_bf16 v[142:145], v[110:113], v[158:161], v[142:145]
	v_mfma_f32_16x16x32_bf16 v[146:149], v[118:121], v[158:161], v[146:149]
	v_mfma_f32_16x16x32_bf16 v[150:153], v[114:117], v[170:173], v[150:153]
	v_mfma_f32_16x16x32_bf16 v[154:157], v[118:121], v[166:169], v[154:157]
	v_mfma_f32_16x16x32_bf16 v[6:9], v[114:117], v[178:181], v[6:9]
	v_mfma_f32_16x16x32_bf16 v[10:13], v[122:125], v[178:181], v[10:13]
	v_mfma_f32_16x16x32_bf16 v[134:137], v[114:117], v[130:133], v[134:137]
	v_mfma_f32_16x16x32_bf16 v[138:141], v[122:125], v[130:133], v[138:141]
	v_mfma_f32_16x16x32_bf16 v[142:145], v[114:117], v[162:165], v[142:145]
	v_mfma_f32_16x16x32_bf16 v[146:149], v[122:125], v[162:165], v[146:149]
	v_mfma_f32_16x16x32_bf16 v[154:157], v[122:125], v[170:173], v[154:157]
	s_barrier
	s_add_u32 s4, s10, 0x10000
	s_addc_u32 s5, s11, 0
	s_mov_b32 m0, s39
	s_nop 0
	global_load_lds_dwordx4 v0, s[4:5]
	s_mov_b32 m0, s43
	s_nop 0
	global_load_lds_dwordx4 v2, s[4:5]
	s_waitcnt vmcnt(6)
	s_barrier
	v_mfma_f32_16x16x32_bf16 v[14:17], v[182:185], v[126:129], v[14:17]
	v_mfma_f32_16x16x32_bf16 v[208:211], v[186:189], v[130:133], v[14:17]
	v_mfma_f32_16x16x32_bf16 v[14:17], v[192:195], v[126:129], v[18:21]
	v_mfma_f32_16x16x32_bf16 v[18:21], v[204:207], v[130:133], v[14:17]
	v_mfma_f32_16x16x32_bf16 v[14:17], v[182:185], v[158:161], v[50:53]
	v_mfma_f32_16x16x32_bf16 v[130:133], v[186:189], v[162:165], v[14:17]
	v_mfma_f32_16x16x32_bf16 v[14:17], v[192:195], v[158:161], v[94:97]
	v_mfma_f32_16x16x32_bf16 v[158:161], v[204:207], v[162:165], v[14:17]
	v_mfma_f32_16x16x32_bf16 v[14:17], v[182:185], v[166:169], v[98:101]
	v_mfma_f32_16x16x32_bf16 v[162:165], v[186:189], v[170:173], v[14:17]
	v_mfma_f32_16x16x32_bf16 v[14:17], v[192:195], v[166:169], v[106:109]
	v_mfma_f32_16x16x32_bf16 v[166:169], v[204:207], v[170:173], v[14:17]
	v_mfma_f32_16x16x32_bf16 v[14:17], v[182:185], v[174:177], v[86:89]
	v_mfma_f32_16x16x32_bf16 v[170:173], v[186:189], v[178:181], v[14:17]
	v_mfma_f32_16x16x32_bf16 v[14:17], v[192:195], v[174:177], v[90:93]
	v_mfma_f32_16x16x32_bf16 v[174:177], v[204:207], v[178:181], v[14:17]
	s_barrier
	s_nop 4
	ds_read_b128 v[14:17], v202
	ds_read_b128 v[50:53], v202 offset:1024
	ds_read_b128 v[178:181], v202 offset:2048
	ds_read_b128 v[182:185], v202 offset:3072
	s_add_u32 s4, s8, 0x10000
	s_addc_u32 s5, s9, 0
	s_mov_b32 m0, s25
	ds_read_b128 v[86:89], v4 offset:32768
	ds_read_b128 v[98:101], v4 offset:33792
	ds_read_b128 v[186:189], v4 offset:34816
	ds_read_b128 v[192:195], v4 offset:35840
	ds_read_b128 v[204:207], v4 offset:36864
	ds_read_b128 v[212:215], v4 offset:37888
	ds_read_b128 v[216:219], v4 offset:38912
	ds_read_b128 v[220:223], v4 offset:39936
	global_load_lds_dwordx4 v0, s[4:5]
	s_mov_b32 m0, s26
	s_nop 0
	global_load_lds_dwordx4 v2, s[4:5]
	s_waitcnt lgkmcnt(8)
	s_barrier
	s_waitcnt lgkmcnt(0)
	s_waitcnt lgkmcnt(0)
	v_mfma_f32_16x16x32_bf16 v[54:57], v[14:17], v[86:89], v[54:57]
	v_mfma_f32_16x16x32_bf16 v[126:129], v[50:53], v[98:101], v[54:57]
	v_mfma_f32_16x16x32_bf16 v[54:57], v[178:181], v[86:89], v[58:61]
	v_mfma_f32_16x16x32_bf16 v[122:125], v[182:185], v[98:101], v[54:57]
	v_mfma_f32_16x16x32_bf16 v[54:57], v[14:17], v[186:189], v[62:65]
	v_mfma_f32_16x16x32_bf16 v[110:113], v[50:53], v[192:195], v[54:57]
	v_mfma_f32_16x16x32_bf16 v[54:57], v[178:181], v[186:189], v[66:69]
	v_mfma_f32_16x16x32_bf16 v[106:109], v[182:185], v[192:195], v[54:57]
	v_mfma_f32_16x16x32_bf16 v[54:57], v[14:17], v[204:207], v[70:73]
	v_mfma_f32_16x16x32_bf16 v[94:97], v[50:53], v[212:215], v[54:57]
	v_mfma_f32_16x16x32_bf16 v[54:57], v[178:181], v[204:207], v[74:77]
	v_mfma_f32_16x16x32_bf16 v[90:93], v[182:185], v[212:215], v[54:57]
	v_mfma_f32_16x16x32_bf16 v[54:57], v[14:17], v[216:219], v[78:81]
	v_mfma_f32_16x16x32_bf16 v[78:81], v[50:53], v[220:223], v[54:57]
	v_mfma_f32_16x16x32_bf16 v[54:57], v[178:181], v[216:219], v[82:85]
	v_mfma_f32_16x16x32_bf16 v[74:77], v[182:185], v[220:223], v[54:57]
	s_barrier
	s_mov_b32 m0, s46
	s_nop 3
	v_lshl_add_u64 v[54:55], v[190:191], 0, s[70:71]
	ds_read_b128 v[224:227], v5
	ds_read_b128 v[228:231], v5 offset:1024
	ds_read_b128 v[232:235], v5 offset:2048
	ds_read_b128 v[236:239], v5 offset:3072
	global_load_lds_dwordx4 v[54:55], off
	v_lshl_add_u64 v[54:55], v[196:197], 0, s[70:71]
	s_mov_b32 m0, s47
	s_nop 0
	global_load_lds_dwordx4 v[54:55], off
	s_barrier
	s_waitcnt lgkmcnt(0)
	s_waitcnt lgkmcnt(0)
	v_mfma_f32_16x16x32_bf16 v[22:25], v[232:235], v[86:89], v[22:25]
	v_mfma_f32_16x16x32_bf16 v[114:117], v[236:239], v[98:101], v[22:25]
	v_mfma_f32_16x16x32_bf16 v[22:25], v[224:227], v[186:189], v[26:29]
	v_mfma_f32_16x16x32_bf16 v[54:57], v[224:227], v[86:89], v[102:105]
	v_mfma_f32_16x16x32_bf16 v[102:105], v[228:231], v[192:195], v[22:25]
	v_mfma_f32_16x16x32_bf16 v[22:25], v[232:235], v[186:189], v[30:33]
	v_mfma_f32_16x16x32_bf16 v[118:121], v[228:231], v[98:101], v[54:57]
	v_mfma_f32_16x16x32_bf16 v[98:101], v[236:239], v[192:195], v[22:25]
	v_mfma_f32_16x16x32_bf16 v[22:25], v[224:227], v[204:207], v[34:37]
	v_mfma_f32_16x16x32_bf16 v[86:89], v[228:231], v[212:215], v[22:25]
	v_mfma_f32_16x16x32_bf16 v[22:25], v[232:235], v[204:207], v[38:41]
	v_mfma_f32_16x16x32_bf16 v[82:85], v[236:239], v[212:215], v[22:25]
	v_mfma_f32_16x16x32_bf16 v[22:25], v[224:227], v[216:219], v[42:45]
	v_mfma_f32_16x16x32_bf16 v[70:73], v[228:231], v[220:223], v[22:25]
	v_mfma_f32_16x16x32_bf16 v[22:25], v[232:235], v[216:219], v[46:49]
	v_mfma_f32_16x16x32_bf16 v[66:69], v[236:239], v[220:223], v[22:25]
	s_mov_b32 m0, s27
	s_barrier
	s_nop 3
	ds_read_b128 v[22:25], v4 offset:49152
	ds_read_b128 v[34:37], v4 offset:50176
	ds_read_b128 v[186:189], v4 offset:51200
	ds_read_b128 v[192:195], v4 offset:52224
	ds_read_b128 v[204:207], v4 offset:53248
	ds_read_b128 v[212:215], v4 offset:54272
	ds_read_b128 v[216:219], v4 offset:55296
	ds_read_b128 v[220:223], v4 offset:56320
	v_lshl_add_u64 v[4:5], v[198:199], 0, s[70:71]
	global_load_lds_dwordx4 v[4:5], off
	v_lshl_add_u64 v[4:5], v[240:241], 0, s[70:71]
	s_mov_b32 m0, s28
	s_nop 0
	global_load_lds_dwordx4 v[4:5], off
	s_barrier
	s_waitcnt lgkmcnt(0)
	s_waitcnt lgkmcnt(0)
	v_mfma_f32_16x16x32_bf16 v[26:29], v[14:17], v[22:25], v[134:137]
	v_mfma_f32_16x16x32_bf16 v[62:65], v[50:53], v[34:37], v[26:29]
	v_mfma_f32_16x16x32_bf16 v[26:29], v[178:181], v[22:25], v[138:141]
	v_mfma_f32_16x16x32_bf16 v[58:61], v[182:185], v[34:37], v[26:29]
	v_mfma_f32_16x16x32_bf16 v[26:29], v[14:17], v[186:189], v[142:145]
	v_mfma_f32_16x16x32_bf16 v[46:49], v[50:53], v[192:195], v[26:29]
	v_mfma_f32_16x16x32_bf16 v[26:29], v[178:181], v[186:189], v[146:149]
	v_mfma_f32_16x16x32_bf16 v[42:45], v[182:185], v[192:195], v[26:29]
	v_mfma_f32_16x16x32_bf16 v[26:29], v[14:17], v[204:207], v[150:153]
	v_mfma_f32_16x16x32_bf16 v[4:7], v[14:17], v[216:219], v[6:9]
	v_mfma_f32_16x16x32_bf16 v[30:33], v[50:53], v[212:215], v[26:29]
	v_mfma_f32_16x16x32_bf16 v[26:29], v[178:181], v[204:207], v[154:157]
	v_mfma_f32_16x16x32_bf16 v[14:17], v[50:53], v[220:223], v[4:7]
	v_mfma_f32_16x16x32_bf16 v[4:7], v[178:181], v[216:219], v[10:13]
	v_mfma_f32_16x16x32_bf16 v[26:29], v[182:185], v[212:215], v[26:29]
	v_mfma_f32_16x16x32_bf16 v[10:13], v[182:185], v[220:223], v[4:7]
	s_barrier
	s_add_u32 s4, s10, 0x10080
	s_addc_u32 s5, s11, 0
	s_mov_b32 m0, s52
	s_nop 0
	global_load_lds_dwordx4 v0, s[4:5]
	s_mov_b32 m0, s60
	s_nop 0
	global_load_lds_dwordx4 v2, s[4:5]
	s_waitcnt vmcnt(6)
	s_barrier
	v_mfma_f32_16x16x32_bf16 v[2:5], v[224:227], v[22:25], v[208:211]
	v_mfma_f32_16x16x32_bf16 v[54:57], v[228:231], v[34:37], v[2:5]
	v_mfma_f32_16x16x32_bf16 v[2:5], v[232:235], v[22:25], v[18:21]
	v_mfma_f32_16x16x32_bf16 v[50:53], v[236:239], v[34:37], v[2:5]
	v_mfma_f32_16x16x32_bf16 v[2:5], v[224:227], v[186:189], v[130:133]
	v_mfma_f32_16x16x32_bf16 v[38:41], v[228:231], v[192:195], v[2:5]
	v_mfma_f32_16x16x32_bf16 v[2:5], v[232:235], v[186:189], v[158:161]
	v_mfma_f32_16x16x32_bf16 v[34:37], v[236:239], v[192:195], v[2:5]
	v_mfma_f32_16x16x32_bf16 v[2:5], v[224:227], v[204:207], v[162:165]
	v_mfma_f32_16x16x32_bf16 v[22:25], v[228:231], v[212:215], v[2:5]
	v_mfma_f32_16x16x32_bf16 v[2:5], v[232:235], v[204:207], v[166:169]
	v_mfma_f32_16x16x32_bf16 v[18:21], v[236:239], v[212:215], v[2:5]
	v_mfma_f32_16x16x32_bf16 v[2:5], v[224:227], v[216:219], v[170:173]
	v_mfma_f32_16x16x32_bf16 v[6:9], v[228:231], v[220:223], v[2:5]
	v_mfma_f32_16x16x32_bf16 v[2:5], v[232:235], v[216:219], v[174:177]
	v_mfma_f32_16x16x32_bf16 v[2:5], v[236:239], v[220:223], v[2:5]
	s_mov_b32 s16, s48
	s_mov_b32 s17, s49
	s_barrier
	v_mbcnt_lo_u32_b32 v0, -1, 0
	v_mbcnt_hi_u32_b32 v0, -1, v0
	s_add_u32 s20, s16, 0x15059c00
	s_addc_u32 s21, s17, 0
	v_and_b32_e32 v150, 15, v0
	s_cmp_lg_u32 s18, 0
	v_bfe_u32 v151, v0, 4, 2
	s_cbranch_scc0 .LBB0_627
	s_add_u32 s18, s16, 0x12500000
	s_addc_u32 s19, s17, 0
	s_lshl_b32 s22, s72, 8
	s_ashr_i32 s23, s22, 31
	s_lshl_b64 s[4:5], s[22:23], 2
	s_add_u32 s4, s20, s4
	v_readlane_b32 s41, v255, 15
	s_addc_u32 s5, s21, s5
	s_lshl_b32 s23, s41, 2
	s_add_u32 s4, s4, s23
	s_addc_u32 s5, s5, 0
	v_lshlrev_b32_e32 v130, 4, v151
	global_load_dwordx4 v[138:141], v130, s[4:5]
	global_load_dwordx4 v[142:145], v130, s[4:5] offset:64
	global_load_dwordx4 v[134:137], v130, s[4:5] offset:512
	s_nop 0
	global_load_dwordx4 v[130:133], v130, s[4:5] offset:576
	s_mov_b32 s4, 0x358637bd
	v_mov_b64_e32 v[146:147], s[4:5]
	s_mov_b32 s56, 0x3b800000
	s_mov_b32 s40, 0x45800000
	s_waitcnt vmcnt(0)
	v_pk_fma_f32 v[138:139], v[138:139], s[56:57], v[146:147] op_sel_hi:[1,0,0]
	s_nop 0
	v_mul_f32_e32 v148, 0x4b800000, v138
	v_cmp_gt_f32_e64 s[4:5], s54, v138
	v_cmp_gt_f32_e32 vcc, s54, v139
	v_pk_fma_f32 v[140:141], v[140:141], s[56:57], v[146:147] op_sel_hi:[1,0,0]
	v_cndmask_b32_e64 v138, v138, v148, s[4:5]
	v_mul_f32_e32 v148, 0x4b800000, v139
	v_cndmask_b32_e32 v139, v139, v148, vcc
	v_rsq_f32_e32 v138, v138
	v_rsq_f32_e32 v139, v139
	v_pk_fma_f32 v[142:143], v[142:143], s[56:57], v[146:147] op_sel_hi:[1,0,0]
	v_pk_fma_f32 v[144:145], v[144:145], s[56:57], v[146:147] op_sel_hi:[1,0,0]
	v_pk_fma_f32 v[134:135], v[134:135], s[56:57], v[146:147] op_sel_hi:[1,0,0]
	v_pk_mul_f32 v[148:149], v[138:139], s[40:41] op_sel_hi:[1,0]
	v_pk_fma_f32 v[136:137], v[136:137], s[56:57], v[146:147] op_sel_hi:[1,0,0]
	v_cndmask_b32_e64 v138, v138, v148, s[4:5]
	v_mul_f32_e32 v148, 0x4b800000, v140
	v_cmp_gt_f32_e64 s[4:5], s54, v140
	v_cndmask_b32_e32 v139, v139, v149, vcc
	v_cmp_gt_f32_e32 vcc, s54, v141
	v_cndmask_b32_e64 v140, v140, v148, s[4:5]
	v_mul_f32_e32 v148, 0x4b800000, v141
	v_cndmask_b32_e32 v141, v141, v148, vcc
	v_rsq_f32_e32 v140, v140
	v_rsq_f32_e32 v141, v141
	v_pk_fma_f32 v[130:131], v[130:131], s[56:57], v[146:147] op_sel_hi:[1,0,0]
	v_pk_fma_f32 v[132:133], v[132:133], s[56:57], v[146:147] op_sel_hi:[1,0,0]
	v_pk_mul_f32 v[148:149], v[140:141], s[40:41] op_sel_hi:[1,0]
	s_nop 0
	v_cndmask_b32_e64 v140, v140, v148, s[4:5]
	v_mul_f32_e32 v148, 0x4b800000, v142
	v_cmp_gt_f32_e64 s[4:5], s54, v142
	v_cndmask_b32_e32 v141, v141, v149, vcc
	v_cmp_gt_f32_e32 vcc, s54, v143
	v_cndmask_b32_e64 v142, v142, v148, s[4:5]
	v_mul_f32_e32 v148, 0x4b800000, v143
	v_cndmask_b32_e32 v143, v143, v148, vcc
	v_rsq_f32_e32 v142, v142
	v_rsq_f32_e32 v143, v143
	v_mul_f32_e32 v146, 0x4b800000, v132
	v_pk_mul_f32 v[148:149], v[142:143], s[40:41] op_sel_hi:[1,0]
	s_nop 0
	v_cndmask_b32_e64 v142, v142, v148, s[4:5]
	v_mul_f32_e32 v148, 0x4b800000, v144
	v_cmp_gt_f32_e64 s[4:5], s54, v144
	v_cndmask_b32_e32 v143, v143, v149, vcc
	v_cmp_gt_f32_e32 vcc, s54, v145
	v_cndmask_b32_e64 v144, v144, v148, s[4:5]
	v_mul_f32_e32 v148, 0x4b800000, v145
	v_cndmask_b32_e32 v145, v145, v148, vcc
	v_rsq_f32_e32 v144, v144
	v_rsq_f32_e32 v145, v145
	s_nop 0
	v_pk_mul_f32 v[148:149], v[144:145], s[40:41] op_sel_hi:[1,0]
	s_nop 0
	v_cndmask_b32_e64 v144, v144, v148, s[4:5]
	v_mul_f32_e32 v148, 0x4b800000, v134
	v_cmp_gt_f32_e64 s[4:5], s54, v134
	v_cndmask_b32_e32 v145, v145, v149, vcc
	v_cmp_gt_f32_e32 vcc, s54, v135
	v_cndmask_b32_e64 v134, v134, v148, s[4:5]
	v_mul_f32_e32 v148, 0x4b800000, v135
	v_cndmask_b32_e32 v135, v135, v148, vcc
	v_rsq_f32_e32 v134, v134
	v_rsq_f32_e32 v135, v135
	s_nop 0
	v_pk_mul_f32 v[148:149], v[134:135], s[40:41] op_sel_hi:[1,0]
	s_nop 0
	v_cndmask_b32_e64 v134, v134, v148, s[4:5]
	v_mul_f32_e32 v148, 0x4b800000, v136
	v_cmp_gt_f32_e64 s[4:5], s54, v136
	v_cndmask_b32_e32 v135, v135, v149, vcc
	v_cmp_gt_f32_e32 vcc, s54, v137
	v_cndmask_b32_e64 v136, v136, v148, s[4:5]
	v_mul_f32_e32 v148, 0x4b800000, v137
	v_cndmask_b32_e32 v137, v137, v148, vcc
	v_rsq_f32_e32 v136, v136
	v_rsq_f32_e32 v137, v137
	s_nop 0
	v_pk_mul_f32 v[148:149], v[136:137], s[40:41] op_sel_hi:[1,0]
	s_nop 0
	v_cndmask_b32_e64 v136, v136, v148, s[4:5]
	v_mul_f32_e32 v148, 0x4b800000, v130
	v_cmp_gt_f32_e64 s[4:5], s54, v130
	v_cndmask_b32_e32 v137, v137, v149, vcc
	v_cmp_gt_f32_e32 vcc, s54, v131
	v_cndmask_b32_e64 v130, v130, v148, s[4:5]
	v_mul_f32_e32 v148, 0x4b800000, v131
	v_cndmask_b32_e32 v131, v131, v148, vcc
	v_rsq_f32_e32 v130, v130
	v_rsq_f32_e32 v131, v131
	s_nop 0
	v_pk_mul_f32 v[148:149], v[130:131], s[40:41] op_sel_hi:[1,0]
	s_nop 0
	v_cndmask_b32_e64 v130, v130, v148, s[4:5]
	v_cmp_gt_f32_e64 s[4:5], s54, v132
	v_cndmask_b32_e32 v131, v131, v149, vcc
	v_cmp_gt_f32_e32 vcc, s54, v133
	v_cndmask_b32_e64 v132, v132, v146, s[4:5]
	v_mul_f32_e32 v146, 0x4b800000, v133
	v_cndmask_b32_e32 v133, v133, v146, vcc
	v_rsq_f32_e32 v132, v132
	v_rsq_f32_e32 v133, v133
	s_nop 0
	v_pk_mul_f32 v[146:147], v[132:133], s[40:41] op_sel_hi:[1,0]
	s_nop 0
	v_cndmask_b32_e64 v132, v132, v146, s[4:5]
	v_readlane_b32 s4, v255, 11
	v_cndmask_b32_e32 v133, v133, v147, vcc
	s_nop 0
	v_or_b32_e32 v146, s4, v150
	v_lshl_add_u32 v158, s73, 8, v146
	v_mov_b64_e32 v[146:147], s[18:19]
	v_mad_i64_i32 v[152:153], s[4:5], v158, s85, v[146:147]
	s_or_b32 s4, s22, s41
	s_nop 0
	v_lshl_or_b32 v148, v151, 2, s4
	v_ashrrev_i32_e32 v149, 31, v148
	v_pk_mul_f32 v[154:155], v[128:129], v[140:141]
	v_pk_mul_f32 v[156:157], v[126:127], v[138:139]
	v_lshlrev_b64 v[148:149], 1, v[148:149]
	v_cvt_pk_bf16_f32 v156, v156, v157
	v_cvt_pk_bf16_f32 v157, v154, v155
	v_lshl_add_u64 v[152:153], v[152:153], 0, v[148:149]
	global_store_dwordx2 v[152:153], v[156:157], off
	v_pk_mul_f32 v[154:155], v[124:125], v[144:145]
	v_pk_mul_f32 v[156:157], v[122:123], v[142:143]
	s_nop 0
	v_cvt_pk_bf16_f32 v156, v156, v157
	v_cvt_pk_bf16_f32 v157, v154, v155
	global_store_dwordx2 v[152:153], v[156:157], off offset:32
	v_pk_mul_f32 v[154:155], v[120:121], v[136:137]
	v_pk_mul_f32 v[156:157], v[118:119], v[134:135]
	s_nop 0
	v_cvt_pk_bf16_f32 v156, v156, v157
	v_cvt_pk_bf16_f32 v157, v154, v155
	global_store_dwordx2 v[152:153], v[156:157], off offset:256
	v_pk_mul_f32 v[154:155], v[116:117], v[132:133]
	v_pk_mul_f32 v[156:157], v[114:115], v[130:131]
	s_nop 0
	v_cvt_pk_bf16_f32 v156, v156, v157
	v_cvt_pk_bf16_f32 v157, v154, v155
	global_store_dwordx2 v[152:153], v[156:157], off offset:288
	v_add_u32_e32 v152, 16, v158
	v_mad_i64_i32 v[152:153], s[4:5], v152, s85, v[146:147]
	v_pk_mul_f32 v[154:155], v[112:113], v[140:141]
	v_pk_mul_f32 v[156:157], v[110:111], v[138:139]
	v_lshl_add_u64 v[152:153], v[152:153], 0, v[148:149]
	v_cvt_pk_bf16_f32 v156, v156, v157
	v_cvt_pk_bf16_f32 v157, v154, v155
	global_store_dwordx2 v[152:153], v[156:157], off
	v_pk_mul_f32 v[154:155], v[108:109], v[144:145]
	v_pk_mul_f32 v[156:157], v[106:107], v[142:143]
	s_nop 0
	v_cvt_pk_bf16_f32 v156, v156, v157
	v_cvt_pk_bf16_f32 v157, v154, v155
	global_store_dwordx2 v[152:153], v[156:157], off offset:32
	v_pk_mul_f32 v[154:155], v[104:105], v[136:137]
	v_pk_mul_f32 v[156:157], v[102:103], v[134:135]
	s_nop 0
	v_cvt_pk_bf16_f32 v156, v156, v157
	v_cvt_pk_bf16_f32 v157, v154, v155
	global_store_dwordx2 v[152:153], v[156:157], off offset:256
	v_pk_mul_f32 v[154:155], v[100:101], v[132:133]
	v_pk_mul_f32 v[156:157], v[98:99], v[130:131]
	s_nop 0
	v_cvt_pk_bf16_f32 v156, v156, v157
	v_cvt_pk_bf16_f32 v157, v154, v155
	global_store_dwordx2 v[152:153], v[156:157], off offset:288
	v_add_u32_e32 v152, 32, v158
	v_mad_i64_i32 v[152:153], s[4:5], v152, s85, v[146:147]
	v_pk_mul_f32 v[154:155], v[96:97], v[140:141]
	v_pk_mul_f32 v[156:157], v[94:95], v[138:139]
	v_lshl_add_u64 v[152:153], v[152:153], 0, v[148:149]
	v_cvt_pk_bf16_f32 v156, v156, v157
	v_cvt_pk_bf16_f32 v157, v154, v155
	global_store_dwordx2 v[152:153], v[156:157], off
	v_pk_mul_f32 v[154:155], v[92:93], v[144:145]
	v_pk_mul_f32 v[156:157], v[90:91], v[142:143]
	s_nop 0
	v_cvt_pk_bf16_f32 v156, v156, v157
	v_cvt_pk_bf16_f32 v157, v154, v155
	global_store_dwordx2 v[152:153], v[156:157], off offset:32
	v_pk_mul_f32 v[154:155], v[88:89], v[136:137]
	v_pk_mul_f32 v[156:157], v[86:87], v[134:135]
	s_nop 0
	v_cvt_pk_bf16_f32 v156, v156, v157
	v_cvt_pk_bf16_f32 v157, v154, v155
	global_store_dwordx2 v[152:153], v[156:157], off offset:256
	v_pk_mul_f32 v[154:155], v[84:85], v[132:133]
	v_pk_mul_f32 v[156:157], v[82:83], v[130:131]
	s_nop 0
	v_cvt_pk_bf16_f32 v156, v156, v157
	v_cvt_pk_bf16_f32 v157, v154, v155
	global_store_dwordx2 v[152:153], v[156:157], off offset:288
	v_add_u32_e32 v152, 48, v158
	v_mad_i64_i32 v[152:153], s[4:5], v152, s85, v[146:147]
	v_pk_mul_f32 v[154:155], v[80:81], v[140:141]
	v_pk_mul_f32 v[156:157], v[78:79], v[138:139]
	v_lshl_add_u64 v[152:153], v[152:153], 0, v[148:149]
	v_cvt_pk_bf16_f32 v156, v156, v157
	v_cvt_pk_bf16_f32 v157, v154, v155
	global_store_dwordx2 v[152:153], v[156:157], off
	v_pk_mul_f32 v[154:155], v[76:77], v[144:145]
	v_pk_mul_f32 v[156:157], v[74:75], v[142:143]
	s_nop 0
	v_cvt_pk_bf16_f32 v156, v156, v157
	v_cvt_pk_bf16_f32 v157, v154, v155
	global_store_dwordx2 v[152:153], v[156:157], off offset:32
	v_pk_mul_f32 v[154:155], v[72:73], v[136:137]
	v_pk_mul_f32 v[156:157], v[70:71], v[134:135]
	s_nop 0
	v_cvt_pk_bf16_f32 v156, v156, v157
	v_cvt_pk_bf16_f32 v157, v154, v155
	global_store_dwordx2 v[152:153], v[156:157], off offset:256
	v_pk_mul_f32 v[154:155], v[68:69], v[132:133]
	v_pk_mul_f32 v[156:157], v[66:67], v[130:131]
	s_nop 0
	v_cvt_pk_bf16_f32 v156, v156, v157
	v_cvt_pk_bf16_f32 v157, v154, v155
	global_store_dwordx2 v[152:153], v[156:157], off offset:288
	v_add_u32_e32 v152, 0x80, v158
	v_mad_i64_i32 v[152:153], s[4:5], v152, s85, v[146:147]
	v_pk_mul_f32 v[154:155], v[64:65], v[140:141]
	v_pk_mul_f32 v[156:157], v[62:63], v[138:139]
	v_lshl_add_u64 v[152:153], v[152:153], 0, v[148:149]
	v_cvt_pk_bf16_f32 v156, v156, v157
	v_cvt_pk_bf16_f32 v157, v154, v155
	global_store_dwordx2 v[152:153], v[156:157], off
	v_pk_mul_f32 v[154:155], v[60:61], v[144:145]
	v_pk_mul_f32 v[156:157], v[58:59], v[142:143]
	s_nop 0
	v_cvt_pk_bf16_f32 v156, v156, v157
	v_cvt_pk_bf16_f32 v157, v154, v155
	global_store_dwordx2 v[152:153], v[156:157], off offset:32
	v_pk_mul_f32 v[154:155], v[56:57], v[136:137]
	v_pk_mul_f32 v[156:157], v[54:55], v[134:135]
	s_nop 0
	v_cvt_pk_bf16_f32 v156, v156, v157
	v_cvt_pk_bf16_f32 v157, v154, v155
	global_store_dwordx2 v[152:153], v[156:157], off offset:256
	v_pk_mul_f32 v[154:155], v[52:53], v[132:133]
	v_pk_mul_f32 v[156:157], v[50:51], v[130:131]
	s_nop 0
	v_cvt_pk_bf16_f32 v156, v156, v157
	v_cvt_pk_bf16_f32 v157, v154, v155
	global_store_dwordx2 v[152:153], v[156:157], off offset:288
	v_add_u32_e32 v152, 0x90, v158
	v_mad_i64_i32 v[152:153], s[4:5], v152, s85, v[146:147]
	v_pk_mul_f32 v[154:155], v[48:49], v[140:141]
	v_pk_mul_f32 v[156:157], v[46:47], v[138:139]
	v_lshl_add_u64 v[152:153], v[152:153], 0, v[148:149]
	v_cvt_pk_bf16_f32 v156, v156, v157
	v_cvt_pk_bf16_f32 v157, v154, v155
	global_store_dwordx2 v[152:153], v[156:157], off
	v_pk_mul_f32 v[154:155], v[44:45], v[144:145]
	v_pk_mul_f32 v[156:157], v[42:43], v[142:143]
	s_nop 0
	v_cvt_pk_bf16_f32 v156, v156, v157
	v_cvt_pk_bf16_f32 v157, v154, v155
	global_store_dwordx2 v[152:153], v[156:157], off offset:32
	v_pk_mul_f32 v[154:155], v[40:41], v[136:137]
	v_pk_mul_f32 v[156:157], v[38:39], v[134:135]
	s_nop 0
	v_cvt_pk_bf16_f32 v156, v156, v157
	v_cvt_pk_bf16_f32 v157, v154, v155
	global_store_dwordx2 v[152:153], v[156:157], off offset:256
	v_pk_mul_f32 v[154:155], v[36:37], v[132:133]
	v_pk_mul_f32 v[156:157], v[34:35], v[130:131]
	s_nop 0
	v_cvt_pk_bf16_f32 v156, v156, v157
	v_cvt_pk_bf16_f32 v157, v154, v155
	global_store_dwordx2 v[152:153], v[156:157], off offset:288
	v_add_u32_e32 v152, 0xa0, v158
	v_mad_i64_i32 v[152:153], s[4:5], v152, s85, v[146:147]
	v_pk_mul_f32 v[154:155], v[32:33], v[140:141]
	v_pk_mul_f32 v[156:157], v[30:31], v[138:139]
	v_lshl_add_u64 v[152:153], v[152:153], 0, v[148:149]
	v_cvt_pk_bf16_f32 v156, v156, v157
	v_cvt_pk_bf16_f32 v157, v154, v155
	global_store_dwordx2 v[152:153], v[156:157], off
	v_pk_mul_f32 v[154:155], v[28:29], v[144:145]
	v_pk_mul_f32 v[156:157], v[26:27], v[142:143]
	s_nop 0
	v_cvt_pk_bf16_f32 v156, v156, v157
	v_cvt_pk_bf16_f32 v157, v154, v155
	global_store_dwordx2 v[152:153], v[156:157], off offset:32
	v_pk_mul_f32 v[154:155], v[24:25], v[136:137]
	v_pk_mul_f32 v[156:157], v[22:23], v[134:135]
	s_nop 0
	v_cvt_pk_bf16_f32 v156, v156, v157
	v_cvt_pk_bf16_f32 v157, v154, v155
	global_store_dwordx2 v[152:153], v[156:157], off offset:256
	v_pk_mul_f32 v[154:155], v[20:21], v[132:133]
	v_pk_mul_f32 v[156:157], v[18:19], v[130:131]
	s_nop 0
	v_cvt_pk_bf16_f32 v156, v156, v157
	v_cvt_pk_bf16_f32 v157, v154, v155
	global_store_dwordx2 v[152:153], v[156:157], off offset:288
	v_add_u32_e32 v152, 0xb0, v158
	v_mad_i64_i32 v[146:147], s[4:5], v152, s85, v[146:147]
	v_pk_mul_f32 v[140:141], v[16:17], v[140:141]
	v_pk_mul_f32 v[138:139], v[14:15], v[138:139]
	v_pk_mul_f32 v[142:143], v[10:11], v[142:143]
	v_cvt_pk_bf16_f32 v138, v138, v139
	v_cvt_pk_bf16_f32 v139, v140, v141
	v_lshl_add_u64 v[140:141], v[146:147], 0, v[148:149]
	global_store_dwordx2 v[140:141], v[138:139], off
	v_pk_mul_f32 v[138:139], v[12:13], v[144:145]
	v_pk_mul_f32 v[136:137], v[8:9], v[136:137]
	v_pk_mul_f32 v[134:135], v[6:7], v[134:135]
	v_pk_mul_f32 v[132:133], v[4:5], v[132:133]
	v_pk_mul_f32 v[130:131], v[2:3], v[130:131]
	v_cvt_pk_bf16_f32 v142, v142, v143
	v_cvt_pk_bf16_f32 v143, v138, v139
	v_cvt_pk_bf16_f32 v134, v134, v135
	v_cvt_pk_bf16_f32 v135, v136, v137
	v_cvt_pk_bf16_f32 v130, v130, v131
	v_cvt_pk_bf16_f32 v131, v132, v133
	global_store_dwordx2 v[140:141], v[142:143], off offset:32
	global_store_dwordx2 v[140:141], v[134:135], off offset:256
	global_store_dwordx2 v[140:141], v[130:131], off offset:288
	s_cbranch_execz .LBB0_628
	s_branch .LBB0_663

.LBB0_676:
	s_add_u32 s6, s4, 0xfffc0080
	s_addc_u32 s7, s5, -1
	s_add_i32 s20, 0, 0x10000
	v_add_u32_e32 v146, s20, v132
	ds_read_b128 v[134:137], v146
	ds_read_b128 v[138:141], v146 offset:1024
	ds_read_b128 v[142:145], v146 offset:2048
	ds_read_b128 v[146:149], v146 offset:3072
	s_cmp_eq_u32 s13, 12
	s_cselect_b32 s9, s15, s7
	s_cselect_b32 s8, s14, s6
	s_cselect_b32 s7, s17, s11
	s_cselect_b32 s6, s16, s10
	v_lshl_add_u64 v[182:183], s[4:5], 0, v[0:1]
	s_add_i32 m0, s63, 0xc000
	ds_read_b128 v[150:153], v133
	ds_read_b128 v[154:157], v133 offset:1024
	ds_read_b128 v[158:161], v133 offset:2048
	ds_read_b128 v[162:165], v133 offset:3072
	ds_read_b128 v[166:169], v133 offset:4096
	ds_read_b128 v[170:173], v133 offset:5120
	ds_read_b128 v[174:177], v133 offset:6144
	ds_read_b128 v[178:181], v133 offset:7168
	global_load_lds_dwordx4 v[182:183], off
	v_lshl_add_u64 v[182:183], s[4:5], 0, v[130:131]
	s_add_i32 m0, s63, 0xe000
	s_nop 0
	global_load_lds_dwordx4 v[182:183], off
	s_waitcnt lgkmcnt(8)
	s_barrier
	s_waitcnt lgkmcnt(0)
	s_waitcnt lgkmcnt(0)
	v_mfma_f32_16x16x32_bf16 v[126:129], v[134:137], v[150:153], v[126:129]
	v_mfma_f32_16x16x32_bf16 v[122:125], v[142:145], v[150:153], v[122:125]
	v_mfma_f32_16x16x32_bf16 v[110:113], v[134:137], v[158:161], v[110:113]
	v_mfma_f32_16x16x32_bf16 v[106:109], v[142:145], v[158:161], v[106:109]
	v_mfma_f32_16x16x32_bf16 v[94:97], v[134:137], v[166:169], v[94:97]
	v_mfma_f32_16x16x32_bf16 v[90:93], v[142:145], v[166:169], v[90:93]
	v_mfma_f32_16x16x32_bf16 v[78:81], v[134:137], v[174:177], v[78:81]
	v_mfma_f32_16x16x32_bf16 v[74:77], v[142:145], v[174:177], v[74:77]
	v_mfma_f32_16x16x32_bf16 v[126:129], v[138:141], v[154:157], v[126:129]
	v_mfma_f32_16x16x32_bf16 v[122:125], v[146:149], v[154:157], v[122:125]
	v_mfma_f32_16x16x32_bf16 v[110:113], v[138:141], v[162:165], v[110:113]
	v_mfma_f32_16x16x32_bf16 v[106:109], v[146:149], v[162:165], v[106:109]
	v_mfma_f32_16x16x32_bf16 v[94:97], v[138:141], v[170:173], v[94:97]
	v_mfma_f32_16x16x32_bf16 v[90:93], v[146:149], v[170:173], v[90:93]
	v_mfma_f32_16x16x32_bf16 v[78:81], v[138:141], v[178:181], v[78:81]
	v_mfma_f32_16x16x32_bf16 v[74:77], v[146:149], v[178:181], v[74:77]
	s_barrier
	s_add_i32 s22, 0, 0x14000
	s_add_i32 s20, s20, s53
	v_add_u32_e32 v190, s22, v132
	v_lshl_add_u64 v[192:193], s[6:7], 0, v[0:1]
	s_mov_b32 m0, s20
	ds_read_b128 v[182:185], v190
	ds_read_b128 v[186:189], v190 offset:1024
	ds_read_b128 v[204:207], v190 offset:2048
	ds_read_b128 v[208:211], v190 offset:3072
	global_load_lds_dwordx4 v[192:193], off
	v_lshl_add_u64 v[194:195], s[6:7], 0, v[130:131]
	s_add_i32 m0, s20, 0x2000
	s_nop 0
	global_load_lds_dwordx4 v[194:195], off
	s_barrier
	s_waitcnt lgkmcnt(0)
	s_waitcnt lgkmcnt(0)
	v_mfma_f32_16x16x32_bf16 v[118:121], v[182:185], v[150:153], v[118:121]
	v_mfma_f32_16x16x32_bf16 v[114:117], v[204:207], v[150:153], v[114:117]
	v_mfma_f32_16x16x32_bf16 v[102:105], v[182:185], v[158:161], v[102:105]
	v_mfma_f32_16x16x32_bf16 v[98:101], v[204:207], v[158:161], v[98:101]
	v_mfma_f32_16x16x32_bf16 v[86:89], v[182:185], v[166:169], v[86:89]
	v_mfma_f32_16x16x32_bf16 v[82:85], v[204:207], v[166:169], v[82:85]
	v_mfma_f32_16x16x32_bf16 v[70:73], v[182:185], v[174:177], v[70:73]
	v_mfma_f32_16x16x32_bf16 v[66:69], v[204:207], v[174:177], v[66:69]
	v_mfma_f32_16x16x32_bf16 v[118:121], v[186:189], v[154:157], v[118:121]
	v_mfma_f32_16x16x32_bf16 v[114:117], v[208:211], v[154:157], v[114:117]
	v_mfma_f32_16x16x32_bf16 v[102:105], v[186:189], v[162:165], v[102:105]
	v_mfma_f32_16x16x32_bf16 v[98:101], v[208:211], v[162:165], v[98:101]
	v_mfma_f32_16x16x32_bf16 v[86:89], v[186:189], v[170:173], v[86:89]
	v_mfma_f32_16x16x32_bf16 v[82:85], v[208:211], v[170:173], v[82:85]
	v_mfma_f32_16x16x32_bf16 v[70:73], v[186:189], v[178:181], v[70:73]
	v_mfma_f32_16x16x32_bf16 v[66:69], v[208:211], v[178:181], v[66:69]
	s_mov_b32 m0, s63
	v_lshl_add_u64 v[196:197], s[8:9], 0, v[0:1]
	s_barrier
	ds_read_b128 v[150:153], v133 offset:16384
	ds_read_b128 v[154:157], v133 offset:17408
	ds_read_b128 v[158:161], v133 offset:18432
	ds_read_b128 v[162:165], v133 offset:19456
	ds_read_b128 v[166:169], v133 offset:20480
	ds_read_b128 v[170:173], v133 offset:21504
	ds_read_b128 v[174:177], v133 offset:22528
	ds_read_b128 v[178:181], v133 offset:23552
	global_load_lds_dwordx4 v[196:197], off
	v_lshl_add_u64 v[198:199], s[8:9], 0, v[130:131]
	s_mov_b32 m0, s83
	s_nop 0
	global_load_lds_dwordx4 v[198:199], off
	s_barrier
	s_waitcnt lgkmcnt(0)
	s_waitcnt lgkmcnt(0)
	v_mfma_f32_16x16x32_bf16 v[62:65], v[134:137], v[150:153], v[62:65]
	v_mfma_f32_16x16x32_bf16 v[58:61], v[142:145], v[150:153], v[58:61]
	v_mfma_f32_16x16x32_bf16 v[46:49], v[134:137], v[158:161], v[46:49]
	v_mfma_f32_16x16x32_bf16 v[42:45], v[142:145], v[158:161], v[42:45]
	v_mfma_f32_16x16x32_bf16 v[30:33], v[134:137], v[166:169], v[30:33]
	v_mfma_f32_16x16x32_bf16 v[26:29], v[142:145], v[166:169], v[26:29]
	v_mfma_f32_16x16x32_bf16 v[14:17], v[134:137], v[174:177], v[14:17]
	v_mfma_f32_16x16x32_bf16 v[10:13], v[142:145], v[174:177], v[10:13]
	v_mfma_f32_16x16x32_bf16 v[62:65], v[138:141], v[154:157], v[62:65]
	v_mfma_f32_16x16x32_bf16 v[58:61], v[146:149], v[154:157], v[58:61]
	v_mfma_f32_16x16x32_bf16 v[46:49], v[138:141], v[162:165], v[46:49]
	v_mfma_f32_16x16x32_bf16 v[42:45], v[146:149], v[162:165], v[42:45]
	v_mfma_f32_16x16x32_bf16 v[30:33], v[138:141], v[170:173], v[30:33]
	v_mfma_f32_16x16x32_bf16 v[26:29], v[146:149], v[170:173], v[26:29]
	v_mfma_f32_16x16x32_bf16 v[14:17], v[138:141], v[178:181], v[14:17]
	v_mfma_f32_16x16x32_bf16 v[10:13], v[146:149], v[178:181], v[10:13]
	s_barrier
	s_add_u32 s20, s6, 0x40000
	s_addc_u32 s21, s7, 0
	s_add_i32 s22, s22, s53
	v_lshl_add_u64 v[134:135], s[20:21], 0, v[0:1]
	s_mov_b32 m0, s22
	s_nop 0
	global_load_lds_dwordx4 v[134:135], off
	v_lshl_add_u64 v[134:135], s[20:21], 0, v[130:131]
	s_add_i32 m0, s22, 0x2000
	s_nop 0
	global_load_lds_dwordx4 v[134:135], off
	s_waitcnt vmcnt(6)
	s_barrier
	v_mfma_f32_16x16x32_bf16 v[54:57], v[182:185], v[150:153], v[54:57]
	v_mfma_f32_16x16x32_bf16 v[50:53], v[204:207], v[150:153], v[50:53]
	v_mfma_f32_16x16x32_bf16 v[38:41], v[182:185], v[158:161], v[38:41]
	v_mfma_f32_16x16x32_bf16 v[34:37], v[204:207], v[158:161], v[34:37]
	v_mfma_f32_16x16x32_bf16 v[22:25], v[182:185], v[166:169], v[22:25]
	v_mfma_f32_16x16x32_bf16 v[18:21], v[204:207], v[166:169], v[18:21]
	v_mfma_f32_16x16x32_bf16 v[6:9], v[182:185], v[174:177], v[6:9]
	v_mfma_f32_16x16x32_bf16 v[2:5], v[204:207], v[174:177], v[2:5]
	v_mfma_f32_16x16x32_bf16 v[54:57], v[186:189], v[154:157], v[54:57]
	v_mfma_f32_16x16x32_bf16 v[50:53], v[208:211], v[154:157], v[50:53]
	v_mfma_f32_16x16x32_bf16 v[38:41], v[186:189], v[162:165], v[38:41]
	v_mfma_f32_16x16x32_bf16 v[34:37], v[208:211], v[162:165], v[34:37]
	v_mfma_f32_16x16x32_bf16 v[22:25], v[186:189], v[170:173], v[22:25]
	v_mfma_f32_16x16x32_bf16 v[18:21], v[208:211], v[170:173], v[18:21]
	v_mfma_f32_16x16x32_bf16 v[6:9], v[186:189], v[178:181], v[6:9]
	v_mfma_f32_16x16x32_bf16 v[2:5], v[208:211], v[178:181], v[2:5]
	s_add_i32 s20, 0, 0x18000
	v_add_u32_e32 v146, s20, v132
	s_barrier
	ds_read_b128 v[134:137], v146
	ds_read_b128 v[138:141], v146 offset:1024
	ds_read_b128 v[142:145], v146 offset:2048
	ds_read_b128 v[146:149], v146 offset:3072
	s_add_u32 s8, s8, 0x40000
	s_addc_u32 s9, s9, 0
	s_mov_b32 m0, s88
	v_lshl_add_u64 v[182:183], s[8:9], 0, v[0:1]
	ds_read_b128 v[150:153], v133 offset:32768
	ds_read_b128 v[154:157], v133 offset:33792
	ds_read_b128 v[158:161], v133 offset:34816
	ds_read_b128 v[162:165], v133 offset:35840
	ds_read_b128 v[166:169], v133 offset:36864
	ds_read_b128 v[170:173], v133 offset:37888
	ds_read_b128 v[174:177], v133 offset:38912
	ds_read_b128 v[178:181], v133 offset:39936
	global_load_lds_dwordx4 v[182:183], off
	v_lshl_add_u64 v[182:183], s[8:9], 0, v[130:131]
	s_mov_b32 m0, s89
	s_nop 0
	global_load_lds_dwordx4 v[182:183], off
	s_waitcnt lgkmcnt(8)
	s_barrier
	s_waitcnt lgkmcnt(0)
	s_waitcnt lgkmcnt(0)
	v_mfma_f32_16x16x32_bf16 v[126:129], v[134:137], v[150:153], v[126:129]
	v_mfma_f32_16x16x32_bf16 v[122:125], v[142:145], v[150:153], v[122:125]
	v_mfma_f32_16x16x32_bf16 v[110:113], v[134:137], v[158:161], v[110:113]
	v_mfma_f32_16x16x32_bf16 v[106:109], v[142:145], v[158:161], v[106:109]
	v_mfma_f32_16x16x32_bf16 v[94:97], v[134:137], v[166:169], v[94:97]
	v_mfma_f32_16x16x32_bf16 v[90:93], v[142:145], v[166:169], v[90:93]
	v_mfma_f32_16x16x32_bf16 v[78:81], v[134:137], v[174:177], v[78:81]
	v_mfma_f32_16x16x32_bf16 v[74:77], v[142:145], v[174:177], v[74:77]
	v_mfma_f32_16x16x32_bf16 v[126:129], v[138:141], v[154:157], v[126:129]
	v_mfma_f32_16x16x32_bf16 v[122:125], v[146:149], v[154:157], v[122:125]
	v_mfma_f32_16x16x32_bf16 v[110:113], v[138:141], v[162:165], v[110:113]
	v_mfma_f32_16x16x32_bf16 v[106:109], v[146:149], v[162:165], v[106:109]
	v_mfma_f32_16x16x32_bf16 v[94:97], v[138:141], v[170:173], v[94:97]
	v_mfma_f32_16x16x32_bf16 v[90:93], v[146:149], v[170:173], v[90:93]
	v_mfma_f32_16x16x32_bf16 v[78:81], v[138:141], v[178:181], v[78:81]
	v_mfma_f32_16x16x32_bf16 v[74:77], v[146:149], v[178:181], v[74:77]
	s_barrier
	s_add_i32 s8, 0, 0x1c000
	s_add_i32 s9, s20, s53
	v_add_u32_e32 v190, s8, v132
	v_lshl_add_u64 v[192:193], v[192:193], 0, s[70:71]
	s_mov_b32 m0, s9
	ds_read_b128 v[182:185], v190
	ds_read_b128 v[186:189], v190 offset:1024
	ds_read_b128 v[204:207], v190 offset:2048
	ds_read_b128 v[208:211], v190 offset:3072
	global_load_lds_dwordx4 v[192:193], off
	v_lshl_add_u64 v[192:193], v[194:195], 0, s[70:71]
	s_add_i32 m0, s9, 0x2000
	s_nop 0
	global_load_lds_dwordx4 v[192:193], off
	s_barrier
	s_waitcnt lgkmcnt(0)
	s_waitcnt lgkmcnt(0)
	v_mfma_f32_16x16x32_bf16 v[118:121], v[182:185], v[150:153], v[118:121]
	v_mfma_f32_16x16x32_bf16 v[114:117], v[204:207], v[150:153], v[114:117]
	v_mfma_f32_16x16x32_bf16 v[102:105], v[182:185], v[158:161], v[102:105]
	v_mfma_f32_16x16x32_bf16 v[98:101], v[204:207], v[158:161], v[98:101]
	v_mfma_f32_16x16x32_bf16 v[86:89], v[182:185], v[166:169], v[86:89]
	v_mfma_f32_16x16x32_bf16 v[82:85], v[204:207], v[166:169], v[82:85]
	v_mfma_f32_16x16x32_bf16 v[70:73], v[182:185], v[174:177], v[70:73]
	v_mfma_f32_16x16x32_bf16 v[66:69], v[204:207], v[174:177], v[66:69]
	v_mfma_f32_16x16x32_bf16 v[118:121], v[186:189], v[154:157], v[118:121]
	v_mfma_f32_16x16x32_bf16 v[114:117], v[208:211], v[154:157], v[114:117]
	v_mfma_f32_16x16x32_bf16 v[102:105], v[186:189], v[162:165], v[102:105]
	v_mfma_f32_16x16x32_bf16 v[98:101], v[208:211], v[162:165], v[98:101]
	v_mfma_f32_16x16x32_bf16 v[86:89], v[186:189], v[170:173], v[86:89]
	v_mfma_f32_16x16x32_bf16 v[82:85], v[208:211], v[170:173], v[82:85]
	v_mfma_f32_16x16x32_bf16 v[70:73], v[186:189], v[178:181], v[70:73]
	v_mfma_f32_16x16x32_bf16 v[66:69], v[208:211], v[178:181], v[66:69]
	s_mov_b32 m0, s43
	v_lshl_add_u64 v[192:193], v[196:197], 0, s[70:71]
	s_barrier
	ds_read_b128 v[150:153], v133 offset:49152
	ds_read_b128 v[154:157], v133 offset:50176
	ds_read_b128 v[158:161], v133 offset:51200
	ds_read_b128 v[162:165], v133 offset:52224
	ds_read_b128 v[166:169], v133 offset:53248
	ds_read_b128 v[170:173], v133 offset:54272
	ds_read_b128 v[174:177], v133 offset:55296
	ds_read_b128 v[178:181], v133 offset:56320
	global_load_lds_dwordx4 v[192:193], off
	v_lshl_add_u64 v[192:193], v[198:199], 0, s[70:71]
	s_mov_b32 m0, s52
	s_nop 0
	global_load_lds_dwordx4 v[192:193], off
	s_barrier
	s_waitcnt lgkmcnt(0)
	s_waitcnt lgkmcnt(0)
	v_mfma_f32_16x16x32_bf16 v[62:65], v[134:137], v[150:153], v[62:65]
	v_mfma_f32_16x16x32_bf16 v[58:61], v[142:145], v[150:153], v[58:61]
	v_mfma_f32_16x16x32_bf16 v[46:49], v[134:137], v[158:161], v[46:49]
	v_mfma_f32_16x16x32_bf16 v[42:45], v[142:145], v[158:161], v[42:45]
	v_mfma_f32_16x16x32_bf16 v[30:33], v[134:137], v[166:169], v[30:33]
	v_mfma_f32_16x16x32_bf16 v[26:29], v[142:145], v[166:169], v[26:29]
	v_mfma_f32_16x16x32_bf16 v[14:17], v[134:137], v[174:177], v[14:17]
	v_mfma_f32_16x16x32_bf16 v[10:13], v[142:145], v[174:177], v[10:13]
	v_mfma_f32_16x16x32_bf16 v[62:65], v[138:141], v[154:157], v[62:65]
	v_mfma_f32_16x16x32_bf16 v[58:61], v[146:149], v[154:157], v[58:61]
	v_mfma_f32_16x16x32_bf16 v[46:49], v[138:141], v[162:165], v[46:49]
	v_mfma_f32_16x16x32_bf16 v[42:45], v[146:149], v[162:165], v[42:45]
	v_mfma_f32_16x16x32_bf16 v[30:33], v[138:141], v[170:173], v[30:33]
	v_mfma_f32_16x16x32_bf16 v[26:29], v[146:149], v[170:173], v[26:29]
	v_mfma_f32_16x16x32_bf16 v[14:17], v[138:141], v[178:181], v[14:17]
	v_mfma_f32_16x16x32_bf16 v[10:13], v[146:149], v[178:181], v[10:13]
	s_barrier
	s_add_u32 s6, s6, 0x40080
	s_addc_u32 s7, s7, 0
	s_add_i32 s8, s8, s53
	v_lshl_add_u64 v[134:135], s[6:7], 0, v[0:1]
	s_mov_b32 m0, s8
	s_nop 0
	global_load_lds_dwordx4 v[134:135], off
	v_lshl_add_u64 v[134:135], s[6:7], 0, v[130:131]
	s_add_i32 m0, s8, 0x2000
	s_nop 0
	global_load_lds_dwordx4 v[134:135], off
	s_waitcnt vmcnt(6)
	s_barrier
	v_mfma_f32_16x16x32_bf16 v[54:57], v[182:185], v[150:153], v[54:57]
	v_mfma_f32_16x16x32_bf16 v[50:53], v[204:207], v[150:153], v[50:53]
	v_mfma_f32_16x16x32_bf16 v[38:41], v[182:185], v[158:161], v[38:41]
	v_mfma_f32_16x16x32_bf16 v[34:37], v[204:207], v[158:161], v[34:37]
	v_mfma_f32_16x16x32_bf16 v[22:25], v[182:185], v[166:169], v[22:25]
	v_mfma_f32_16x16x32_bf16 v[18:21], v[204:207], v[166:169], v[18:21]
	v_mfma_f32_16x16x32_bf16 v[6:9], v[182:185], v[174:177], v[6:9]
	v_mfma_f32_16x16x32_bf16 v[2:5], v[204:207], v[174:177], v[2:5]
	v_mfma_f32_16x16x32_bf16 v[54:57], v[186:189], v[154:157], v[54:57]
	v_mfma_f32_16x16x32_bf16 v[50:53], v[208:211], v[154:157], v[50:53]
	v_mfma_f32_16x16x32_bf16 v[38:41], v[186:189], v[162:165], v[38:41]
	v_mfma_f32_16x16x32_bf16 v[34:37], v[208:211], v[162:165], v[34:37]
	v_mfma_f32_16x16x32_bf16 v[22:25], v[186:189], v[170:173], v[22:25]
	v_mfma_f32_16x16x32_bf16 v[18:21], v[208:211], v[170:173], v[18:21]
	v_mfma_f32_16x16x32_bf16 v[6:9], v[186:189], v[178:181], v[6:9]
	v_mfma_f32_16x16x32_bf16 v[2:5], v[208:211], v[178:181], v[2:5]
	s_add_i32 s13, s13, 2
	s_add_u32 s10, s10, 0x100
	s_addc_u32 s11, s11, 0
	s_add_u32 s4, s4, 0x100
	s_addc_u32 s5, s5, 0
	s_cmp_gt_u32 s13, 13
	s_barrier
	s_cbranch_scc0 .LBB0_676
	s_mov_b32 s9, s49
	s_mov_b32 s8, s48
	v_readlane_b32 s4, v252, 35
	v_mbcnt_lo_u32_b32 v0, -1, 0
	v_mbcnt_hi_u32_b32 v0, -1, v0
	v_readlane_b32 s5, v252, 36
	s_add_u32 s4, s8, s4
	s_addc_u32 s5, s9, s5
	s_add_u32 s20, s8, 0x4180000
	s_addc_u32 s21, s9, 0
	s_add_u32 s22, s8, 0x6200000
	s_addc_u32 s23, s9, 0
	s_add_u32 s24, s8, 0xc380000
	s_mov_b32 s6, s51
	s_mov_b32 s7, s50
	s_addc_u32 s25, s9, 0
	s_add_u32 s28, s7, 0x30c0000
	s_addc_u32 s29, s6, 0
	s_add_u32 s10, s8, 0x14580000
	s_addc_u32 s11, s9, 0
	s_add_u32 s34, s8, 0x14da0000
	s_addc_u32 s35, s9, 0
	s_add_u32 s26, s8, 0x15049800
	s_addc_u32 s27, s9, 0
	s_add_u32 s46, s8, 0x15059c00
	s_addc_u32 s47, s9, 0
	s_add_u32 s30, s8, 0x1506a000
	s_addc_u32 s31, s9, 0
	s_add_u32 s36, s8, 0x14fa8000
	s_addc_u32 s37, s9, 0
	s_add_u32 s38, s8, 0x14fe8800
	s_addc_u32 s39, s9, 0
	s_lshl_b32 s6, s44, 8
	s_add_i32 s6, s6, s42
	v_and_or_b32 v134, v0, 15, s6
	v_ashrrev_i32_e32 v135, 31, v134
	v_lshl_add_u64 v[130:131], v[134:135], 2, s[4:5]
	s_mov_b64 s[4:5], 0x15029000
	v_lshl_add_u64 v[132:133], v[130:131], 0, s[4:5]
	s_mov_b32 s4, 0x15029000
	v_add_co_u32_e32 v130, vcc, s4, v130
	v_bfe_u32 v141, v0, 4, 2
	s_nop 0
	v_addc_co_u32_e32 v131, vcc, 0, v131, vcc
	global_load_dword v136, v[130:131], off
	global_load_dword v153, v[132:133], off offset:64
	global_load_dword v152, v[132:133], off offset:128
	global_load_dword v151, v[132:133], off offset:192
	global_load_dword v150, v[132:133], off offset:512
	global_load_dword v149, v[132:133], off offset:576
	global_load_dword v148, v[132:133], off offset:640
	global_load_dword v147, v[132:133], off offset:704
	v_and_b32_e32 v130, 63, v0
	v_lshlrev_b32_e32 v146, 3, v141
	v_readlane_b32 s6, v255, 15
	v_lshlrev_b32_e32 v0, 2, v130
	v_cmp_gt_u32_e64 s[4:5], 16, v130
	v_lshlrev_b32_e32 v130, 2, v141
	v_or_b32_e32 v144, s6, v146
	v_readlane_b32 s6, v255, 12
	s_cmp_gt_i32 s82, 3
	v_readlane_b32 s41, v255, 13
	v_or_b32_e32 v145, s6, v130
	s_cselect_b64 s[6:7], -1, 0
	s_cmp_gt_u32 s82, 7
	s_cselect_b64 s[86:87], -1, 0
	s_cmp_lt_u32 s82, 27
	s_cselect_b64 s[64:65], -1, 0
	s_cmp_gt_u32 s82, 23
	s_cselect_b64 s[72:73], -1, 0
	s_lshl_b32 s40, s82, 6
	s_add_i32 s40, s41, s40
	v_xor_b32_e32 v143, 64, v0
	v_xor_b32_e32 v142, 0x80, v0
	v_or_b32_e32 v0, s40, v130
	v_lshl_add_u64 v[132:133], v[0:1], 1, s[8:9]
	s_mov_b64 s[8:9], 0x8280000
	v_lshl_add_u64 v[130:131], v[132:133], 0, s[8:9]
	s_mov_b64 s[8:9], 0xa300000
	v_mov_b32_e32 v0, 0x358637bd
	s_lshl_b32 s13, s82, 8
	v_lshl_add_u64 v[132:133], v[132:133], 0, s[8:9]
	v_readlane_b32 s8, v255, 14
	s_add_i32 s8, s8, s13
	s_waitcnt vmcnt(0)
	v_fmamk_f32 v0, v136, 0x3a800000, v0
	v_rsq_f32_e32 v136, v0
	v_or_b32_e32 v140, s8, v146
	v_readlane_b32 s8, v255, 16
	s_add_i32 s8, s8, s13
	s_nop 0
	v_or_b32_e32 v137, s8, v146
	s_mov_b64 s[8:9], -1
	s_and_b64 vcc, exec, s[6:7]
	s_cbranch_vccz .LBB0_708
	s_and_b64 vcc, exec, s[86:87]
	s_cbranch_vccz .LBB0_705
	s_and_b64 vcc, exec, s[64:65]
	s_cbranch_vccz .LBB0_702
	s_and_b64 vcc, exec, s[72:73]
	s_cbranch_vccz .LBB0_699
	s_cmp_gt_i32 s82, 25
	s_cbranch_scc0 .LBB0_685
	v_lshl_or_b32 v0, v134, 8, v144
	v_pk_mul_f32 v[160:161], v[122:123], v[136:137] op_sel_hi:[1,0]
	v_lshl_add_u64 v[138:139], v[0:1], 1, s[10:11]
	v_pk_mul_f32 v[154:155], v[126:127], v[136:137] op_sel_hi:[1,0]
	v_mul_f32_e32 v0, v160, v160
	v_mul_f32_e32 v162, v161, v161
	v_pk_mul_f32 v[158:159], v[124:125], v[136:137] op_sel_hi:[1,0]
	v_fmac_f32_e32 v0, v154, v154
	v_fmac_f32_e32 v162, v155, v155
	v_pk_mul_f32 v[156:157], v[128:129], v[136:137] op_sel_hi:[1,0]
	v_add_f32_e32 v0, v0, v162
	v_mul_f32_e32 v162, v158, v158
	v_fmac_f32_e32 v162, v156, v156
	v_add_f32_e32 v0, v162, v0
	v_mul_f32_e32 v162, v159, v159
	v_fmac_f32_e32 v162, v157, v157
	v_cvt_pk_bf16_f32 v154, v154, v155
	v_cvt_pk_bf16_f32 v155, v156, v157
	v_cvt_pk_bf16_f32 v156, v160, v161
	v_cvt_pk_bf16_f32 v157, v158, v159
	v_pk_mul_f32 v[160:161], v[114:115], v[136:137] op_sel_hi:[1,0]
	v_add_f32_e32 v0, v162, v0
	global_store_dwordx4 v[138:139], v[154:157], off
	v_mul_f32_e32 v162, v160, v160
	v_pk_mul_f32 v[158:159], v[116:117], v[136:137] op_sel_hi:[1,0]
	v_pk_mul_f32 v[154:155], v[118:119], v[136:137] op_sel_hi:[1,0]
	v_pk_mul_f32 v[156:157], v[120:121], v[136:137] op_sel_hi:[1,0]
	v_fmac_f32_e32 v162, v154, v154
	v_add_f32_e32 v0, v162, v0
	v_mul_f32_e32 v162, v161, v161
	v_fmac_f32_e32 v162, v155, v155
	v_add_f32_e32 v0, v162, v0
	v_mul_f32_e32 v162, v158, v158
	v_fmac_f32_e32 v162, v156, v156
	v_add_f32_e32 v0, v162, v0
	v_mul_f32_e32 v162, v159, v159
	v_fmac_f32_e32 v162, v157, v157
	v_add_f32_e32 v0, v162, v0
	v_cvt_pk_bf16_f32 v154, v154, v155
	v_cvt_pk_bf16_f32 v155, v156, v157
	v_cvt_pk_bf16_f32 v156, v160, v161
	v_cvt_pk_bf16_f32 v157, v158, v159
	global_store_dwordx4 v[138:139], v[154:157], off offset:256
	ds_bpermute_b32 v138, v143, v0
	v_readlane_b32 s8, v253, 19
	s_waitcnt lgkmcnt(0)
	v_add_f32_e32 v0, v0, v138
	ds_bpermute_b32 v138, v142, v0
	v_or_b32_e32 v139, s8, v141
	v_cmp_eq_u32_e32 vcc, 0, v139
	s_and_saveexec_b64 s[8:9], vcc
	s_cbranch_execz .LBB0_684
	s_waitcnt lgkmcnt(0)
	v_add_f32_e32 v0, v0, v138
	v_lshl_add_u64 v[138:139], v[134:135], 2, s[46:47]
	global_atomic_add_f32 v[138:139], v0, off

.LBB0_958:
	s_add_u32 s8, s6, 0xfffc0080
	s_addc_u32 s9, s7, -1
	s_add_i32 s23, 0, 0x10000
	v_add_u32_e32 v146, s23, v132
	ds_read_b128 v[134:137], v146
	ds_read_b128 v[138:141], v146 offset:1024
	ds_read_b128 v[142:145], v146 offset:2048
	ds_read_b128 v[146:149], v146 offset:3072
	s_cmp_eq_u32 s22, 12
	s_cselect_b32 s11, s19, s9
	s_cselect_b32 s10, s18, s8
	s_cselect_b32 s9, s17, s15
	s_cselect_b32 s8, s16, s14
	v_lshl_add_u64 v[182:183], s[6:7], 0, v[0:1]
	s_add_i32 m0, s63, 0xc000
	ds_read_b128 v[150:153], v133
	ds_read_b128 v[154:157], v133 offset:1024
	ds_read_b128 v[158:161], v133 offset:2048
	ds_read_b128 v[162:165], v133 offset:3072
	ds_read_b128 v[166:169], v133 offset:4096
	ds_read_b128 v[170:173], v133 offset:5120
	ds_read_b128 v[174:177], v133 offset:6144
	ds_read_b128 v[178:181], v133 offset:7168
	global_load_lds_dwordx4 v[182:183], off
	v_lshl_add_u64 v[182:183], s[6:7], 0, v[130:131]
	s_add_i32 m0, s63, 0xe000
	s_nop 0
	global_load_lds_dwordx4 v[182:183], off
	s_waitcnt lgkmcnt(8)
	s_barrier
	s_waitcnt lgkmcnt(0)
	s_waitcnt lgkmcnt(0)
	v_mfma_f32_16x16x32_bf16 v[126:129], v[134:137], v[150:153], v[126:129]
	v_mfma_f32_16x16x32_bf16 v[122:125], v[142:145], v[150:153], v[122:125]
	v_mfma_f32_16x16x32_bf16 v[110:113], v[134:137], v[158:161], v[110:113]
	v_mfma_f32_16x16x32_bf16 v[106:109], v[142:145], v[158:161], v[106:109]
	v_mfma_f32_16x16x32_bf16 v[94:97], v[134:137], v[166:169], v[94:97]
	v_mfma_f32_16x16x32_bf16 v[90:93], v[142:145], v[166:169], v[90:93]
	v_mfma_f32_16x16x32_bf16 v[78:81], v[134:137], v[174:177], v[78:81]
	v_mfma_f32_16x16x32_bf16 v[74:77], v[142:145], v[174:177], v[74:77]
	v_mfma_f32_16x16x32_bf16 v[126:129], v[138:141], v[154:157], v[126:129]
	v_mfma_f32_16x16x32_bf16 v[122:125], v[146:149], v[154:157], v[122:125]
	v_mfma_f32_16x16x32_bf16 v[110:113], v[138:141], v[162:165], v[110:113]
	v_mfma_f32_16x16x32_bf16 v[106:109], v[146:149], v[162:165], v[106:109]
	v_mfma_f32_16x16x32_bf16 v[94:97], v[138:141], v[170:173], v[94:97]
	v_mfma_f32_16x16x32_bf16 v[90:93], v[146:149], v[170:173], v[90:93]
	v_mfma_f32_16x16x32_bf16 v[78:81], v[138:141], v[178:181], v[78:81]
	v_mfma_f32_16x16x32_bf16 v[74:77], v[146:149], v[178:181], v[74:77]
	s_barrier
	s_add_i32 s26, 0, 0x14000
	v_add_u32_e32 v190, s26, v132
	s_add_i32 s23, s23, s53
	ds_read_b128 v[182:185], v190
	ds_read_b128 v[186:189], v190 offset:1024
	ds_read_b128 v[192:195], v190 offset:2048
	ds_read_b128 v[196:199], v190 offset:3072
	v_lshl_add_u64 v[190:191], s[8:9], 0, v[0:1]
	s_mov_b32 m0, s23
	v_lshl_add_u64 v[200:201], s[8:9], 0, v[130:131]
	global_load_lds_dwordx4 v[190:191], off
	s_add_i32 m0, s23, 0x2000
	s_nop 0
	global_load_lds_dwordx4 v[200:201], off
	s_barrier
	s_waitcnt lgkmcnt(0)
	s_waitcnt lgkmcnt(0)
	v_mfma_f32_16x16x32_bf16 v[118:121], v[182:185], v[150:153], v[118:121]
	v_mfma_f32_16x16x32_bf16 v[114:117], v[192:195], v[150:153], v[114:117]
	v_mfma_f32_16x16x32_bf16 v[102:105], v[182:185], v[158:161], v[102:105]
	v_mfma_f32_16x16x32_bf16 v[98:101], v[192:195], v[158:161], v[98:101]
	v_mfma_f32_16x16x32_bf16 v[86:89], v[182:185], v[166:169], v[86:89]
	v_mfma_f32_16x16x32_bf16 v[82:85], v[192:195], v[166:169], v[82:85]
	v_mfma_f32_16x16x32_bf16 v[70:73], v[182:185], v[174:177], v[70:73]
	v_mfma_f32_16x16x32_bf16 v[66:69], v[192:195], v[174:177], v[66:69]
	v_mfma_f32_16x16x32_bf16 v[118:121], v[186:189], v[154:157], v[118:121]
	v_mfma_f32_16x16x32_bf16 v[114:117], v[196:199], v[154:157], v[114:117]
	v_mfma_f32_16x16x32_bf16 v[102:105], v[186:189], v[162:165], v[102:105]
	v_mfma_f32_16x16x32_bf16 v[98:101], v[196:199], v[162:165], v[98:101]
	v_mfma_f32_16x16x32_bf16 v[86:89], v[186:189], v[170:173], v[86:89]
	v_mfma_f32_16x16x32_bf16 v[82:85], v[196:199], v[170:173], v[82:85]
	v_mfma_f32_16x16x32_bf16 v[70:73], v[186:189], v[178:181], v[70:73]
	v_mfma_f32_16x16x32_bf16 v[66:69], v[196:199], v[178:181], v[66:69]
	s_mov_b32 m0, s63
	v_lshl_add_u64 v[202:203], s[10:11], 0, v[0:1]
	s_barrier
	ds_read_b128 v[150:153], v133 offset:16384
	ds_read_b128 v[154:157], v133 offset:17408
	ds_read_b128 v[158:161], v133 offset:18432
	ds_read_b128 v[162:165], v133 offset:19456
	ds_read_b128 v[166:169], v133 offset:20480
	ds_read_b128 v[170:173], v133 offset:21504
	ds_read_b128 v[174:177], v133 offset:22528
	ds_read_b128 v[178:181], v133 offset:23552
	global_load_lds_dwordx4 v[202:203], off
	v_lshl_add_u64 v[204:205], s[10:11], 0, v[130:131]
	s_mov_b32 m0, s30
	s_nop 0
	global_load_lds_dwordx4 v[204:205], off
	s_barrier
	s_waitcnt lgkmcnt(0)
	s_waitcnt lgkmcnt(0)
	v_mfma_f32_16x16x32_bf16 v[62:65], v[134:137], v[150:153], v[62:65]
	v_mfma_f32_16x16x32_bf16 v[58:61], v[142:145], v[150:153], v[58:61]
	v_mfma_f32_16x16x32_bf16 v[46:49], v[134:137], v[158:161], v[46:49]
	v_mfma_f32_16x16x32_bf16 v[42:45], v[142:145], v[158:161], v[42:45]
	v_mfma_f32_16x16x32_bf16 v[30:33], v[134:137], v[166:169], v[30:33]
	v_mfma_f32_16x16x32_bf16 v[26:29], v[142:145], v[166:169], v[26:29]
	v_mfma_f32_16x16x32_bf16 v[14:17], v[134:137], v[174:177], v[14:17]
	v_mfma_f32_16x16x32_bf16 v[10:13], v[142:145], v[174:177], v[10:13]
	v_mfma_f32_16x16x32_bf16 v[62:65], v[138:141], v[154:157], v[62:65]
	v_mfma_f32_16x16x32_bf16 v[58:61], v[146:149], v[154:157], v[58:61]
	v_mfma_f32_16x16x32_bf16 v[46:49], v[138:141], v[162:165], v[46:49]
	v_mfma_f32_16x16x32_bf16 v[42:45], v[146:149], v[162:165], v[42:45]
	v_mfma_f32_16x16x32_bf16 v[30:33], v[138:141], v[170:173], v[30:33]
	v_mfma_f32_16x16x32_bf16 v[26:29], v[146:149], v[170:173], v[26:29]
	v_mfma_f32_16x16x32_bf16 v[14:17], v[138:141], v[178:181], v[14:17]
	v_mfma_f32_16x16x32_bf16 v[10:13], v[146:149], v[178:181], v[10:13]
	s_barrier
	s_add_u32 s24, s8, 0x40000
	s_addc_u32 s25, s9, 0
	s_add_i32 s23, s26, s53
	v_lshl_add_u64 v[134:135], s[24:25], 0, v[0:1]
	s_mov_b32 m0, s23
	s_nop 0
	global_load_lds_dwordx4 v[134:135], off
	v_lshl_add_u64 v[134:135], s[24:25], 0, v[130:131]
	s_add_i32 m0, s23, 0x2000
	s_nop 0
	global_load_lds_dwordx4 v[134:135], off
	s_waitcnt vmcnt(6)
	s_barrier
	v_mfma_f32_16x16x32_bf16 v[54:57], v[182:185], v[150:153], v[54:57]
	v_mfma_f32_16x16x32_bf16 v[50:53], v[192:195], v[150:153], v[50:53]
	v_mfma_f32_16x16x32_bf16 v[38:41], v[182:185], v[158:161], v[38:41]
	v_mfma_f32_16x16x32_bf16 v[34:37], v[192:195], v[158:161], v[34:37]
	v_mfma_f32_16x16x32_bf16 v[22:25], v[182:185], v[166:169], v[22:25]
	v_mfma_f32_16x16x32_bf16 v[18:21], v[192:195], v[166:169], v[18:21]
	v_mfma_f32_16x16x32_bf16 v[6:9], v[182:185], v[174:177], v[6:9]
	v_mfma_f32_16x16x32_bf16 v[2:5], v[192:195], v[174:177], v[2:5]
	v_mfma_f32_16x16x32_bf16 v[54:57], v[186:189], v[154:157], v[54:57]
	v_mfma_f32_16x16x32_bf16 v[50:53], v[196:199], v[154:157], v[50:53]
	v_mfma_f32_16x16x32_bf16 v[38:41], v[186:189], v[162:165], v[38:41]
	v_mfma_f32_16x16x32_bf16 v[34:37], v[196:199], v[162:165], v[34:37]
	v_mfma_f32_16x16x32_bf16 v[22:25], v[186:189], v[170:173], v[22:25]
	v_mfma_f32_16x16x32_bf16 v[18:21], v[196:199], v[170:173], v[18:21]
	v_mfma_f32_16x16x32_bf16 v[6:9], v[186:189], v[178:181], v[6:9]
	v_mfma_f32_16x16x32_bf16 v[2:5], v[196:199], v[178:181], v[2:5]
	s_add_i32 s23, 0, 0x18000
	v_add_u32_e32 v146, s23, v132
	s_barrier
	ds_read_b128 v[134:137], v146
	ds_read_b128 v[138:141], v146 offset:1024
	ds_read_b128 v[142:145], v146 offset:2048
	ds_read_b128 v[146:149], v146 offset:3072
	s_add_u32 s10, s10, 0x40000
	s_addc_u32 s11, s11, 0
	s_mov_b32 m0, s31
	v_lshl_add_u64 v[182:183], s[10:11], 0, v[0:1]
	ds_read_b128 v[150:153], v133 offset:32768
	ds_read_b128 v[154:157], v133 offset:33792
	ds_read_b128 v[158:161], v133 offset:34816
	ds_read_b128 v[162:165], v133 offset:35840
	ds_read_b128 v[166:169], v133 offset:36864
	ds_read_b128 v[170:173], v133 offset:37888
	ds_read_b128 v[174:177], v133 offset:38912
	ds_read_b128 v[178:181], v133 offset:39936
	global_load_lds_dwordx4 v[182:183], off
	v_lshl_add_u64 v[182:183], s[10:11], 0, v[130:131]
	s_mov_b32 m0, s34
	s_nop 0
	global_load_lds_dwordx4 v[182:183], off
	s_waitcnt lgkmcnt(8)
	s_barrier
	s_waitcnt lgkmcnt(0)
	s_waitcnt lgkmcnt(0)
	v_mfma_f32_16x16x32_bf16 v[126:129], v[134:137], v[150:153], v[126:129]
	v_mfma_f32_16x16x32_bf16 v[122:125], v[142:145], v[150:153], v[122:125]
	v_mfma_f32_16x16x32_bf16 v[110:113], v[134:137], v[158:161], v[110:113]
	v_mfma_f32_16x16x32_bf16 v[106:109], v[142:145], v[158:161], v[106:109]
	v_mfma_f32_16x16x32_bf16 v[94:97], v[134:137], v[166:169], v[94:97]
	v_mfma_f32_16x16x32_bf16 v[90:93], v[142:145], v[166:169], v[90:93]
	v_mfma_f32_16x16x32_bf16 v[78:81], v[134:137], v[174:177], v[78:81]
	v_mfma_f32_16x16x32_bf16 v[74:77], v[142:145], v[174:177], v[74:77]
	v_mfma_f32_16x16x32_bf16 v[126:129], v[138:141], v[154:157], v[126:129]
	v_mfma_f32_16x16x32_bf16 v[122:125], v[146:149], v[154:157], v[122:125]
	v_mfma_f32_16x16x32_bf16 v[110:113], v[138:141], v[162:165], v[110:113]
	v_mfma_f32_16x16x32_bf16 v[106:109], v[146:149], v[162:165], v[106:109]
	v_mfma_f32_16x16x32_bf16 v[94:97], v[138:141], v[170:173], v[94:97]
	v_mfma_f32_16x16x32_bf16 v[90:93], v[146:149], v[170:173], v[90:93]
	v_mfma_f32_16x16x32_bf16 v[78:81], v[138:141], v[178:181], v[78:81]
	v_mfma_f32_16x16x32_bf16 v[74:77], v[146:149], v[178:181], v[74:77]
	s_barrier
	s_add_i32 s10, 0, 0x1c000
	s_add_i32 s11, s23, s53
	v_add_u32_e32 v196, s10, v132
	v_lshl_add_u64 v[190:191], v[190:191], 0, s[70:71]
	s_mov_b32 m0, s11
	ds_read_b128 v[182:185], v196
	ds_read_b128 v[186:189], v196 offset:1024
	ds_read_b128 v[192:195], v196 offset:2048
	ds_read_b128 v[196:199], v196 offset:3072
	global_load_lds_dwordx4 v[190:191], off
	v_lshl_add_u64 v[190:191], v[200:201], 0, s[70:71]
	s_add_i32 m0, s11, 0x2000
	s_nop 0
	global_load_lds_dwordx4 v[190:191], off
	s_barrier
	s_waitcnt lgkmcnt(0)
	s_waitcnt lgkmcnt(0)
	v_mfma_f32_16x16x32_bf16 v[118:121], v[182:185], v[150:153], v[118:121]
	v_mfma_f32_16x16x32_bf16 v[114:117], v[192:195], v[150:153], v[114:117]
	v_mfma_f32_16x16x32_bf16 v[102:105], v[182:185], v[158:161], v[102:105]
	v_mfma_f32_16x16x32_bf16 v[98:101], v[192:195], v[158:161], v[98:101]
	v_mfma_f32_16x16x32_bf16 v[86:89], v[182:185], v[166:169], v[86:89]
	v_mfma_f32_16x16x32_bf16 v[82:85], v[192:195], v[166:169], v[82:85]
	v_mfma_f32_16x16x32_bf16 v[70:73], v[182:185], v[174:177], v[70:73]
	v_mfma_f32_16x16x32_bf16 v[66:69], v[192:195], v[174:177], v[66:69]
	v_mfma_f32_16x16x32_bf16 v[118:121], v[186:189], v[154:157], v[118:121]
	v_mfma_f32_16x16x32_bf16 v[114:117], v[196:199], v[154:157], v[114:117]
	v_mfma_f32_16x16x32_bf16 v[102:105], v[186:189], v[162:165], v[102:105]
	v_mfma_f32_16x16x32_bf16 v[98:101], v[196:199], v[162:165], v[98:101]
	v_mfma_f32_16x16x32_bf16 v[86:89], v[186:189], v[170:173], v[86:89]
	v_mfma_f32_16x16x32_bf16 v[82:85], v[196:199], v[170:173], v[82:85]
	v_mfma_f32_16x16x32_bf16 v[70:73], v[186:189], v[178:181], v[70:73]
	v_mfma_f32_16x16x32_bf16 v[66:69], v[196:199], v[178:181], v[66:69]
	s_mov_b32 m0, s35
	v_lshl_add_u64 v[190:191], v[202:203], 0, s[70:71]
	s_barrier
	ds_read_b128 v[150:153], v133 offset:49152
	ds_read_b128 v[154:157], v133 offset:50176
	ds_read_b128 v[158:161], v133 offset:51200
	ds_read_b128 v[162:165], v133 offset:52224
	ds_read_b128 v[166:169], v133 offset:53248
	ds_read_b128 v[170:173], v133 offset:54272
	ds_read_b128 v[174:177], v133 offset:55296
	ds_read_b128 v[178:181], v133 offset:56320
	global_load_lds_dwordx4 v[190:191], off
	v_lshl_add_u64 v[190:191], v[204:205], 0, s[70:71]
	s_mov_b32 m0, s36
	s_nop 0
	global_load_lds_dwordx4 v[190:191], off
	s_barrier
	s_waitcnt lgkmcnt(0)
	s_waitcnt lgkmcnt(0)
	v_mfma_f32_16x16x32_bf16 v[62:65], v[134:137], v[150:153], v[62:65]
	v_mfma_f32_16x16x32_bf16 v[58:61], v[142:145], v[150:153], v[58:61]
	v_mfma_f32_16x16x32_bf16 v[46:49], v[134:137], v[158:161], v[46:49]
	v_mfma_f32_16x16x32_bf16 v[42:45], v[142:145], v[158:161], v[42:45]
	v_mfma_f32_16x16x32_bf16 v[30:33], v[134:137], v[166:169], v[30:33]
	v_mfma_f32_16x16x32_bf16 v[26:29], v[142:145], v[166:169], v[26:29]
	v_mfma_f32_16x16x32_bf16 v[14:17], v[134:137], v[174:177], v[14:17]
	v_mfma_f32_16x16x32_bf16 v[10:13], v[142:145], v[174:177], v[10:13]
	v_mfma_f32_16x16x32_bf16 v[62:65], v[138:141], v[154:157], v[62:65]
	v_mfma_f32_16x16x32_bf16 v[58:61], v[146:149], v[154:157], v[58:61]
	v_mfma_f32_16x16x32_bf16 v[46:49], v[138:141], v[162:165], v[46:49]
	v_mfma_f32_16x16x32_bf16 v[42:45], v[146:149], v[162:165], v[42:45]
	v_mfma_f32_16x16x32_bf16 v[30:33], v[138:141], v[170:173], v[30:33]
	v_mfma_f32_16x16x32_bf16 v[26:29], v[146:149], v[170:173], v[26:29]
	v_mfma_f32_16x16x32_bf16 v[14:17], v[138:141], v[178:181], v[14:17]
	v_mfma_f32_16x16x32_bf16 v[10:13], v[146:149], v[178:181], v[10:13]
	s_barrier
	s_add_u32 s8, s8, 0x40080
	s_addc_u32 s9, s9, 0
	s_add_i32 s10, s10, s53
	v_lshl_add_u64 v[134:135], s[8:9], 0, v[0:1]
	s_mov_b32 m0, s10
	s_nop 0
	global_load_lds_dwordx4 v[134:135], off
	v_lshl_add_u64 v[134:135], s[8:9], 0, v[130:131]
	s_add_i32 m0, s10, 0x2000
	s_nop 0
	global_load_lds_dwordx4 v[134:135], off
	s_waitcnt vmcnt(6)
	s_barrier
	v_mfma_f32_16x16x32_bf16 v[54:57], v[182:185], v[150:153], v[54:57]
	v_mfma_f32_16x16x32_bf16 v[50:53], v[192:195], v[150:153], v[50:53]
	v_mfma_f32_16x16x32_bf16 v[38:41], v[182:185], v[158:161], v[38:41]
	v_mfma_f32_16x16x32_bf16 v[34:37], v[192:195], v[158:161], v[34:37]
	v_mfma_f32_16x16x32_bf16 v[22:25], v[182:185], v[166:169], v[22:25]
	v_mfma_f32_16x16x32_bf16 v[18:21], v[192:195], v[166:169], v[18:21]
	v_mfma_f32_16x16x32_bf16 v[6:9], v[182:185], v[174:177], v[6:9]
	v_mfma_f32_16x16x32_bf16 v[2:5], v[192:195], v[174:177], v[2:5]
	v_mfma_f32_16x16x32_bf16 v[54:57], v[186:189], v[154:157], v[54:57]
	v_mfma_f32_16x16x32_bf16 v[50:53], v[196:199], v[154:157], v[50:53]
	v_mfma_f32_16x16x32_bf16 v[38:41], v[186:189], v[162:165], v[38:41]
	v_mfma_f32_16x16x32_bf16 v[34:37], v[196:199], v[162:165], v[34:37]
	v_mfma_f32_16x16x32_bf16 v[22:25], v[186:189], v[170:173], v[22:25]
	v_mfma_f32_16x16x32_bf16 v[18:21], v[196:199], v[170:173], v[18:21]
	v_mfma_f32_16x16x32_bf16 v[6:9], v[186:189], v[178:181], v[6:9]
	v_mfma_f32_16x16x32_bf16 v[2:5], v[196:199], v[178:181], v[2:5]
	s_add_i32 s22, s22, 2
	s_add_u32 s14, s14, 0x100
	s_addc_u32 s15, s15, 0
	s_add_u32 s6, s6, 0x100
	s_addc_u32 s7, s7, 0
	s_cmp_gt_u32 s22, 13
	s_barrier
	s_cbranch_scc0 .LBB0_958
	s_mov_b32 s14, s48
	s_mov_b32 s15, s49
	v_mbcnt_lo_u32_b32 v156, -1, 0
	v_mbcnt_hi_u32_b32 v156, -1, v156
	s_add_u32 s22, s14, 0x2100000
	s_addc_u32 s23, s15, 0
	s_lshl_b32 s6, s13, 8
	v_lshrrev_b32_e32 v0, 1, v156
	s_add_i32 s6, s6, s42
	v_and_b32_e32 v0, 24, v0
	v_and_or_b32 v144, v156, 15, s6
	v_lshl_or_b32 v0, s12, 8, v0
	v_readlane_b32 s6, v254, 23
	v_ashrrev_i32_e32 v145, 31, v144
	v_lshlrev_b64 v[130:131], 11, v[144:145]
	v_or_b32_e32 v142, s6, v0
	v_ashrrev_i32_e32 v143, 31, v142
	v_lshl_add_u64 v[130:131], s[22:23], 0, v[130:131]
	v_lshlrev_b64 v[132:133], 1, v[142:143]
	s_mov_b32 s24, s50
	s_mov_b32 s25, s51
	v_lshl_add_u64 v[152:153], v[130:131], 0, v[132:133]
	global_load_dwordx4 v[158:161], v[152:153], off
	global_load_dwordx4 v[138:141], v[152:153], off offset:256
	v_lshl_add_u64 v[146:147], s[22:23], 0, v[132:133]
	v_or_b32_e32 v148, 16, v144
	v_ashrrev_i32_e32 v149, 31, v148
	v_lshlrev_b64 v[150:151], 11, v[148:149]
	v_lshl_add_u64 v[130:131], v[146:147], 0, v[150:151]
	global_load_dwordx4 v[134:137], v[130:131], off
	s_nop 0
	global_load_dwordx4 v[130:133], v[130:131], off offset:256
	v_mul_hi_i32 v0, v144, s59
	v_lshrrev_b32_e32 v154, 31, v0
	v_ashrrev_i32_e32 v0, 7, v0
	v_add_u32_e32 v154, v0, v154
	v_mad_i32_i24 v0, v154, s81, v144
	v_ashrrev_i32_e32 v155, 31, v154
	v_cmp_gt_i32_e64 s[10:11], 16, v0
	v_add_u32_e32 v0, -16, v0
	v_lshlrev_b64 v[154:155], 23, v[154:155]
	v_lshl_add_u64 v[154:155], s[24:25], 0, v[154:155]
	v_lshlrev_b64 v[162:163], 12, v[0:1]
	v_lshl_add_u64 v[154:155], v[154:155], 0, v[162:163]
	s_waitcnt vmcnt(0)
	v_lshlrev_b32_e32 v162, 16, v158
	v_and_b32_e32 v163, 0xffff0000, v158
	v_pk_add_f32 v[126:127], v[126:127], v[162:163]
	v_lshlrev_b32_e32 v162, 16, v160
	v_and_b32_e32 v163, 0xffff0000, v160
	v_pk_add_f32 v[122:123], v[122:123], v[162:163]
	v_and_b32_e32 v163, 0xffff0000, v159
	v_lshlrev_b32_e32 v162, 16, v159
	v_and_b32_e32 v159, 0xffff0000, v161
	v_lshlrev_b32_e32 v158, 16, v161
	v_cmp_lt_i32_e64 s[8:9], s80, v144
	v_pk_add_f32 v[128:129], v[128:129], v[162:163]
	v_pk_add_f32 v[124:125], v[124:125], v[158:159]
	s_mov_b64 s[6:7], -1
	s_and_b64 vcc, exec, s[92:93]
	s_cbranch_vccz .LBB0_963
	s_nor_b64 s[12:13], s[8:9], s[10:11]
	s_and_saveexec_b64 s[6:7], s[12:13]
	s_cbranch_execz .LBB0_962
	v_lshl_add_u64 v[158:159], v[142:143], 2, v[154:155]
	global_store_dwordx4 v[158:159], v[126:129], off
	global_store_dwordx4 v[158:159], v[122:125], off offset:16
